# softmax row sums in all four mixers use packed f32 adds for the even/odd partial-sum pair (half as many add instructions, same arithmetic)
# baseline (speedup 1.0000x reference)
.LBB0_735:
	s_cmp_eq_u32 s99, 0
	s_cbranch_scc1 .Lm3b_loop
	s_add_i32 s8, s6, -1
	s_min_i32 s9, s6, 35
	s_cmp_lt_u32 s8, 31
	s_cselect_b32 s15, 0, 0xffffffe0
	s_cselect_b32 s16, s13, s14
	s_add_i32 s15, s15, s9
	s_lshl_b32 s9, s15, 6
	s_add_i32 s9, s9, s16
	s_and_b32 s16, s8, 1
	s_mul_i32 s15, s16, 0x3400
	s_mulk_i32 s16, 0x3000
	v_add_u32_e32 v244, s15, v184
	v_add_u32_e32 v246, s16, v243
	ds_read_b128 v[218:221], v244
	ds_read_b128 v[222:225], v244 offset:6656
	ds_read_b128 v[226:229], v244 offset:32
	ds_read_b128 v[230:233], v244 offset:6688
	ds_read_b128 v[168:171], v244 offset:64
	ds_read_b128 v[172:175], v244 offset:6720
	ds_read_b128 v[176:179], v244 offset:96
	ds_read_b128 v[180:183], v244 offset:6752
	s_waitcnt lgkmcnt(7)
	v_mfma_f32_32x32x16_bf16 v[96:111], v[218:221], v[128:131], v[48:63]
	s_waitcnt lgkmcnt(6)
	v_mfma_f32_32x32x16_bf16 v[112:127], v[222:225], v[128:131], v[48:63]
	s_waitcnt lgkmcnt(5)
	v_mfma_f32_32x32x16_bf16 v[96:111], v[226:229], v[132:135], v[96:111]
	s_waitcnt lgkmcnt(4)
	v_mfma_f32_32x32x16_bf16 v[112:127], v[230:233], v[132:135], v[112:127]
	ds_read_b64_tr_b16 v[152:153], v246 offset:26624
	ds_read_b64_tr_b16 v[154:155], v246 offset:28160
	ds_read_b64_tr_b16 v[156:157], v246 offset:26688
	ds_read_b64_tr_b16 v[158:159], v246 offset:28224
	ds_read_b64_tr_b16 v[160:161], v246 offset:29696
	ds_read_b64_tr_b16 v[162:163], v246 offset:31232
	ds_read_b64_tr_b16 v[164:165], v246 offset:29760
	ds_read_b64_tr_b16 v[166:167], v246 offset:31296
	v_add_u32_e32 v186, s9, v239
	v_mad_i64_i32 v[186:187], s[16:17], v186, s33, v[194:195]
	v_add_u32_e32 v188, s9, v240
	v_mad_i64_i32 v[188:189], s[16:17], v188, s33, v[196:197]
	global_load_dwordx4 v[148:151], v[186:187], off
	global_load_dwordx4 v[144:147], v[188:189], off
	s_waitcnt lgkmcnt(11)
	v_mfma_f32_32x32x16_bf16 v[202:217], v[168:171], v[136:139], v[80:95]
	v_exp_f32_e32 v96, v96
	v_exp_f32_e32 v97, v97
	v_exp_f32_e32 v98, v98
	s_waitcnt lgkmcnt(10)
	v_mfma_f32_32x32x16_bf16 v[218:233], v[172:175], v[136:139], v[80:95]
	v_exp_f32_e32 v99, v99
	v_exp_f32_e32 v100, v100
	v_exp_f32_e32 v101, v101
	s_waitcnt lgkmcnt(9)
	v_mfma_f32_32x32x16_bf16 v[202:217], v[176:179], v[140:143], v[202:217]
	v_exp_f32_e32 v102, v102
	v_exp_f32_e32 v103, v103
	v_pk_add_f32 v[234:235], v[96:97], v[98:99]
	s_waitcnt lgkmcnt(8)
	v_mfma_f32_32x32x16_bf16 v[218:233], v[180:183], v[140:143], v[218:233]
	v_pk_add_f32 v[234:235], v[234:235], v[100:101]
	v_pk_add_f32 v[234:235], v[234:235], v[102:103]
	v_cvt_pk_bf16_f32 v96, v96, v97
	v_cvt_pk_bf16_f32 v97, v98, v99
	s_waitcnt lgkmcnt(7)
	ds_read_b64_tr_b16 v[168:169], v246 offset:32768
	ds_read_b64_tr_b16 v[170:171], v246 offset:34304
	ds_read_b64_tr_b16 v[172:173], v246 offset:32832
	ds_read_b64_tr_b16 v[174:175], v246 offset:34368
	ds_read_b64_tr_b16 v[176:177], v246 offset:35840
	ds_read_b64_tr_b16 v[178:179], v246 offset:37376
	ds_read_b64_tr_b16 v[180:181], v246 offset:35904
	ds_read_b64_tr_b16 v[182:183], v246 offset:37440
	v_cvt_pk_bf16_f32 v98, v100, v101
	v_cvt_pk_bf16_f32 v99, v102, v103
	v_exp_f32_e32 v104, v104
	v_exp_f32_e32 v105, v105
	s_waitcnt lgkmcnt(14)
	v_mfma_f32_32x32x16_bf16 v[16:31], v[152:155], v[96:99], v[16:31]
	v_exp_f32_e32 v106, v106
	v_exp_f32_e32 v107, v107
	v_exp_f32_e32 v108, v108
	s_waitcnt lgkmcnt(12)
	v_mfma_f32_32x32x16_bf16 v[0:15], v[156:159], v[96:99], v[0:15]
	v_exp_f32_e32 v109, v109
	v_exp_f32_e32 v110, v110
	v_exp_f32_e32 v111, v111
	v_pk_add_f32 v[234:235], v[234:235], v[104:105]
	v_pk_add_f32 v[234:235], v[234:235], v[106:107]
	v_pk_add_f32 v[234:235], v[234:235], v[108:109]
	v_pk_add_f32 v[234:235], v[234:235], v[110:111]
	v_cvt_pk_bf16_f32 v104, v104, v105
	v_cvt_pk_bf16_f32 v105, v106, v107
	v_cvt_pk_bf16_f32 v106, v108, v109
	v_cvt_pk_bf16_f32 v107, v110, v111
	v_exp_f32_e32 v112, v112
	v_exp_f32_e32 v113, v113
	s_waitcnt lgkmcnt(10)
	v_mfma_f32_32x32x16_bf16 v[16:31], v[160:163], v[104:107], v[16:31]
	v_exp_f32_e32 v114, v114
	v_exp_f32_e32 v115, v115
	v_exp_f32_e32 v116, v116
	s_waitcnt lgkmcnt(8)
	v_mfma_f32_32x32x16_bf16 v[0:15], v[164:167], v[104:107], v[0:15]
	v_exp_f32_e32 v117, v117
	v_exp_f32_e32 v118, v118
	v_exp_f32_e32 v119, v119
	v_pk_add_f32 v[234:235], v[234:235], v[112:113]
	v_pk_add_f32 v[234:235], v[234:235], v[114:115]
	v_pk_add_f32 v[234:235], v[234:235], v[116:117]
	v_pk_add_f32 v[234:235], v[234:235], v[118:119]
	v_cvt_pk_bf16_f32 v112, v112, v113
	v_cvt_pk_bf16_f32 v113, v114, v115
	v_cvt_pk_bf16_f32 v114, v116, v117
	v_cvt_pk_bf16_f32 v115, v118, v119
	v_exp_f32_e32 v120, v120
	v_exp_f32_e32 v121, v121
	s_waitcnt lgkmcnt(6)
	v_mfma_f32_32x32x16_bf16 v[16:31], v[168:171], v[112:115], v[16:31]
	v_exp_f32_e32 v122, v122
	v_exp_f32_e32 v123, v123
	v_exp_f32_e32 v124, v124
	s_waitcnt lgkmcnt(4)
	v_mfma_f32_32x32x16_bf16 v[0:15], v[172:175], v[112:115], v[0:15]
	v_exp_f32_e32 v125, v125
	v_exp_f32_e32 v126, v126
	v_exp_f32_e32 v127, v127
	v_pk_add_f32 v[234:235], v[234:235], v[120:121]
	v_pk_add_f32 v[234:235], v[234:235], v[122:123]
	v_pk_add_f32 v[234:235], v[234:235], v[124:125]
	v_pk_add_f32 v[234:235], v[234:235], v[126:127]
	v_cvt_pk_bf16_f32 v120, v120, v121
	v_cvt_pk_bf16_f32 v121, v122, v123
	v_cvt_pk_bf16_f32 v122, v124, v125
	v_cvt_pk_bf16_f32 v123, v126, v127
	v_exp_f32_e32 v202, v202
	v_exp_f32_e32 v203, v203
	s_waitcnt lgkmcnt(2)
	v_mfma_f32_32x32x16_bf16 v[16:31], v[176:179], v[120:123], v[16:31]
	v_exp_f32_e32 v204, v204
	v_exp_f32_e32 v205, v205
	v_exp_f32_e32 v206, v206
	s_waitcnt lgkmcnt(0)
	v_mfma_f32_32x32x16_bf16 v[0:15], v[180:183], v[120:123], v[0:15]
	v_exp_f32_e32 v207, v207
	v_exp_f32_e32 v208, v208
	v_exp_f32_e32 v209, v209
	s_cmp_gt_u32 s8, 34
	s_cbranch_scc1 .Lm3a_skipw
	s_and_b32 s8, s7, 64
	s_mul_i32 s9, s8, 0xd0
	s_mulk_i32 s8, 0xc0
	v_add_u32_e32 v186, s9, v241
	v_add_u32_e32 v188, s8, v242
	s_waitcnt vmcnt(1)
	ds_write_b128 v186, v[148:151]
	s_waitcnt vmcnt(0)
	ds_write_b128 v188, v[144:147] offset:26624
.Lm3a_skipw:
	v_pk_add_f32 v[236:237], v[202:203], v[204:205]
	v_pk_add_f32 v[236:237], v[236:237], v[206:207]
	v_pk_add_f32 v[236:237], v[236:237], v[208:209]
	v_cvt_pk_bf16_f32 v202, v202, v203
	v_cvt_pk_bf16_f32 v203, v204, v205
	v_cvt_pk_bf16_f32 v204, v206, v207
	v_cvt_pk_bf16_f32 v205, v208, v209
	v_exp_f32_e32 v210, v210
	v_exp_f32_e32 v211, v211
	v_mfma_f32_32x32x16_bf16 v[64:79], v[152:155], v[202:205], v[64:79]
	v_exp_f32_e32 v212, v212
	v_exp_f32_e32 v213, v213
	v_exp_f32_e32 v214, v214
	v_mfma_f32_32x32x16_bf16 v[32:47], v[156:159], v[202:205], v[32:47]
	v_exp_f32_e32 v215, v215
	v_exp_f32_e32 v216, v216
	v_exp_f32_e32 v217, v217
	v_pk_add_f32 v[236:237], v[236:237], v[210:211]
	v_pk_add_f32 v[236:237], v[236:237], v[212:213]
	v_pk_add_f32 v[236:237], v[236:237], v[214:215]
	v_pk_add_f32 v[236:237], v[236:237], v[216:217]
	v_cvt_pk_bf16_f32 v210, v210, v211
	v_cvt_pk_bf16_f32 v211, v212, v213
	v_cvt_pk_bf16_f32 v212, v214, v215
	v_cvt_pk_bf16_f32 v213, v216, v217
	v_exp_f32_e32 v218, v218
	v_exp_f32_e32 v219, v219
	v_mfma_f32_32x32x16_bf16 v[64:79], v[160:163], v[210:213], v[64:79]
	v_exp_f32_e32 v220, v220
	v_exp_f32_e32 v221, v221
	v_exp_f32_e32 v222, v222
	v_mfma_f32_32x32x16_bf16 v[32:47], v[164:167], v[210:213], v[32:47]
	v_exp_f32_e32 v223, v223
	v_exp_f32_e32 v224, v224
	v_exp_f32_e32 v225, v225
	v_pk_add_f32 v[236:237], v[236:237], v[218:219]
	v_pk_add_f32 v[236:237], v[236:237], v[220:221]
	v_pk_add_f32 v[236:237], v[236:237], v[222:223]
	v_pk_add_f32 v[236:237], v[236:237], v[224:225]
	v_cvt_pk_bf16_f32 v218, v218, v219
	v_cvt_pk_bf16_f32 v219, v220, v221
	v_cvt_pk_bf16_f32 v220, v222, v223
	v_cvt_pk_bf16_f32 v221, v224, v225
	v_exp_f32_e32 v226, v226
	v_exp_f32_e32 v227, v227
	v_mfma_f32_32x32x16_bf16 v[64:79], v[168:171], v[218:221], v[64:79]
	v_exp_f32_e32 v228, v228
	v_exp_f32_e32 v229, v229
	v_exp_f32_e32 v230, v230
	v_mfma_f32_32x32x16_bf16 v[32:47], v[172:175], v[218:221], v[32:47]
	v_exp_f32_e32 v231, v231
	v_exp_f32_e32 v232, v232
	v_exp_f32_e32 v233, v233
	v_pk_add_f32 v[236:237], v[236:237], v[226:227]
	v_pk_add_f32 v[236:237], v[236:237], v[228:229]
	v_pk_add_f32 v[236:237], v[236:237], v[230:231]
	v_pk_add_f32 v[236:237], v[236:237], v[232:233]
	v_cvt_pk_bf16_f32 v226, v226, v227
	v_cvt_pk_bf16_f32 v227, v228, v229
	v_cvt_pk_bf16_f32 v228, v230, v231
	v_cvt_pk_bf16_f32 v229, v232, v233
	s_nop 1
	v_mfma_f32_32x32x16_bf16 v[64:79], v[176:179], v[226:229], v[64:79]
	v_mfma_f32_32x32x16_bf16 v[32:47], v[180:183], v[226:229], v[32:47]
	v_add_f32_e32 v234, v234, v235
	v_add_f32_e32 v236, v236, v237
	v_add_f32_e32 v199, v199, v234
	v_add_f32_e32 v201, v201, v236
	v_max_f32_e32 v247, v234, v236
	v_cmp_lt_f32_e32 vcc, 0x43000000, v247
	s_cbranch_vccz .Lm3a_norescale
	s_nop 15
	v_mov_b32_e32 v235, v234
	s_nop 1
	v_permlane32_swap_b32_e32 v234, v235
	v_add_f32_e32 v247, v234, v235
	v_cmp_lt_f32_e32 vcc, 0x43800000, v247
	v_frexp_exp_i32_f32_e32 v248, v247
	s_nop 1
	v_cndmask_b32_e32 v248, 0, v248, vcc
	v_cvt_f32_i32_e32 v249, v248
	v_sub_u32_e32 v248, 0, v248
	v_ldexp_f32 v247, 1.0, v248
	v_add_f32_e32 v198, v198, v249
	v_mul_f32_e32 v199, v199, v247
	v_mul_f32_e32 v16, v16, v247
	v_mul_f32_e32 v17, v17, v247
	v_mul_f32_e32 v18, v18, v247
	v_mul_f32_e32 v19, v19, v247
	v_mul_f32_e32 v20, v20, v247
	v_mul_f32_e32 v21, v21, v247
	v_mul_f32_e32 v22, v22, v247
	v_mul_f32_e32 v23, v23, v247
	v_mul_f32_e32 v24, v24, v247
	v_mul_f32_e32 v25, v25, v247
	v_mul_f32_e32 v26, v26, v247
	v_mul_f32_e32 v27, v27, v247
	v_mul_f32_e32 v28, v28, v247
	v_mul_f32_e32 v29, v29, v247
	v_mul_f32_e32 v30, v30, v247
	v_mul_f32_e32 v31, v31, v247
	v_mul_f32_e32 v0, v0, v247
	v_mul_f32_e32 v1, v1, v247
	v_mul_f32_e32 v2, v2, v247
	v_mul_f32_e32 v3, v3, v247
	v_mul_f32_e32 v4, v4, v247
	v_mul_f32_e32 v5, v5, v247
	v_mul_f32_e32 v6, v6, v247
	v_mul_f32_e32 v7, v7, v247
	v_mul_f32_e32 v8, v8, v247
	v_mul_f32_e32 v9, v9, v247
	v_mul_f32_e32 v10, v10, v247
	v_mul_f32_e32 v11, v11, v247
	v_mul_f32_e32 v12, v12, v247
	v_mul_f32_e32 v13, v13, v247
	v_mul_f32_e32 v14, v14, v247
	v_mul_f32_e32 v15, v15, v247
	v_sub_f32_e32 v48, 0, v198
	v_mov_b32_e32 v49, v48
	v_mov_b32_e32 v50, v48
	v_mov_b32_e32 v51, v48
	v_mov_b32_e32 v52, v48
	v_mov_b32_e32 v53, v48
	v_mov_b32_e32 v54, v48
	v_mov_b32_e32 v55, v48
	v_mov_b32_e32 v56, v48
	v_mov_b32_e32 v57, v48
	v_mov_b32_e32 v58, v48
	v_mov_b32_e32 v59, v48
	v_mov_b32_e32 v60, v48
	v_mov_b32_e32 v61, v48
	v_mov_b32_e32 v62, v48
	v_mov_b32_e32 v63, v48
	v_mov_b32_e32 v237, v236
	s_nop 1
	v_permlane32_swap_b32_e32 v236, v237
	v_add_f32_e32 v247, v236, v237
	v_cmp_lt_f32_e32 vcc, 0x43800000, v247
	v_frexp_exp_i32_f32_e32 v248, v247
	s_nop 1
	v_cndmask_b32_e32 v248, 0, v248, vcc
	v_cvt_f32_i32_e32 v249, v248
	v_sub_u32_e32 v248, 0, v248
	v_ldexp_f32 v247, 1.0, v248
	v_add_f32_e32 v200, v200, v249
	v_mul_f32_e32 v201, v201, v247
	v_mul_f32_e32 v64, v64, v247
	v_mul_f32_e32 v65, v65, v247
	v_mul_f32_e32 v66, v66, v247
	v_mul_f32_e32 v67, v67, v247
	v_mul_f32_e32 v68, v68, v247
	v_mul_f32_e32 v69, v69, v247
	v_mul_f32_e32 v70, v70, v247
	v_mul_f32_e32 v71, v71, v247
	v_mul_f32_e32 v72, v72, v247
	v_mul_f32_e32 v73, v73, v247
	v_mul_f32_e32 v74, v74, v247
	v_mul_f32_e32 v75, v75, v247
	v_mul_f32_e32 v76, v76, v247
	v_mul_f32_e32 v77, v77, v247
	v_mul_f32_e32 v78, v78, v247
	v_mul_f32_e32 v79, v79, v247
	v_mul_f32_e32 v32, v32, v247
	v_mul_f32_e32 v33, v33, v247
	v_mul_f32_e32 v34, v34, v247
	v_mul_f32_e32 v35, v35, v247
	v_mul_f32_e32 v36, v36, v247
	v_mul_f32_e32 v37, v37, v247
	v_mul_f32_e32 v38, v38, v247
	v_mul_f32_e32 v39, v39, v247
	v_mul_f32_e32 v40, v40, v247
	v_mul_f32_e32 v41, v41, v247
	v_mul_f32_e32 v42, v42, v247
	v_mul_f32_e32 v43, v43, v247
	v_mul_f32_e32 v44, v44, v247
	v_mul_f32_e32 v45, v45, v247
	v_mul_f32_e32 v46, v46, v247
	v_mul_f32_e32 v47, v47, v247
	v_sub_f32_e32 v80, 0, v200
	v_mov_b32_e32 v81, v80
	v_mov_b32_e32 v82, v80
	v_mov_b32_e32 v83, v80
	v_mov_b32_e32 v84, v80
	v_mov_b32_e32 v85, v80
	v_mov_b32_e32 v86, v80
	v_mov_b32_e32 v87, v80
	v_mov_b32_e32 v88, v80
	v_mov_b32_e32 v89, v80
	v_mov_b32_e32 v90, v80
	v_mov_b32_e32 v91, v80
	v_mov_b32_e32 v92, v80
	v_mov_b32_e32 v93, v80
	v_mov_b32_e32 v94, v80
	v_mov_b32_e32 v95, v80

.Lm3b_x:
	v_exp_f32_e32 v96, v96
	v_exp_f32_e32 v97, v97
	v_exp_f32_e32 v98, v98
	v_exp_f32_e32 v99, v99
	v_exp_f32_e32 v100, v100
	v_exp_f32_e32 v101, v101
	v_exp_f32_e32 v102, v102
	v_exp_f32_e32 v103, v103
	v_pk_add_f32 v[234:235], v[96:97], v[98:99]
	v_pk_add_f32 v[234:235], v[234:235], v[100:101]
	v_pk_add_f32 v[234:235], v[234:235], v[102:103]
	v_cvt_pk_bf16_f32 v96, v96, v97
	v_cvt_pk_bf16_f32 v97, v98, v99
	v_cvt_pk_bf16_f32 v98, v100, v101
	v_cvt_pk_bf16_f32 v99, v102, v103
	v_exp_f32_e32 v104, v104
	v_exp_f32_e32 v105, v105
	s_waitcnt lgkmcnt(14)
	v_mfma_f32_32x32x16_bf16 v[16:31], v[152:155], v[96:99], v[16:31]
	v_exp_f32_e32 v106, v106
	v_exp_f32_e32 v107, v107
	v_exp_f32_e32 v108, v108
	s_waitcnt lgkmcnt(12)
	v_mfma_f32_32x32x16_bf16 v[0:15], v[156:159], v[96:99], v[0:15]
	v_exp_f32_e32 v109, v109
	v_exp_f32_e32 v110, v110
	v_exp_f32_e32 v111, v111
	v_pk_add_f32 v[234:235], v[234:235], v[104:105]
	v_pk_add_f32 v[234:235], v[234:235], v[106:107]
	v_pk_add_f32 v[234:235], v[234:235], v[108:109]
	v_pk_add_f32 v[234:235], v[234:235], v[110:111]
	v_cvt_pk_bf16_f32 v104, v104, v105
	v_cvt_pk_bf16_f32 v105, v106, v107
	v_cvt_pk_bf16_f32 v106, v108, v109
	v_cvt_pk_bf16_f32 v107, v110, v111
	v_exp_f32_e32 v112, v112
	v_exp_f32_e32 v113, v113
	s_waitcnt lgkmcnt(10)
	v_mfma_f32_32x32x16_bf16 v[16:31], v[160:163], v[104:107], v[16:31]
	v_exp_f32_e32 v114, v114
	v_exp_f32_e32 v115, v115
	v_exp_f32_e32 v116, v116
	s_waitcnt lgkmcnt(8)
	v_mfma_f32_32x32x16_bf16 v[0:15], v[164:167], v[104:107], v[0:15]
	v_exp_f32_e32 v117, v117
	v_exp_f32_e32 v118, v118
	v_exp_f32_e32 v119, v119
	v_pk_add_f32 v[234:235], v[234:235], v[112:113]
	v_pk_add_f32 v[234:235], v[234:235], v[114:115]
	v_pk_add_f32 v[234:235], v[234:235], v[116:117]
	v_pk_add_f32 v[234:235], v[234:235], v[118:119]
	v_cvt_pk_bf16_f32 v112, v112, v113
	v_cvt_pk_bf16_f32 v113, v114, v115
	v_cvt_pk_bf16_f32 v114, v116, v117
	v_cvt_pk_bf16_f32 v115, v118, v119
	v_exp_f32_e32 v120, v120
	v_exp_f32_e32 v121, v121
	s_waitcnt lgkmcnt(6)
	v_mfma_f32_32x32x16_bf16 v[16:31], v[168:171], v[112:115], v[16:31]
	v_exp_f32_e32 v122, v122
	v_exp_f32_e32 v123, v123
	v_exp_f32_e32 v124, v124
	s_waitcnt lgkmcnt(4)
	v_mfma_f32_32x32x16_bf16 v[0:15], v[172:175], v[112:115], v[0:15]
	v_exp_f32_e32 v125, v125
	v_exp_f32_e32 v126, v126
	v_exp_f32_e32 v127, v127
	v_pk_add_f32 v[234:235], v[234:235], v[120:121]
	v_pk_add_f32 v[234:235], v[234:235], v[122:123]
	v_pk_add_f32 v[234:235], v[234:235], v[124:125]
	v_pk_add_f32 v[234:235], v[234:235], v[126:127]
	v_cvt_pk_bf16_f32 v120, v120, v121
	v_cvt_pk_bf16_f32 v121, v122, v123
	v_cvt_pk_bf16_f32 v122, v124, v125
	v_cvt_pk_bf16_f32 v123, v126, v127
	v_exp_f32_e32 v202, v202
	v_exp_f32_e32 v203, v203
	s_waitcnt lgkmcnt(2)
	v_mfma_f32_32x32x16_bf16 v[16:31], v[176:179], v[120:123], v[16:31]
	v_exp_f32_e32 v204, v204
	v_exp_f32_e32 v205, v205
	v_exp_f32_e32 v206, v206
	s_waitcnt lgkmcnt(0)
	v_mfma_f32_32x32x16_bf16 v[0:15], v[180:183], v[120:123], v[0:15]
	v_exp_f32_e32 v207, v207
	v_exp_f32_e32 v208, v208
	v_exp_f32_e32 v209, v209
	s_cmp_eq_u32 s99, 0
	s_cbranch_scc1 .Lm3b_skipwy
	s_cmp_gt_u32 s8, 34
	s_cbranch_scc1 .Lm3b_skipwy
	s_and_b32 s8, s7, 64
	s_mul_i32 s9, s8, 0xd0
	s_mulk_i32 s8, 0xc0
	v_add_u32_e32 v186, s9, v241
	v_add_u32_e32 v188, s8, v242
	s_waitcnt vmcnt(1)
	ds_write_b128 v186, v[148:151]
	s_waitcnt vmcnt(0)
	ds_write_b128 v188, v[144:147] offset:26624

.Lm1_xA:
	v_exp_f32_e32 v144, v144
	v_exp_f32_e32 v145, v145
	v_exp_f32_e32 v146, v146
	v_exp_f32_e32 v147, v147
	v_exp_f32_e32 v148, v148
	v_exp_f32_e32 v149, v149
	v_exp_f32_e32 v150, v150
	v_exp_f32_e32 v151, v151
	v_pk_add_f32 v[204:205], v[144:145], v[146:147]
	v_pk_add_f32 v[204:205], v[204:205], v[148:149]
	v_pk_add_f32 v[204:205], v[204:205], v[150:151]
	v_cvt_pk_bf16_f32 v144, v144, v145
	v_cvt_pk_bf16_f32 v145, v146, v147
	v_cvt_pk_bf16_f32 v146, v148, v149
	v_cvt_pk_bf16_f32 v147, v150, v151
	v_exp_f32_e32 v152, v152
	v_exp_f32_e32 v153, v153
	s_waitcnt lgkmcnt(14)
	v_mfma_f32_32x32x16_bf16 v[16:31], v[48:51], v[144:147], v[16:31]
	v_exp_f32_e32 v154, v154
	v_exp_f32_e32 v155, v155
	v_exp_f32_e32 v156, v156
	s_waitcnt lgkmcnt(12)
	v_mfma_f32_32x32x16_bf16 v[0:15], v[52:55], v[144:147], v[0:15]
	v_exp_f32_e32 v157, v157
	v_exp_f32_e32 v158, v158
	v_exp_f32_e32 v159, v159
	v_pk_add_f32 v[204:205], v[204:205], v[152:153]
	v_pk_add_f32 v[204:205], v[204:205], v[154:155]
	v_pk_add_f32 v[204:205], v[204:205], v[156:157]
	v_pk_add_f32 v[204:205], v[204:205], v[158:159]
	v_cvt_pk_bf16_f32 v152, v152, v153
	v_cvt_pk_bf16_f32 v153, v154, v155
	v_cvt_pk_bf16_f32 v154, v156, v157
	v_cvt_pk_bf16_f32 v155, v158, v159
	v_exp_f32_e32 v160, v160
	v_exp_f32_e32 v161, v161
	s_waitcnt lgkmcnt(10)
	v_mfma_f32_32x32x16_bf16 v[16:31], v[56:59], v[152:155], v[16:31]
	v_exp_f32_e32 v162, v162
	v_exp_f32_e32 v163, v163
	v_exp_f32_e32 v164, v164
	s_waitcnt lgkmcnt(8)
	v_mfma_f32_32x32x16_bf16 v[0:15], v[60:63], v[152:155], v[0:15]
	v_exp_f32_e32 v165, v165
	v_exp_f32_e32 v166, v166
	v_exp_f32_e32 v167, v167
	v_pk_add_f32 v[204:205], v[204:205], v[160:161]
	v_pk_add_f32 v[204:205], v[204:205], v[162:163]
	v_pk_add_f32 v[204:205], v[204:205], v[164:165]
	v_pk_add_f32 v[204:205], v[204:205], v[166:167]
	v_cvt_pk_bf16_f32 v160, v160, v161
	v_cvt_pk_bf16_f32 v161, v162, v163
	v_cvt_pk_bf16_f32 v162, v164, v165
	v_cvt_pk_bf16_f32 v163, v166, v167
	v_exp_f32_e32 v168, v168
	v_exp_f32_e32 v169, v169
	s_waitcnt lgkmcnt(6)
	v_mfma_f32_32x32x16_bf16 v[16:31], v[64:67], v[160:163], v[16:31]
	v_exp_f32_e32 v170, v170
	v_exp_f32_e32 v171, v171
	v_exp_f32_e32 v172, v172
	s_waitcnt lgkmcnt(4)
	v_mfma_f32_32x32x16_bf16 v[0:15], v[68:71], v[160:163], v[0:15]
	v_exp_f32_e32 v173, v173
	v_exp_f32_e32 v174, v174
	v_exp_f32_e32 v175, v175
	v_pk_add_f32 v[204:205], v[204:205], v[168:169]
	v_pk_add_f32 v[204:205], v[204:205], v[170:171]
	v_pk_add_f32 v[204:205], v[204:205], v[172:173]
	v_pk_add_f32 v[204:205], v[204:205], v[174:175]
	v_cvt_pk_bf16_f32 v168, v168, v169
	v_cvt_pk_bf16_f32 v169, v170, v171
	v_cvt_pk_bf16_f32 v170, v172, v173
	v_cvt_pk_bf16_f32 v171, v174, v175
	s_nop 1
	s_waitcnt lgkmcnt(2)
	v_mfma_f32_32x32x16_bf16 v[16:31], v[72:75], v[168:171], v[16:31]
	s_waitcnt lgkmcnt(0)
	v_mfma_f32_32x32x16_bf16 v[0:15], v[76:79], v[168:171], v[0:15]
	s_cmp_eq_u32 s99, 0
	s_cbranch_scc1 .Lm1_yA
	s_waitcnt vmcnt(5)
	ds_write_b128 v198, v[120:123] offset:13312
	s_waitcnt vmcnt(4)
	ds_write_b128 v199, v[124:127] offset:13312
	s_waitcnt vmcnt(3)
	ds_write_b128 v200, v[128:131] offset:38912

.Lm1_xB:
	v_exp_f32_e32 v144, v144
	v_exp_f32_e32 v145, v145
	v_exp_f32_e32 v146, v146
	v_exp_f32_e32 v147, v147
	v_exp_f32_e32 v148, v148
	v_exp_f32_e32 v149, v149
	v_exp_f32_e32 v150, v150
	v_exp_f32_e32 v151, v151
	v_pk_add_f32 v[204:205], v[144:145], v[146:147]
	v_pk_add_f32 v[204:205], v[204:205], v[148:149]
	v_pk_add_f32 v[204:205], v[204:205], v[150:151]
	v_cvt_pk_bf16_f32 v144, v144, v145
	v_cvt_pk_bf16_f32 v145, v146, v147
	v_cvt_pk_bf16_f32 v146, v148, v149
	v_cvt_pk_bf16_f32 v147, v150, v151
	v_exp_f32_e32 v152, v152
	v_exp_f32_e32 v153, v153
	s_waitcnt lgkmcnt(14)
	v_mfma_f32_32x32x16_bf16 v[16:31], v[48:51], v[144:147], v[16:31]
	v_exp_f32_e32 v154, v154
	v_exp_f32_e32 v155, v155
	v_exp_f32_e32 v156, v156
	s_waitcnt lgkmcnt(12)
	v_mfma_f32_32x32x16_bf16 v[0:15], v[52:55], v[144:147], v[0:15]
	v_exp_f32_e32 v157, v157
	v_exp_f32_e32 v158, v158
	v_exp_f32_e32 v159, v159
	v_pk_add_f32 v[204:205], v[204:205], v[152:153]
	v_pk_add_f32 v[204:205], v[204:205], v[154:155]
	v_pk_add_f32 v[204:205], v[204:205], v[156:157]
	v_pk_add_f32 v[204:205], v[204:205], v[158:159]
	v_cvt_pk_bf16_f32 v152, v152, v153
	v_cvt_pk_bf16_f32 v153, v154, v155
	v_cvt_pk_bf16_f32 v154, v156, v157
	v_cvt_pk_bf16_f32 v155, v158, v159
	v_exp_f32_e32 v160, v160
	v_exp_f32_e32 v161, v161
	s_waitcnt lgkmcnt(10)
	v_mfma_f32_32x32x16_bf16 v[16:31], v[56:59], v[152:155], v[16:31]
	v_exp_f32_e32 v162, v162
	v_exp_f32_e32 v163, v163
	v_exp_f32_e32 v164, v164
	s_waitcnt lgkmcnt(8)
	v_mfma_f32_32x32x16_bf16 v[0:15], v[60:63], v[152:155], v[0:15]
	v_exp_f32_e32 v165, v165
	v_exp_f32_e32 v166, v166
	v_exp_f32_e32 v167, v167
	v_pk_add_f32 v[204:205], v[204:205], v[160:161]
	v_pk_add_f32 v[204:205], v[204:205], v[162:163]
	v_pk_add_f32 v[204:205], v[204:205], v[164:165]
	v_pk_add_f32 v[204:205], v[204:205], v[166:167]
	v_cvt_pk_bf16_f32 v160, v160, v161
	v_cvt_pk_bf16_f32 v161, v162, v163
	v_cvt_pk_bf16_f32 v162, v164, v165
	v_cvt_pk_bf16_f32 v163, v166, v167
	v_exp_f32_e32 v168, v168
	v_exp_f32_e32 v169, v169
	s_waitcnt lgkmcnt(6)
	v_mfma_f32_32x32x16_bf16 v[16:31], v[64:67], v[160:163], v[16:31]
	v_exp_f32_e32 v170, v170
	v_exp_f32_e32 v171, v171
	v_exp_f32_e32 v172, v172
	s_waitcnt lgkmcnt(4)
	v_mfma_f32_32x32x16_bf16 v[0:15], v[68:71], v[160:163], v[0:15]
	v_exp_f32_e32 v173, v173
	v_exp_f32_e32 v174, v174
	v_exp_f32_e32 v175, v175
	v_pk_add_f32 v[204:205], v[204:205], v[168:169]
	v_pk_add_f32 v[204:205], v[204:205], v[170:171]
	v_pk_add_f32 v[204:205], v[204:205], v[172:173]
	v_pk_add_f32 v[204:205], v[204:205], v[174:175]
	v_cvt_pk_bf16_f32 v168, v168, v169
	v_cvt_pk_bf16_f32 v169, v170, v171
	v_cvt_pk_bf16_f32 v170, v172, v173
	v_cvt_pk_bf16_f32 v171, v174, v175
	s_nop 1
	s_waitcnt lgkmcnt(2)
	v_mfma_f32_32x32x16_bf16 v[16:31], v[72:75], v[168:171], v[16:31]
	s_waitcnt lgkmcnt(0)
	v_mfma_f32_32x32x16_bf16 v[0:15], v[76:79], v[168:171], v[0:15]
	s_cmp_eq_u32 s99, 0
	s_cbranch_scc1 .Lm1_yB
	s_cmp_gt_u32 s13, 33
	s_cbranch_scc1 .Lm1_skipwy
	s_waitcnt vmcnt(5)
	ds_write_b128 v198, v[132:135]
	s_waitcnt vmcnt(4)
	ds_write_b128 v199, v[136:139]
	s_waitcnt vmcnt(3)
	ds_write_b128 v200, v[140:143] offset:26624

.LBB0_878:
	s_add_i32 s24, s47, 2
	s_min_i32 s24, s24, s34
	s_cmp_lt_i32 s24, s35
	s_cselect_b32 s25, s21, s46
	s_cselect_b32 s26, s29, s44
	s_add_i32 s25, s25, s24
	s_lshl_b32 s25, s25, 6
	s_add_i32 s26, s26, s25
	v_add_u32_e32 v236, s26, v161
	v_mad_i64_i32 v[236:237], s[98:99], v236, s33, v[164:165]
	global_load_dwordx4 v[120:123], v[236:237], off
	v_add_u32_e32 v236, s26, v163
	v_mad_i64_i32 v[236:237], s[98:99], v236, s33, v[166:167]
	global_load_dwordx4 v[124:127], v[236:237], off
	s_mov_b32 s24, s47
	s_cmp_ge_i32 s24, s35
	s_cbranch_scc1 .Lm0_ctxA
	s_add_i32 s25, s20, s24
	s_add_i32 s25, s25, -4
	s_cmp_lt_u32 s25, s39
	s_cbranch_scc1 .Lm0_doneA
	s_cmp_ge_u32 s25, s45
	s_cbranch_scc1 .Lm0_doneA
	s_cmp_lg_u32 s51, 0
	s_cbranch_scc1 .Lm0_m1A
	v_add_u32_e32 v236, v173, v162
	ds_read_b128 v[128:131], v236
	ds_read_b128 v[144:147], v236 offset:6656
	ds_read_b128 v[132:135], v236 offset:32
	ds_read_b128 v[148:151], v236 offset:6688
	ds_read_b128 v[136:139], v236 offset:64
	ds_read_b128 v[152:155], v236 offset:6720
	ds_read_b128 v[140:143], v236 offset:96
	ds_read_b128 v[156:159], v236 offset:6752
	v_add_u32_e32 v237, v175, v174
	s_waitcnt lgkmcnt(7)
	v_mfma_f32_32x32x16_bf16 v[32:47], v[128:131], v[96:99], v[218:233]
	s_waitcnt lgkmcnt(6)
	v_mfma_f32_32x32x16_bf16 v[48:63], v[144:147], v[96:99], v[218:233]
	s_waitcnt lgkmcnt(5)
	v_mfma_f32_32x32x16_bf16 v[32:47], v[132:135], v[100:103], v[32:47]
	s_waitcnt lgkmcnt(4)
	v_mfma_f32_32x32x16_bf16 v[48:63], v[148:151], v[100:103], v[48:63]
	s_waitcnt lgkmcnt(3)
	v_mfma_f32_32x32x16_bf16 v[32:47], v[136:139], v[104:107], v[32:47]
	s_waitcnt lgkmcnt(2)
	v_mfma_f32_32x32x16_bf16 v[48:63], v[152:155], v[104:107], v[48:63]
	s_waitcnt lgkmcnt(1)
	v_mfma_f32_32x32x16_bf16 v[32:47], v[140:143], v[108:111], v[32:47]
	s_waitcnt lgkmcnt(0)
	v_mfma_f32_32x32x16_bf16 v[48:63], v[156:159], v[108:111], v[48:63]
	ds_read_b32 v64, v177 offset:0
	ds_read_b32 v65, v177 offset:4
	ds_read_b32 v66, v177 offset:8
	ds_read_b32 v67, v177 offset:12
	ds_read_b32 v68, v177 offset:32
	ds_read_b32 v69, v177 offset:36
	ds_read_b32 v70, v177 offset:40
	ds_read_b32 v71, v177 offset:44
	ds_read_b32 v72, v177 offset:64
	ds_read_b32 v73, v177 offset:68
	ds_read_b32 v74, v177 offset:72
	ds_read_b32 v75, v177 offset:76
	ds_read_b32 v76, v177 offset:96
	ds_read_b32 v77, v177 offset:100
	ds_read_b32 v78, v177 offset:104
	ds_read_b32 v79, v177 offset:108
	ds_read_b32 v80, v177 offset:128
	ds_read_b32 v81, v177 offset:132
	ds_read_b32 v82, v177 offset:136
	ds_read_b32 v83, v177 offset:140
	ds_read_b32 v84, v177 offset:160
	ds_read_b32 v85, v177 offset:164
	ds_read_b32 v86, v177 offset:168
	ds_read_b32 v87, v177 offset:172
	ds_read_b64_tr_b16 v[186:187], v237 offset:26624
	ds_read_b64_tr_b16 v[188:189], v237 offset:28160
	ds_read_b64_tr_b16 v[190:191], v237 offset:26688
	ds_read_b64_tr_b16 v[192:193], v237 offset:28224
	ds_read_b64_tr_b16 v[194:195], v237 offset:29696
	ds_read_b64_tr_b16 v[196:197], v237 offset:31232
	ds_read_b64_tr_b16 v[198:199], v237 offset:29760
	ds_read_b64_tr_b16 v[200:201], v237 offset:31296
	ds_read_b64_tr_b16 v[202:203], v237 offset:32768
	ds_read_b64_tr_b16 v[204:205], v237 offset:34304
	ds_read_b64_tr_b16 v[206:207], v237 offset:32832
	ds_read_b64_tr_b16 v[208:209], v237 offset:34368
	v_readlane_b32 s24, v255, 33
	v_readlane_b32 s25, v255, 34
	v_readlane_b32 s26, v255, 37
	v_readlane_b32 s27, v255, 38
	s_waitcnt lgkmcnt(12)
	v_fmac_f32_e32 v64, 0x3e38aa3b, v32
	v_fmac_f32_e32 v65, 0x3e38aa3b, v33
	v_fmac_f32_e32 v66, 0x3e38aa3b, v34
	v_fmac_f32_e32 v67, 0x3e38aa3b, v35
	v_fmac_f32_e32 v68, 0x3e38aa3b, v36
	v_fmac_f32_e32 v69, 0x3e38aa3b, v37
	v_fmac_f32_e32 v70, 0x3e38aa3b, v38
	v_fmac_f32_e32 v71, 0x3e38aa3b, v39
	v_cndmask_b32_e64 v64, v64, v238, s[40:41]
	v_cndmask_b32_e64 v65, v65, v238, s[24:25]
	v_cndmask_b32_e64 v66, v66, v238, s[26:27]
	v_cndmask_b32_e64 v67, v67, v238, s[56:57]
	v_cndmask_b32_e64 v68, v68, v238, s[62:63]
	v_cndmask_b32_e64 v69, v69, v238, s[68:69]
	v_cndmask_b32_e64 v70, v70, v238, s[74:75]
	v_cndmask_b32_e64 v71, v71, v238, s[80:81]
	v_exp_f32_e32 v64, v64
	v_exp_f32_e32 v65, v65
	v_exp_f32_e32 v66, v66
	v_exp_f32_e32 v67, v67
	v_exp_f32_e32 v68, v68
	v_exp_f32_e32 v69, v69
	v_exp_f32_e32 v70, v70
	v_exp_f32_e32 v71, v71
	v_pk_add_f32 v[234:235], v[64:65], v[66:67]
	v_pk_add_f32 v[234:235], v[234:235], v[68:69]
	v_pk_add_f32 v[234:235], v[234:235], v[70:71]
	v_cvt_pk_bf16_f32 v64, v64, v65
	v_cvt_pk_bf16_f32 v65, v66, v67
	v_cvt_pk_bf16_f32 v66, v68, v69
	v_cvt_pk_bf16_f32 v67, v70, v71
	v_fmac_f32_e32 v72, 0x3e38aa3b, v40
	v_fmac_f32_e32 v73, 0x3e38aa3b, v41
	s_waitcnt lgkmcnt(10)
	v_mfma_f32_32x32x16_bf16 v[16:31], v[186:189], v[64:67], v[16:31]
	v_fmac_f32_e32 v74, 0x3e38aa3b, v42
	v_fmac_f32_e32 v75, 0x3e38aa3b, v43
	v_fmac_f32_e32 v76, 0x3e38aa3b, v44
	v_fmac_f32_e32 v77, 0x3e38aa3b, v45
	v_fmac_f32_e32 v78, 0x3e38aa3b, v46
	v_fmac_f32_e32 v79, 0x3e38aa3b, v47
	s_waitcnt lgkmcnt(8)
	v_mfma_f32_32x32x16_bf16 v[0:15], v[190:193], v[64:67], v[0:15]
	v_cndmask_b32_e64 v72, v238, v72, s[86:87]
	v_cndmask_b32_e64 v73, v238, v73, s[90:91]
	v_cndmask_b32_e64 v74, v238, v74, s[94:95]
	v_cndmask_b32_e64 v75, v238, v75, s[0:1]
	v_cndmask_b32_e64 v76, v238, v76, s[4:5]
	v_cndmask_b32_e64 v77, v238, v77, s[8:9]
	v_cndmask_b32_e64 v78, v238, v78, s[12:13]
	v_cndmask_b32_e64 v79, v238, v79, s[16:17]
	v_exp_f32_e32 v72, v72
	v_exp_f32_e32 v73, v73
	v_exp_f32_e32 v74, v74
	v_exp_f32_e32 v75, v75
	v_exp_f32_e32 v76, v76
	v_exp_f32_e32 v77, v77
	v_exp_f32_e32 v78, v78
	v_exp_f32_e32 v79, v79
	v_pk_add_f32 v[234:235], v[234:235], v[72:73]
	v_pk_add_f32 v[234:235], v[234:235], v[74:75]
	v_pk_add_f32 v[234:235], v[234:235], v[76:77]
	v_pk_add_f32 v[234:235], v[234:235], v[78:79]
	v_cvt_pk_bf16_f32 v72, v72, v73
	v_cvt_pk_bf16_f32 v73, v74, v75
	v_cvt_pk_bf16_f32 v74, v76, v77
	v_cvt_pk_bf16_f32 v75, v78, v79
	v_fmac_f32_e32 v80, 0x3e38aa3b, v48
	v_fmac_f32_e32 v81, 0x3e38aa3b, v49
	s_waitcnt lgkmcnt(6)
	v_mfma_f32_32x32x16_bf16 v[16:31], v[194:197], v[72:75], v[16:31]
	v_fmac_f32_e32 v82, 0x3e38aa3b, v50
	v_fmac_f32_e32 v83, 0x3e38aa3b, v51
	v_fmac_f32_e32 v84, 0x3e38aa3b, v52
	v_fmac_f32_e32 v85, 0x3e38aa3b, v53
	v_fmac_f32_e32 v86, 0x3e38aa3b, v54
	v_fmac_f32_e32 v87, 0x3e38aa3b, v55
	s_waitcnt lgkmcnt(4)
	v_mfma_f32_32x32x16_bf16 v[0:15], v[198:201], v[72:75], v[0:15]
	v_cndmask_b32_e64 v80, v238, v80, s[42:43]
	v_cndmask_b32_e64 v81, v238, v81, s[48:49]
	v_cndmask_b32_e64 v82, v238, v82, s[54:55]
	v_cndmask_b32_e64 v83, v238, v83, s[60:61]
	v_cndmask_b32_e64 v84, v238, v84, s[66:67]
	v_cndmask_b32_e64 v85, v238, v85, s[72:73]
	v_cndmask_b32_e64 v86, v238, v86, s[78:79]
	v_cndmask_b32_e64 v87, v238, v87, s[84:85]
	v_exp_f32_e32 v80, v80
	v_exp_f32_e32 v81, v81
	v_exp_f32_e32 v82, v82
	v_exp_f32_e32 v83, v83
	v_exp_f32_e32 v84, v84
	v_exp_f32_e32 v85, v85
	v_exp_f32_e32 v86, v86
	v_exp_f32_e32 v87, v87
	v_pk_add_f32 v[234:235], v[234:235], v[80:81]
	v_pk_add_f32 v[234:235], v[234:235], v[82:83]
	v_pk_add_f32 v[234:235], v[234:235], v[84:85]
	v_pk_add_f32 v[234:235], v[234:235], v[86:87]
	v_cvt_pk_bf16_f32 v80, v80, v81
	v_cvt_pk_bf16_f32 v81, v82, v83
	v_cvt_pk_bf16_f32 v82, v84, v85
	v_cvt_pk_bf16_f32 v83, v86, v87
	s_nop 1
	s_waitcnt lgkmcnt(2)
	v_mfma_f32_32x32x16_bf16 v[16:31], v[202:205], v[80:83], v[16:31]
	s_waitcnt lgkmcnt(0)
	v_mfma_f32_32x32x16_bf16 v[0:15], v[206:209], v[80:83], v[0:15]
	v_add_f32_e32 v234, v234, v235
	v_add_f32_e32 v176, v176, v234
	v_cmp_lt_f32_e32 vcc, 0x43000000, v234
	s_cbranch_vccz .Lm0_nr_m0A
	s_nop 15
	v_mov_b32_e32 v235, v234
	s_nop 1
	v_permlane32_swap_b32_e32 v234, v235
	v_add_f32_e32 v178, v234, v235
	v_cmp_lt_f32_e32 vcc, 0x43800000, v178
	v_frexp_exp_i32_f32_e32 v179, v178
	s_nop 1
	v_cndmask_b32_e32 v179, 0, v179, vcc
	v_cvt_f32_i32_e32 v180, v179
	v_sub_u32_e32 v179, 0, v179
	v_ldexp_f32 v178, 1.0, v179
	v_add_f32_e32 v168, v168, v180
	v_mul_f32_e32 v176, v176, v178
	v_mul_f32_e32 v0, v0, v178
	v_mul_f32_e32 v1, v1, v178
	v_mul_f32_e32 v2, v2, v178
	v_mul_f32_e32 v3, v3, v178
	v_mul_f32_e32 v4, v4, v178
	v_mul_f32_e32 v5, v5, v178
	v_mul_f32_e32 v6, v6, v178
	v_mul_f32_e32 v7, v7, v178
	v_mul_f32_e32 v8, v8, v178
	v_mul_f32_e32 v9, v9, v178
	v_mul_f32_e32 v10, v10, v178
	v_mul_f32_e32 v11, v11, v178
	v_mul_f32_e32 v12, v12, v178
	v_mul_f32_e32 v13, v13, v178
	v_mul_f32_e32 v14, v14, v178
	v_mul_f32_e32 v15, v15, v178
	v_mul_f32_e32 v16, v16, v178
	v_mul_f32_e32 v17, v17, v178
	v_mul_f32_e32 v18, v18, v178
	v_mul_f32_e32 v19, v19, v178
	v_mul_f32_e32 v20, v20, v178
	v_mul_f32_e32 v21, v21, v178
	v_mul_f32_e32 v22, v22, v178
	v_mul_f32_e32 v23, v23, v178
	v_mul_f32_e32 v24, v24, v178
	v_mul_f32_e32 v25, v25, v178
	v_mul_f32_e32 v26, v26, v178
	v_mul_f32_e32 v27, v27, v178
	v_mul_f32_e32 v28, v28, v178
	v_mul_f32_e32 v29, v29, v178
	v_mul_f32_e32 v30, v30, v178
	v_mul_f32_e32 v31, v31, v178
	v_mul_f32_e32 v218, 0xc0b17218, v168
	v_mov_b32_e32 v219, v218
	v_mov_b32_e32 v220, v218
	v_mov_b32_e32 v221, v218
	v_mov_b32_e32 v222, v218
	v_mov_b32_e32 v223, v218
	v_mov_b32_e32 v224, v218
	v_mov_b32_e32 v225, v218
	v_mov_b32_e32 v226, v218
	v_mov_b32_e32 v227, v218
	v_mov_b32_e32 v228, v218
	v_mov_b32_e32 v229, v218
	v_mov_b32_e32 v230, v218
	v_mov_b32_e32 v231, v218
	v_mov_b32_e32 v232, v218
	v_mov_b32_e32 v233, v218

.Lm0_m1A:
	v_add_u32_e32 v236, v173, v162
	ds_read_b128 v[128:131], v236
	ds_read_b128 v[144:147], v236 offset:6656
	ds_read_b128 v[132:135], v236 offset:32
	ds_read_b128 v[148:151], v236 offset:6688
	ds_read_b128 v[136:139], v236 offset:64
	ds_read_b128 v[152:155], v236 offset:6720
	ds_read_b128 v[140:143], v236 offset:96
	ds_read_b128 v[156:159], v236 offset:6752
	v_add_u32_e32 v237, v175, v174
	s_waitcnt lgkmcnt(7)
	v_mfma_f32_32x32x16_bf16 v[32:47], v[128:131], v[96:99], v[218:233]
	s_waitcnt lgkmcnt(6)
	v_mfma_f32_32x32x16_bf16 v[48:63], v[144:147], v[96:99], v[218:233]
	s_waitcnt lgkmcnt(5)
	v_mfma_f32_32x32x16_bf16 v[32:47], v[132:135], v[100:103], v[32:47]
	s_waitcnt lgkmcnt(4)
	v_mfma_f32_32x32x16_bf16 v[48:63], v[148:151], v[100:103], v[48:63]
	s_waitcnt lgkmcnt(3)
	v_mfma_f32_32x32x16_bf16 v[32:47], v[136:139], v[104:107], v[32:47]
	s_waitcnt lgkmcnt(2)
	v_mfma_f32_32x32x16_bf16 v[48:63], v[152:155], v[104:107], v[48:63]
	s_waitcnt lgkmcnt(1)
	v_mfma_f32_32x32x16_bf16 v[32:47], v[140:143], v[108:111], v[32:47]
	s_waitcnt lgkmcnt(0)
	v_mfma_f32_32x32x16_bf16 v[48:63], v[156:159], v[108:111], v[48:63]
	ds_read_b32 v72, v177 offset:64
	ds_read_b32 v73, v177 offset:68
	ds_read_b32 v74, v177 offset:72
	ds_read_b32 v75, v177 offset:76
	ds_read_b32 v76, v177 offset:96
	ds_read_b32 v77, v177 offset:100
	ds_read_b32 v78, v177 offset:104
	ds_read_b32 v79, v177 offset:108
	ds_read_b32 v80, v177 offset:128
	ds_read_b32 v81, v177 offset:132
	ds_read_b32 v82, v177 offset:136
	ds_read_b32 v83, v177 offset:140
	ds_read_b32 v84, v177 offset:160
	ds_read_b32 v85, v177 offset:164
	ds_read_b32 v86, v177 offset:168
	ds_read_b32 v87, v177 offset:172
	ds_read_b32 v88, v177 offset:192
	ds_read_b32 v89, v177 offset:196
	ds_read_b32 v90, v177 offset:200
	ds_read_b32 v91, v177 offset:204
	ds_read_b32 v92, v177 offset:224
	ds_read_b32 v93, v177 offset:228
	ds_read_b32 v94, v177 offset:232
	ds_read_b32 v95, v177 offset:236
	ds_read_b64_tr_b16 v[186:187], v237 offset:29696
	ds_read_b64_tr_b16 v[188:189], v237 offset:31232
	ds_read_b64_tr_b16 v[190:191], v237 offset:29760
	ds_read_b64_tr_b16 v[192:193], v237 offset:31296
	ds_read_b64_tr_b16 v[194:195], v237 offset:32768
	ds_read_b64_tr_b16 v[196:197], v237 offset:34304
	ds_read_b64_tr_b16 v[198:199], v237 offset:32832
	ds_read_b64_tr_b16 v[200:201], v237 offset:34368
	ds_read_b64_tr_b16 v[202:203], v237 offset:35840
	ds_read_b64_tr_b16 v[204:205], v237 offset:37376
	ds_read_b64_tr_b16 v[206:207], v237 offset:35904
	ds_read_b64_tr_b16 v[208:209], v237 offset:37440
	s_waitcnt lgkmcnt(12)
	v_fmac_f32_e32 v72, 0x3e38aa3b, v40
	v_fmac_f32_e32 v73, 0x3e38aa3b, v41
	v_fmac_f32_e32 v74, 0x3e38aa3b, v42
	v_fmac_f32_e32 v75, 0x3e38aa3b, v43
	v_fmac_f32_e32 v76, 0x3e38aa3b, v44
	v_fmac_f32_e32 v77, 0x3e38aa3b, v45
	v_fmac_f32_e32 v78, 0x3e38aa3b, v46
	v_fmac_f32_e32 v79, 0x3e38aa3b, v47
	v_cndmask_b32_e64 v72, v238, v72, s[86:87]
	v_cndmask_b32_e64 v73, v238, v73, s[90:91]
	v_cndmask_b32_e64 v74, v238, v74, s[94:95]
	v_cndmask_b32_e64 v75, v238, v75, s[0:1]
	v_cndmask_b32_e64 v76, v238, v76, s[4:5]
	v_cndmask_b32_e64 v77, v238, v77, s[8:9]
	v_cndmask_b32_e64 v78, v238, v78, s[12:13]
	v_cndmask_b32_e64 v79, v238, v79, s[16:17]
	v_exp_f32_e32 v72, v72
	v_exp_f32_e32 v73, v73
	v_exp_f32_e32 v74, v74
	v_exp_f32_e32 v75, v75
	v_exp_f32_e32 v76, v76
	v_exp_f32_e32 v77, v77
	v_exp_f32_e32 v78, v78
	v_exp_f32_e32 v79, v79
	v_pk_add_f32 v[234:235], v[72:73], v[74:75]
	v_pk_add_f32 v[234:235], v[234:235], v[76:77]
	v_pk_add_f32 v[234:235], v[234:235], v[78:79]
	v_cvt_pk_bf16_f32 v72, v72, v73
	v_cvt_pk_bf16_f32 v73, v74, v75
	v_cvt_pk_bf16_f32 v74, v76, v77
	v_cvt_pk_bf16_f32 v75, v78, v79
	v_fmac_f32_e32 v80, 0x3e38aa3b, v48
	v_fmac_f32_e32 v81, 0x3e38aa3b, v49
	s_waitcnt lgkmcnt(10)
	v_mfma_f32_32x32x16_bf16 v[16:31], v[186:189], v[72:75], v[16:31]
	v_fmac_f32_e32 v82, 0x3e38aa3b, v50
	v_fmac_f32_e32 v83, 0x3e38aa3b, v51
	v_fmac_f32_e32 v84, 0x3e38aa3b, v52
	v_fmac_f32_e32 v85, 0x3e38aa3b, v53
	v_fmac_f32_e32 v86, 0x3e38aa3b, v54
	v_fmac_f32_e32 v87, 0x3e38aa3b, v55
	s_waitcnt lgkmcnt(8)
	v_mfma_f32_32x32x16_bf16 v[0:15], v[190:193], v[72:75], v[0:15]
	v_cndmask_b32_e64 v80, v238, v80, s[42:43]
	v_cndmask_b32_e64 v81, v238, v81, s[48:49]
	v_cndmask_b32_e64 v82, v238, v82, s[54:55]
	v_cndmask_b32_e64 v83, v238, v83, s[60:61]
	v_cndmask_b32_e64 v84, v238, v84, s[66:67]
	v_cndmask_b32_e64 v85, v238, v85, s[72:73]
	v_cndmask_b32_e64 v86, v238, v86, s[78:79]
	v_cndmask_b32_e64 v87, v238, v87, s[84:85]
	v_exp_f32_e32 v80, v80
	v_exp_f32_e32 v81, v81
	v_exp_f32_e32 v82, v82
	v_exp_f32_e32 v83, v83
	v_exp_f32_e32 v84, v84
	v_exp_f32_e32 v85, v85
	v_exp_f32_e32 v86, v86
	v_exp_f32_e32 v87, v87
	v_pk_add_f32 v[234:235], v[234:235], v[80:81]
	v_pk_add_f32 v[234:235], v[234:235], v[82:83]
	v_pk_add_f32 v[234:235], v[234:235], v[84:85]
	v_pk_add_f32 v[234:235], v[234:235], v[86:87]
	v_cvt_pk_bf16_f32 v80, v80, v81
	v_cvt_pk_bf16_f32 v81, v82, v83
	v_cvt_pk_bf16_f32 v82, v84, v85
	v_cvt_pk_bf16_f32 v83, v86, v87
	v_fmac_f32_e32 v88, 0x3e38aa3b, v56
	v_fmac_f32_e32 v89, 0x3e38aa3b, v57
	s_waitcnt lgkmcnt(6)
	v_mfma_f32_32x32x16_bf16 v[16:31], v[194:197], v[80:83], v[16:31]
	v_fmac_f32_e32 v90, 0x3e38aa3b, v58
	v_fmac_f32_e32 v91, 0x3e38aa3b, v59
	v_fmac_f32_e32 v92, 0x3e38aa3b, v60
	v_fmac_f32_e32 v93, 0x3e38aa3b, v61
	v_fmac_f32_e32 v94, 0x3e38aa3b, v62
	v_fmac_f32_e32 v95, 0x3e38aa3b, v63
	s_waitcnt lgkmcnt(4)
	v_mfma_f32_32x32x16_bf16 v[0:15], v[198:201], v[80:83], v[0:15]
	v_cndmask_b32_e64 v88, v238, v88, s[88:89]
	v_cndmask_b32_e64 v89, v238, v89, s[92:93]
	v_cndmask_b32_e64 v90, v238, v90, s[96:97]
	v_cndmask_b32_e64 v91, v238, v91, s[2:3]
	v_cndmask_b32_e64 v92, v238, v92, s[6:7]
	v_cndmask_b32_e64 v93, v238, v93, s[10:11]
	v_cndmask_b32_e64 v94, v238, v94, s[14:15]
	v_cndmask_b32_e64 v95, v238, v95, s[18:19]
	v_exp_f32_e32 v88, v88
	v_exp_f32_e32 v89, v89
	v_exp_f32_e32 v90, v90
	v_exp_f32_e32 v91, v91
	v_exp_f32_e32 v92, v92
	v_exp_f32_e32 v93, v93
	v_exp_f32_e32 v94, v94
	v_exp_f32_e32 v95, v95
	v_pk_add_f32 v[234:235], v[234:235], v[88:89]
	v_pk_add_f32 v[234:235], v[234:235], v[90:91]
	v_pk_add_f32 v[234:235], v[234:235], v[92:93]
	v_pk_add_f32 v[234:235], v[234:235], v[94:95]
	v_cvt_pk_bf16_f32 v88, v88, v89
	v_cvt_pk_bf16_f32 v89, v90, v91
	v_cvt_pk_bf16_f32 v90, v92, v93
	v_cvt_pk_bf16_f32 v91, v94, v95
	s_nop 1
	s_waitcnt lgkmcnt(2)
	v_mfma_f32_32x32x16_bf16 v[16:31], v[202:205], v[88:91], v[16:31]
	s_waitcnt lgkmcnt(0)
	v_mfma_f32_32x32x16_bf16 v[0:15], v[206:209], v[88:91], v[0:15]
	v_add_f32_e32 v234, v234, v235
	v_add_f32_e32 v176, v176, v234
	v_cmp_lt_f32_e32 vcc, 0x43000000, v234
	s_cbranch_vccz .Lm0_nr_m1A
	s_nop 15
	v_mov_b32_e32 v235, v234
	s_nop 1
	v_permlane32_swap_b32_e32 v234, v235
	v_add_f32_e32 v178, v234, v235
	v_cmp_lt_f32_e32 vcc, 0x43800000, v178
	v_frexp_exp_i32_f32_e32 v179, v178
	s_nop 1
	v_cndmask_b32_e32 v179, 0, v179, vcc
	v_cvt_f32_i32_e32 v180, v179
	v_sub_u32_e32 v179, 0, v179
	v_ldexp_f32 v178, 1.0, v179
	v_add_f32_e32 v168, v168, v180
	v_mul_f32_e32 v176, v176, v178
	v_mul_f32_e32 v0, v0, v178
	v_mul_f32_e32 v1, v1, v178
	v_mul_f32_e32 v2, v2, v178
	v_mul_f32_e32 v3, v3, v178
	v_mul_f32_e32 v4, v4, v178
	v_mul_f32_e32 v5, v5, v178
	v_mul_f32_e32 v6, v6, v178
	v_mul_f32_e32 v7, v7, v178
	v_mul_f32_e32 v8, v8, v178
	v_mul_f32_e32 v9, v9, v178
	v_mul_f32_e32 v10, v10, v178
	v_mul_f32_e32 v11, v11, v178
	v_mul_f32_e32 v12, v12, v178
	v_mul_f32_e32 v13, v13, v178
	v_mul_f32_e32 v14, v14, v178
	v_mul_f32_e32 v15, v15, v178
	v_mul_f32_e32 v16, v16, v178
	v_mul_f32_e32 v17, v17, v178
	v_mul_f32_e32 v18, v18, v178
	v_mul_f32_e32 v19, v19, v178
	v_mul_f32_e32 v20, v20, v178
	v_mul_f32_e32 v21, v21, v178
	v_mul_f32_e32 v22, v22, v178
	v_mul_f32_e32 v23, v23, v178
	v_mul_f32_e32 v24, v24, v178
	v_mul_f32_e32 v25, v25, v178
	v_mul_f32_e32 v26, v26, v178
	v_mul_f32_e32 v27, v27, v178
	v_mul_f32_e32 v28, v28, v178
	v_mul_f32_e32 v29, v29, v178
	v_mul_f32_e32 v30, v30, v178
	v_mul_f32_e32 v31, v31, v178
	v_mul_f32_e32 v218, 0xc0b17218, v168
	v_mov_b32_e32 v219, v218
	v_mov_b32_e32 v220, v218
	v_mov_b32_e32 v221, v218
	v_mov_b32_e32 v222, v218
	v_mov_b32_e32 v223, v218
	v_mov_b32_e32 v224, v218
	v_mov_b32_e32 v225, v218
	v_mov_b32_e32 v226, v218
	v_mov_b32_e32 v227, v218
	v_mov_b32_e32 v228, v218
	v_mov_b32_e32 v229, v218
	v_mov_b32_e32 v230, v218
	v_mov_b32_e32 v231, v218
	v_mov_b32_e32 v232, v218
	v_mov_b32_e32 v233, v218

.Lm0_ctxA:
	v_add_u32_e32 v236, v173, v162
	ds_read_b128 v[128:131], v236
	ds_read_b128 v[144:147], v236 offset:6656
	ds_read_b128 v[132:135], v236 offset:32
	ds_read_b128 v[148:151], v236 offset:6688
	ds_read_b128 v[136:139], v236 offset:64
	ds_read_b128 v[152:155], v236 offset:6720
	ds_read_b128 v[140:143], v236 offset:96
	ds_read_b128 v[156:159], v236 offset:6752
	v_add_u32_e32 v237, v175, v174
	s_waitcnt lgkmcnt(7)
	v_mfma_f32_32x32x16_bf16 v[32:47], v[128:131], v[96:99], v[218:233]
	s_waitcnt lgkmcnt(6)
	v_mfma_f32_32x32x16_bf16 v[48:63], v[144:147], v[96:99], v[218:233]
	s_waitcnt lgkmcnt(5)
	v_mfma_f32_32x32x16_bf16 v[32:47], v[132:135], v[100:103], v[32:47]
	s_waitcnt lgkmcnt(4)
	v_mfma_f32_32x32x16_bf16 v[48:63], v[148:151], v[100:103], v[48:63]
	s_waitcnt lgkmcnt(3)
	v_mfma_f32_32x32x16_bf16 v[32:47], v[136:139], v[104:107], v[32:47]
	s_waitcnt lgkmcnt(2)
	v_mfma_f32_32x32x16_bf16 v[48:63], v[152:155], v[104:107], v[48:63]
	s_waitcnt lgkmcnt(1)
	v_mfma_f32_32x32x16_bf16 v[32:47], v[140:143], v[108:111], v[32:47]
	s_waitcnt lgkmcnt(0)
	v_mfma_f32_32x32x16_bf16 v[48:63], v[156:159], v[108:111], v[48:63]
	ds_read_b64_tr_b16 v[186:187], v237 offset:26624
	ds_read_b64_tr_b16 v[188:189], v237 offset:28160
	ds_read_b64_tr_b16 v[190:191], v237 offset:26688
	ds_read_b64_tr_b16 v[192:193], v237 offset:28224
	ds_read_b64_tr_b16 v[194:195], v237 offset:29696
	ds_read_b64_tr_b16 v[196:197], v237 offset:31232
	ds_read_b64_tr_b16 v[198:199], v237 offset:29760
	ds_read_b64_tr_b16 v[200:201], v237 offset:31296
	ds_read_b64_tr_b16 v[202:203], v237 offset:32768
	ds_read_b64_tr_b16 v[204:205], v237 offset:34304
	ds_read_b64_tr_b16 v[206:207], v237 offset:32832
	ds_read_b64_tr_b16 v[208:209], v237 offset:34368
	ds_read_b64_tr_b16 v[210:211], v237 offset:35840
	ds_read_b64_tr_b16 v[212:213], v237 offset:37376
	ds_read_b64_tr_b16 v[214:215], v237 offset:35904
	ds_read_b64_tr_b16 v[216:217], v237 offset:37440
	v_mul_f32_e32 v32, 0x3e38aa3b, v32
	v_mul_f32_e32 v33, 0x3e38aa3b, v33
	v_mul_f32_e32 v34, 0x3e38aa3b, v34
	v_mul_f32_e32 v35, 0x3e38aa3b, v35
	v_mul_f32_e32 v36, 0x3e38aa3b, v36
	v_mul_f32_e32 v37, 0x3e38aa3b, v37
	v_mul_f32_e32 v38, 0x3e38aa3b, v38
	v_mul_f32_e32 v39, 0x3e38aa3b, v39
	v_exp_f32_e32 v32, v32
	v_exp_f32_e32 v33, v33
	v_exp_f32_e32 v34, v34
	v_exp_f32_e32 v35, v35
	v_exp_f32_e32 v36, v36
	v_exp_f32_e32 v37, v37
	v_exp_f32_e32 v38, v38
	v_exp_f32_e32 v39, v39
	v_pk_add_f32 v[234:235], v[32:33], v[34:35]
	v_pk_add_f32 v[234:235], v[234:235], v[36:37]
	v_pk_add_f32 v[234:235], v[234:235], v[38:39]
	v_cvt_pk_bf16_f32 v32, v32, v33
	v_cvt_pk_bf16_f32 v33, v34, v35
	v_cvt_pk_bf16_f32 v34, v36, v37
	v_cvt_pk_bf16_f32 v35, v38, v39
	v_mul_f32_e32 v40, 0x3e38aa3b, v40
	v_mul_f32_e32 v41, 0x3e38aa3b, v41
	s_waitcnt lgkmcnt(14)
	v_mfma_f32_32x32x16_bf16 v[16:31], v[186:189], v[32:35], v[16:31]
	v_mul_f32_e32 v42, 0x3e38aa3b, v42
	v_mul_f32_e32 v43, 0x3e38aa3b, v43
	v_mul_f32_e32 v44, 0x3e38aa3b, v44
	v_mul_f32_e32 v45, 0x3e38aa3b, v45
	v_mul_f32_e32 v46, 0x3e38aa3b, v46
	v_mul_f32_e32 v47, 0x3e38aa3b, v47
	s_waitcnt lgkmcnt(12)
	v_mfma_f32_32x32x16_bf16 v[0:15], v[190:193], v[32:35], v[0:15]
	v_exp_f32_e32 v40, v40
	v_exp_f32_e32 v41, v41
	v_exp_f32_e32 v42, v42
	v_exp_f32_e32 v43, v43
	v_exp_f32_e32 v44, v44
	v_exp_f32_e32 v45, v45
	v_exp_f32_e32 v46, v46
	v_exp_f32_e32 v47, v47
	v_pk_add_f32 v[234:235], v[234:235], v[40:41]
	v_pk_add_f32 v[234:235], v[234:235], v[42:43]
	v_pk_add_f32 v[234:235], v[234:235], v[44:45]
	v_pk_add_f32 v[234:235], v[234:235], v[46:47]
	v_cvt_pk_bf16_f32 v40, v40, v41
	v_cvt_pk_bf16_f32 v41, v42, v43
	v_cvt_pk_bf16_f32 v42, v44, v45
	v_cvt_pk_bf16_f32 v43, v46, v47
	v_mul_f32_e32 v48, 0x3e38aa3b, v48
	v_mul_f32_e32 v49, 0x3e38aa3b, v49
	s_waitcnt lgkmcnt(10)
	v_mfma_f32_32x32x16_bf16 v[16:31], v[194:197], v[40:43], v[16:31]
	v_mul_f32_e32 v50, 0x3e38aa3b, v50
	v_mul_f32_e32 v51, 0x3e38aa3b, v51
	v_mul_f32_e32 v52, 0x3e38aa3b, v52
	v_mul_f32_e32 v53, 0x3e38aa3b, v53
	v_mul_f32_e32 v54, 0x3e38aa3b, v54
	v_mul_f32_e32 v55, 0x3e38aa3b, v55
	s_waitcnt lgkmcnt(8)
	v_mfma_f32_32x32x16_bf16 v[0:15], v[198:201], v[40:43], v[0:15]
	v_exp_f32_e32 v48, v48
	v_exp_f32_e32 v49, v49
	v_exp_f32_e32 v50, v50
	v_exp_f32_e32 v51, v51
	v_exp_f32_e32 v52, v52
	v_exp_f32_e32 v53, v53
	v_exp_f32_e32 v54, v54
	v_exp_f32_e32 v55, v55
	v_pk_add_f32 v[234:235], v[234:235], v[48:49]
	v_pk_add_f32 v[234:235], v[234:235], v[50:51]
	v_pk_add_f32 v[234:235], v[234:235], v[52:53]
	v_pk_add_f32 v[234:235], v[234:235], v[54:55]
	v_cvt_pk_bf16_f32 v48, v48, v49
	v_cvt_pk_bf16_f32 v49, v50, v51
	v_cvt_pk_bf16_f32 v50, v52, v53
	v_cvt_pk_bf16_f32 v51, v54, v55
	v_mul_f32_e32 v56, 0x3e38aa3b, v56
	v_mul_f32_e32 v57, 0x3e38aa3b, v57
	s_waitcnt lgkmcnt(6)
	v_mfma_f32_32x32x16_bf16 v[16:31], v[202:205], v[48:51], v[16:31]
	v_mul_f32_e32 v58, 0x3e38aa3b, v58
	v_mul_f32_e32 v59, 0x3e38aa3b, v59
	v_mul_f32_e32 v60, 0x3e38aa3b, v60
	v_mul_f32_e32 v61, 0x3e38aa3b, v61
	v_mul_f32_e32 v62, 0x3e38aa3b, v62
	v_mul_f32_e32 v63, 0x3e38aa3b, v63
	s_waitcnt lgkmcnt(4)
	v_mfma_f32_32x32x16_bf16 v[0:15], v[206:209], v[48:51], v[0:15]
	v_exp_f32_e32 v56, v56
	v_exp_f32_e32 v57, v57
	v_exp_f32_e32 v58, v58
	v_exp_f32_e32 v59, v59
	v_exp_f32_e32 v60, v60
	v_exp_f32_e32 v61, v61
	v_exp_f32_e32 v62, v62
	v_exp_f32_e32 v63, v63
	v_pk_add_f32 v[234:235], v[234:235], v[56:57]
	v_pk_add_f32 v[234:235], v[234:235], v[58:59]
	v_pk_add_f32 v[234:235], v[234:235], v[60:61]
	v_pk_add_f32 v[234:235], v[234:235], v[62:63]
	v_cvt_pk_bf16_f32 v56, v56, v57
	v_cvt_pk_bf16_f32 v57, v58, v59
	v_cvt_pk_bf16_f32 v58, v60, v61
	v_cvt_pk_bf16_f32 v59, v62, v63
	s_nop 1
	s_waitcnt lgkmcnt(2)
	v_mfma_f32_32x32x16_bf16 v[16:31], v[210:213], v[56:59], v[16:31]
	s_waitcnt lgkmcnt(0)
	v_mfma_f32_32x32x16_bf16 v[0:15], v[214:217], v[56:59], v[0:15]
	v_add_f32_e32 v234, v234, v235
	v_add_f32_e32 v176, v176, v234
	v_cmp_lt_f32_e32 vcc, 0x43000000, v234
	s_cbranch_vccz .Lm0_nr_cA
	s_nop 15
	v_mov_b32_e32 v235, v234
	s_nop 1
	v_permlane32_swap_b32_e32 v234, v235
	v_add_f32_e32 v178, v234, v235
	v_cmp_lt_f32_e32 vcc, 0x43800000, v178
	v_frexp_exp_i32_f32_e32 v179, v178
	s_nop 1
	v_cndmask_b32_e32 v179, 0, v179, vcc
	v_cvt_f32_i32_e32 v180, v179
	v_sub_u32_e32 v179, 0, v179
	v_ldexp_f32 v178, 1.0, v179
	v_add_f32_e32 v168, v168, v180
	v_mul_f32_e32 v176, v176, v178
	v_mul_f32_e32 v0, v0, v178
	v_mul_f32_e32 v1, v1, v178
	v_mul_f32_e32 v2, v2, v178
	v_mul_f32_e32 v3, v3, v178
	v_mul_f32_e32 v4, v4, v178
	v_mul_f32_e32 v5, v5, v178
	v_mul_f32_e32 v6, v6, v178
	v_mul_f32_e32 v7, v7, v178
	v_mul_f32_e32 v8, v8, v178
	v_mul_f32_e32 v9, v9, v178
	v_mul_f32_e32 v10, v10, v178
	v_mul_f32_e32 v11, v11, v178
	v_mul_f32_e32 v12, v12, v178
	v_mul_f32_e32 v13, v13, v178
	v_mul_f32_e32 v14, v14, v178
	v_mul_f32_e32 v15, v15, v178
	v_mul_f32_e32 v16, v16, v178
	v_mul_f32_e32 v17, v17, v178
	v_mul_f32_e32 v18, v18, v178
	v_mul_f32_e32 v19, v19, v178
	v_mul_f32_e32 v20, v20, v178
	v_mul_f32_e32 v21, v21, v178
	v_mul_f32_e32 v22, v22, v178
	v_mul_f32_e32 v23, v23, v178
	v_mul_f32_e32 v24, v24, v178
	v_mul_f32_e32 v25, v25, v178
	v_mul_f32_e32 v26, v26, v178
	v_mul_f32_e32 v27, v27, v178
	v_mul_f32_e32 v28, v28, v178
	v_mul_f32_e32 v29, v29, v178
	v_mul_f32_e32 v30, v30, v178
	v_mul_f32_e32 v31, v31, v178
	v_mul_f32_e32 v218, 0xc0b17218, v168
	v_mov_b32_e32 v219, v218
	v_mov_b32_e32 v220, v218
	v_mov_b32_e32 v221, v218
	v_mov_b32_e32 v222, v218
	v_mov_b32_e32 v223, v218
	v_mov_b32_e32 v224, v218
	v_mov_b32_e32 v225, v218
	v_mov_b32_e32 v226, v218
	v_mov_b32_e32 v227, v218
	v_mov_b32_e32 v228, v218
	v_mov_b32_e32 v229, v218
	v_mov_b32_e32 v230, v218
	v_mov_b32_e32 v231, v218
	v_mov_b32_e32 v232, v218
	v_mov_b32_e32 v233, v218

.Lm0_nwA:
	s_waitcnt lgkmcnt(0)
	s_barrier
	s_add_i32 s24, s47, 3
	s_min_i32 s24, s24, s34
	s_cmp_lt_i32 s24, s35
	s_cselect_b32 s25, s21, s46
	s_cselect_b32 s26, s29, s44
	s_add_i32 s25, s25, s24
	s_lshl_b32 s25, s25, 6
	s_add_i32 s26, s26, s25
	v_add_u32_e32 v236, s26, v161
	v_mad_i64_i32 v[236:237], s[98:99], v236, s33, v[164:165]
	global_load_dwordx4 v[112:115], v[236:237], off
	v_add_u32_e32 v236, s26, v163
	v_mad_i64_i32 v[236:237], s[98:99], v236, s33, v[166:167]
	global_load_dwordx4 v[116:119], v[236:237], off
	s_add_i32 s24, s47, 1
	s_cmp_ge_i32 s24, s38
	s_cbranch_scc1 .Lm0_doneB
	s_cmp_ge_i32 s24, s35
	s_cbranch_scc1 .Lm0_ctxB
	s_add_i32 s25, s20, s24
	s_add_i32 s25, s25, -4
	s_cmp_lt_u32 s25, s39
	s_cbranch_scc1 .Lm0_doneB
	s_cmp_ge_u32 s25, s45
	s_cbranch_scc1 .Lm0_doneB
	s_cmp_lg_u32 s51, 0
	s_cbranch_scc1 .Lm0_m1B
	v_add_u32_e32 v236, v173, v162
	ds_read_b128 v[128:131], v236 offset:13312
	ds_read_b128 v[144:147], v236 offset:19968
	ds_read_b128 v[132:135], v236 offset:13344
	ds_read_b128 v[148:151], v236 offset:20000
	ds_read_b128 v[136:139], v236 offset:13376
	ds_read_b128 v[152:155], v236 offset:20032
	ds_read_b128 v[140:143], v236 offset:13408
	ds_read_b128 v[156:159], v236 offset:20064
	v_add_u32_e32 v237, v175, v174
	s_waitcnt lgkmcnt(7)
	v_mfma_f32_32x32x16_bf16 v[32:47], v[128:131], v[96:99], v[218:233]
	s_waitcnt lgkmcnt(6)
	v_mfma_f32_32x32x16_bf16 v[48:63], v[144:147], v[96:99], v[218:233]
	s_waitcnt lgkmcnt(5)
	v_mfma_f32_32x32x16_bf16 v[32:47], v[132:135], v[100:103], v[32:47]
	s_waitcnt lgkmcnt(4)
	v_mfma_f32_32x32x16_bf16 v[48:63], v[148:151], v[100:103], v[48:63]
	s_waitcnt lgkmcnt(3)
	v_mfma_f32_32x32x16_bf16 v[32:47], v[136:139], v[104:107], v[32:47]
	s_waitcnt lgkmcnt(2)
	v_mfma_f32_32x32x16_bf16 v[48:63], v[152:155], v[104:107], v[48:63]
	s_waitcnt lgkmcnt(1)
	v_mfma_f32_32x32x16_bf16 v[32:47], v[140:143], v[108:111], v[32:47]
	s_waitcnt lgkmcnt(0)
	v_mfma_f32_32x32x16_bf16 v[48:63], v[156:159], v[108:111], v[48:63]
	ds_read_b32 v64, v177 offset:124
	ds_read_b32 v65, v177 offset:128
	ds_read_b32 v66, v177 offset:132
	ds_read_b32 v67, v177 offset:136
	ds_read_b32 v68, v177 offset:156
	ds_read_b32 v69, v177 offset:160
	ds_read_b32 v70, v177 offset:164
	ds_read_b32 v71, v177 offset:168
	ds_read_b32 v72, v177 offset:188
	ds_read_b32 v73, v177 offset:192
	ds_read_b32 v74, v177 offset:196
	ds_read_b32 v75, v177 offset:200
	ds_read_b32 v76, v177 offset:220
	ds_read_b32 v77, v177 offset:224
	ds_read_b32 v78, v177 offset:228
	ds_read_b32 v79, v177 offset:232
	ds_read_b32 v80, v177 offset:252
	ds_read_b32 v81, v177 offset:256
	ds_read_b32 v82, v177 offset:260
	ds_read_b32 v83, v177 offset:264
	ds_read_b32 v84, v177 offset:284
	ds_read_b32 v85, v177 offset:288
	ds_read_b32 v86, v177 offset:292
	ds_read_b32 v87, v177 offset:296
	ds_read_b64_tr_b16 v[186:187], v237 offset:38912
	ds_read_b64_tr_b16 v[188:189], v237 offset:40448
	ds_read_b64_tr_b16 v[190:191], v237 offset:38976
	ds_read_b64_tr_b16 v[192:193], v237 offset:40512
	ds_read_b64_tr_b16 v[194:195], v237 offset:41984
	ds_read_b64_tr_b16 v[196:197], v237 offset:43520
	ds_read_b64_tr_b16 v[198:199], v237 offset:42048
	ds_read_b64_tr_b16 v[200:201], v237 offset:43584
	ds_read_b64_tr_b16 v[202:203], v237 offset:45056
	ds_read_b64_tr_b16 v[204:205], v237 offset:46592
	ds_read_b64_tr_b16 v[206:207], v237 offset:45120
	ds_read_b64_tr_b16 v[208:209], v237 offset:46656
	v_readlane_b32 s24, v255, 33
	v_readlane_b32 s25, v255, 34
	v_readlane_b32 s26, v255, 37
	v_readlane_b32 s27, v255, 38
	s_waitcnt lgkmcnt(12)
	v_fmac_f32_e32 v64, 0x3e38aa3b, v32
	v_fmac_f32_e32 v65, 0x3e38aa3b, v33
	v_fmac_f32_e32 v66, 0x3e38aa3b, v34
	v_fmac_f32_e32 v67, 0x3e38aa3b, v35
	v_fmac_f32_e32 v68, 0x3e38aa3b, v36
	v_fmac_f32_e32 v69, 0x3e38aa3b, v37
	v_fmac_f32_e32 v70, 0x3e38aa3b, v38
	v_fmac_f32_e32 v71, 0x3e38aa3b, v39
	v_cndmask_b32_e64 v64, v64, v238, s[40:41]
	v_cndmask_b32_e64 v65, v65, v238, s[24:25]
	v_cndmask_b32_e64 v66, v66, v238, s[26:27]
	v_cndmask_b32_e64 v67, v67, v238, s[56:57]
	v_cndmask_b32_e64 v68, v68, v238, s[62:63]
	v_cndmask_b32_e64 v69, v69, v238, s[68:69]
	v_cndmask_b32_e64 v70, v70, v238, s[74:75]
	v_cndmask_b32_e64 v71, v71, v238, s[80:81]
	v_exp_f32_e32 v64, v64
	v_exp_f32_e32 v65, v65
	v_exp_f32_e32 v66, v66
	v_exp_f32_e32 v67, v67
	v_exp_f32_e32 v68, v68
	v_exp_f32_e32 v69, v69
	v_exp_f32_e32 v70, v70
	v_exp_f32_e32 v71, v71
	v_pk_add_f32 v[234:235], v[64:65], v[66:67]
	v_pk_add_f32 v[234:235], v[234:235], v[68:69]
	v_pk_add_f32 v[234:235], v[234:235], v[70:71]
	v_cvt_pk_bf16_f32 v64, v64, v65
	v_cvt_pk_bf16_f32 v65, v66, v67
	v_cvt_pk_bf16_f32 v66, v68, v69
	v_cvt_pk_bf16_f32 v67, v70, v71
	v_fmac_f32_e32 v72, 0x3e38aa3b, v40
	v_fmac_f32_e32 v73, 0x3e38aa3b, v41
	s_waitcnt lgkmcnt(10)
	v_mfma_f32_32x32x16_bf16 v[16:31], v[186:189], v[64:67], v[16:31]
	v_fmac_f32_e32 v74, 0x3e38aa3b, v42
	v_fmac_f32_e32 v75, 0x3e38aa3b, v43
	v_fmac_f32_e32 v76, 0x3e38aa3b, v44
	v_fmac_f32_e32 v77, 0x3e38aa3b, v45
	v_fmac_f32_e32 v78, 0x3e38aa3b, v46
	v_fmac_f32_e32 v79, 0x3e38aa3b, v47
	s_waitcnt lgkmcnt(8)
	v_mfma_f32_32x32x16_bf16 v[0:15], v[190:193], v[64:67], v[0:15]
	v_cndmask_b32_e64 v72, v238, v72, s[86:87]
	v_cndmask_b32_e64 v73, v238, v73, s[90:91]
	v_cndmask_b32_e64 v74, v238, v74, s[94:95]
	v_cndmask_b32_e64 v75, v238, v75, s[0:1]
	v_cndmask_b32_e64 v76, v238, v76, s[4:5]
	v_cndmask_b32_e64 v77, v238, v77, s[8:9]
	v_cndmask_b32_e64 v78, v238, v78, s[12:13]
	v_cndmask_b32_e64 v79, v238, v79, s[16:17]
	v_exp_f32_e32 v72, v72
	v_exp_f32_e32 v73, v73
	v_exp_f32_e32 v74, v74
	v_exp_f32_e32 v75, v75
	v_exp_f32_e32 v76, v76
	v_exp_f32_e32 v77, v77
	v_exp_f32_e32 v78, v78
	v_exp_f32_e32 v79, v79
	v_pk_add_f32 v[234:235], v[234:235], v[72:73]
	v_pk_add_f32 v[234:235], v[234:235], v[74:75]
	v_pk_add_f32 v[234:235], v[234:235], v[76:77]
	v_pk_add_f32 v[234:235], v[234:235], v[78:79]
	v_cvt_pk_bf16_f32 v72, v72, v73
	v_cvt_pk_bf16_f32 v73, v74, v75
	v_cvt_pk_bf16_f32 v74, v76, v77
	v_cvt_pk_bf16_f32 v75, v78, v79
	v_fmac_f32_e32 v80, 0x3e38aa3b, v48
	v_fmac_f32_e32 v81, 0x3e38aa3b, v49
	s_waitcnt lgkmcnt(6)
	v_mfma_f32_32x32x16_bf16 v[16:31], v[194:197], v[72:75], v[16:31]
	v_fmac_f32_e32 v82, 0x3e38aa3b, v50
	v_fmac_f32_e32 v83, 0x3e38aa3b, v51
	v_fmac_f32_e32 v84, 0x3e38aa3b, v52
	v_fmac_f32_e32 v85, 0x3e38aa3b, v53
	v_fmac_f32_e32 v86, 0x3e38aa3b, v54
	v_fmac_f32_e32 v87, 0x3e38aa3b, v55
	s_waitcnt lgkmcnt(4)
	v_mfma_f32_32x32x16_bf16 v[0:15], v[198:201], v[72:75], v[0:15]
	v_cndmask_b32_e64 v80, v238, v80, s[42:43]
	v_cndmask_b32_e64 v81, v238, v81, s[48:49]
	v_cndmask_b32_e64 v82, v238, v82, s[54:55]
	v_cndmask_b32_e64 v83, v238, v83, s[60:61]
	v_cndmask_b32_e64 v84, v238, v84, s[66:67]
	v_cndmask_b32_e64 v85, v238, v85, s[72:73]
	v_cndmask_b32_e64 v86, v238, v86, s[78:79]
	v_cndmask_b32_e64 v87, v238, v87, s[84:85]
	v_exp_f32_e32 v80, v80
	v_exp_f32_e32 v81, v81
	v_exp_f32_e32 v82, v82
	v_exp_f32_e32 v83, v83
	v_exp_f32_e32 v84, v84
	v_exp_f32_e32 v85, v85
	v_exp_f32_e32 v86, v86
	v_exp_f32_e32 v87, v87
	v_pk_add_f32 v[234:235], v[234:235], v[80:81]
	v_pk_add_f32 v[234:235], v[234:235], v[82:83]
	v_pk_add_f32 v[234:235], v[234:235], v[84:85]
	v_pk_add_f32 v[234:235], v[234:235], v[86:87]
	v_cvt_pk_bf16_f32 v80, v80, v81
	v_cvt_pk_bf16_f32 v81, v82, v83
	v_cvt_pk_bf16_f32 v82, v84, v85
	v_cvt_pk_bf16_f32 v83, v86, v87
	s_nop 1
	s_waitcnt lgkmcnt(2)
	v_mfma_f32_32x32x16_bf16 v[16:31], v[202:205], v[80:83], v[16:31]
	s_waitcnt lgkmcnt(0)
	v_mfma_f32_32x32x16_bf16 v[0:15], v[206:209], v[80:83], v[0:15]
	v_add_f32_e32 v234, v234, v235
	v_add_f32_e32 v176, v176, v234
	v_cmp_lt_f32_e32 vcc, 0x43000000, v234
	s_cbranch_vccz .Lm0_nr_m0B
	s_nop 15
	v_mov_b32_e32 v235, v234
	s_nop 1
	v_permlane32_swap_b32_e32 v234, v235
	v_add_f32_e32 v178, v234, v235
	v_cmp_lt_f32_e32 vcc, 0x43800000, v178
	v_frexp_exp_i32_f32_e32 v179, v178
	s_nop 1
	v_cndmask_b32_e32 v179, 0, v179, vcc
	v_cvt_f32_i32_e32 v180, v179
	v_sub_u32_e32 v179, 0, v179
	v_ldexp_f32 v178, 1.0, v179
	v_add_f32_e32 v168, v168, v180
	v_mul_f32_e32 v176, v176, v178
	v_mul_f32_e32 v0, v0, v178
	v_mul_f32_e32 v1, v1, v178
	v_mul_f32_e32 v2, v2, v178
	v_mul_f32_e32 v3, v3, v178
	v_mul_f32_e32 v4, v4, v178
	v_mul_f32_e32 v5, v5, v178
	v_mul_f32_e32 v6, v6, v178
	v_mul_f32_e32 v7, v7, v178
	v_mul_f32_e32 v8, v8, v178
	v_mul_f32_e32 v9, v9, v178
	v_mul_f32_e32 v10, v10, v178
	v_mul_f32_e32 v11, v11, v178
	v_mul_f32_e32 v12, v12, v178
	v_mul_f32_e32 v13, v13, v178
	v_mul_f32_e32 v14, v14, v178
	v_mul_f32_e32 v15, v15, v178
	v_mul_f32_e32 v16, v16, v178
	v_mul_f32_e32 v17, v17, v178
	v_mul_f32_e32 v18, v18, v178
	v_mul_f32_e32 v19, v19, v178
	v_mul_f32_e32 v20, v20, v178
	v_mul_f32_e32 v21, v21, v178
	v_mul_f32_e32 v22, v22, v178
	v_mul_f32_e32 v23, v23, v178
	v_mul_f32_e32 v24, v24, v178
	v_mul_f32_e32 v25, v25, v178
	v_mul_f32_e32 v26, v26, v178
	v_mul_f32_e32 v27, v27, v178
	v_mul_f32_e32 v28, v28, v178
	v_mul_f32_e32 v29, v29, v178
	v_mul_f32_e32 v30, v30, v178
	v_mul_f32_e32 v31, v31, v178
	v_mul_f32_e32 v218, 0xc0b17218, v168
	v_mov_b32_e32 v219, v218
	v_mov_b32_e32 v220, v218
	v_mov_b32_e32 v221, v218
	v_mov_b32_e32 v222, v218
	v_mov_b32_e32 v223, v218
	v_mov_b32_e32 v224, v218
	v_mov_b32_e32 v225, v218
	v_mov_b32_e32 v226, v218
	v_mov_b32_e32 v227, v218
	v_mov_b32_e32 v228, v218
	v_mov_b32_e32 v229, v218
	v_mov_b32_e32 v230, v218
	v_mov_b32_e32 v231, v218
	v_mov_b32_e32 v232, v218
	v_mov_b32_e32 v233, v218

.Lm0_m1B:
	v_add_u32_e32 v236, v173, v162
	ds_read_b128 v[128:131], v236 offset:13312
	ds_read_b128 v[144:147], v236 offset:19968
	ds_read_b128 v[132:135], v236 offset:13344
	ds_read_b128 v[148:151], v236 offset:20000
	ds_read_b128 v[136:139], v236 offset:13376
	ds_read_b128 v[152:155], v236 offset:20032
	ds_read_b128 v[140:143], v236 offset:13408
	ds_read_b128 v[156:159], v236 offset:20064
	v_add_u32_e32 v237, v175, v174
	s_waitcnt lgkmcnt(7)
	v_mfma_f32_32x32x16_bf16 v[32:47], v[128:131], v[96:99], v[218:233]
	s_waitcnt lgkmcnt(6)
	v_mfma_f32_32x32x16_bf16 v[48:63], v[144:147], v[96:99], v[218:233]
	s_waitcnt lgkmcnt(5)
	v_mfma_f32_32x32x16_bf16 v[32:47], v[132:135], v[100:103], v[32:47]
	s_waitcnt lgkmcnt(4)
	v_mfma_f32_32x32x16_bf16 v[48:63], v[148:151], v[100:103], v[48:63]
	s_waitcnt lgkmcnt(3)
	v_mfma_f32_32x32x16_bf16 v[32:47], v[136:139], v[104:107], v[32:47]
	s_waitcnt lgkmcnt(2)
	v_mfma_f32_32x32x16_bf16 v[48:63], v[152:155], v[104:107], v[48:63]
	s_waitcnt lgkmcnt(1)
	v_mfma_f32_32x32x16_bf16 v[32:47], v[140:143], v[108:111], v[32:47]
	s_waitcnt lgkmcnt(0)
	v_mfma_f32_32x32x16_bf16 v[48:63], v[156:159], v[108:111], v[48:63]
	ds_read_b32 v72, v177 offset:188
	ds_read_b32 v73, v177 offset:192
	ds_read_b32 v74, v177 offset:196
	ds_read_b32 v75, v177 offset:200
	ds_read_b32 v76, v177 offset:220
	ds_read_b32 v77, v177 offset:224
	ds_read_b32 v78, v177 offset:228
	ds_read_b32 v79, v177 offset:232
	ds_read_b32 v80, v177 offset:252
	ds_read_b32 v81, v177 offset:256
	ds_read_b32 v82, v177 offset:260
	ds_read_b32 v83, v177 offset:264
	ds_read_b32 v84, v177 offset:284
	ds_read_b32 v85, v177 offset:288
	ds_read_b32 v86, v177 offset:292
	ds_read_b32 v87, v177 offset:296
	ds_read_b32 v88, v177 offset:316
	ds_read_b32 v89, v177 offset:320
	ds_read_b32 v90, v177 offset:324
	ds_read_b32 v91, v177 offset:328
	ds_read_b32 v92, v177 offset:348
	ds_read_b32 v93, v177 offset:352
	ds_read_b32 v94, v177 offset:356
	ds_read_b32 v95, v177 offset:360
	ds_read_b64_tr_b16 v[186:187], v237 offset:41984
	ds_read_b64_tr_b16 v[188:189], v237 offset:43520
	ds_read_b64_tr_b16 v[190:191], v237 offset:42048
	ds_read_b64_tr_b16 v[192:193], v237 offset:43584
	ds_read_b64_tr_b16 v[194:195], v237 offset:45056
	ds_read_b64_tr_b16 v[196:197], v237 offset:46592
	ds_read_b64_tr_b16 v[198:199], v237 offset:45120
	ds_read_b64_tr_b16 v[200:201], v237 offset:46656
	ds_read_b64_tr_b16 v[202:203], v237 offset:48128
	ds_read_b64_tr_b16 v[204:205], v237 offset:49664
	ds_read_b64_tr_b16 v[206:207], v237 offset:48192
	ds_read_b64_tr_b16 v[208:209], v237 offset:49728
	s_waitcnt lgkmcnt(12)
	v_fmac_f32_e32 v72, 0x3e38aa3b, v40
	v_fmac_f32_e32 v73, 0x3e38aa3b, v41
	v_fmac_f32_e32 v74, 0x3e38aa3b, v42
	v_fmac_f32_e32 v75, 0x3e38aa3b, v43
	v_fmac_f32_e32 v76, 0x3e38aa3b, v44
	v_fmac_f32_e32 v77, 0x3e38aa3b, v45
	v_fmac_f32_e32 v78, 0x3e38aa3b, v46
	v_fmac_f32_e32 v79, 0x3e38aa3b, v47
	v_cndmask_b32_e64 v72, v238, v72, s[86:87]
	v_cndmask_b32_e64 v73, v238, v73, s[90:91]
	v_cndmask_b32_e64 v74, v238, v74, s[94:95]
	v_cndmask_b32_e64 v75, v238, v75, s[0:1]
	v_cndmask_b32_e64 v76, v238, v76, s[4:5]
	v_cndmask_b32_e64 v77, v238, v77, s[8:9]
	v_cndmask_b32_e64 v78, v238, v78, s[12:13]
	v_cndmask_b32_e64 v79, v238, v79, s[16:17]
	v_exp_f32_e32 v72, v72
	v_exp_f32_e32 v73, v73
	v_exp_f32_e32 v74, v74
	v_exp_f32_e32 v75, v75
	v_exp_f32_e32 v76, v76
	v_exp_f32_e32 v77, v77
	v_exp_f32_e32 v78, v78
	v_exp_f32_e32 v79, v79
	v_pk_add_f32 v[234:235], v[72:73], v[74:75]
	v_pk_add_f32 v[234:235], v[234:235], v[76:77]
	v_pk_add_f32 v[234:235], v[234:235], v[78:79]
	v_cvt_pk_bf16_f32 v72, v72, v73
	v_cvt_pk_bf16_f32 v73, v74, v75
	v_cvt_pk_bf16_f32 v74, v76, v77
	v_cvt_pk_bf16_f32 v75, v78, v79
	v_fmac_f32_e32 v80, 0x3e38aa3b, v48
	v_fmac_f32_e32 v81, 0x3e38aa3b, v49
	s_waitcnt lgkmcnt(10)
	v_mfma_f32_32x32x16_bf16 v[16:31], v[186:189], v[72:75], v[16:31]
	v_fmac_f32_e32 v82, 0x3e38aa3b, v50
	v_fmac_f32_e32 v83, 0x3e38aa3b, v51
	v_fmac_f32_e32 v84, 0x3e38aa3b, v52
	v_fmac_f32_e32 v85, 0x3e38aa3b, v53
	v_fmac_f32_e32 v86, 0x3e38aa3b, v54
	v_fmac_f32_e32 v87, 0x3e38aa3b, v55
	s_waitcnt lgkmcnt(8)
	v_mfma_f32_32x32x16_bf16 v[0:15], v[190:193], v[72:75], v[0:15]
	v_cndmask_b32_e64 v80, v238, v80, s[42:43]
	v_cndmask_b32_e64 v81, v238, v81, s[48:49]
	v_cndmask_b32_e64 v82, v238, v82, s[54:55]
	v_cndmask_b32_e64 v83, v238, v83, s[60:61]
	v_cndmask_b32_e64 v84, v238, v84, s[66:67]
	v_cndmask_b32_e64 v85, v238, v85, s[72:73]
	v_cndmask_b32_e64 v86, v238, v86, s[78:79]
	v_cndmask_b32_e64 v87, v238, v87, s[84:85]
	v_exp_f32_e32 v80, v80
	v_exp_f32_e32 v81, v81
	v_exp_f32_e32 v82, v82
	v_exp_f32_e32 v83, v83
	v_exp_f32_e32 v84, v84
	v_exp_f32_e32 v85, v85
	v_exp_f32_e32 v86, v86
	v_exp_f32_e32 v87, v87
	v_pk_add_f32 v[234:235], v[234:235], v[80:81]
	v_pk_add_f32 v[234:235], v[234:235], v[82:83]
	v_pk_add_f32 v[234:235], v[234:235], v[84:85]
	v_pk_add_f32 v[234:235], v[234:235], v[86:87]
	v_cvt_pk_bf16_f32 v80, v80, v81
	v_cvt_pk_bf16_f32 v81, v82, v83
	v_cvt_pk_bf16_f32 v82, v84, v85
	v_cvt_pk_bf16_f32 v83, v86, v87
	v_fmac_f32_e32 v88, 0x3e38aa3b, v56
	v_fmac_f32_e32 v89, 0x3e38aa3b, v57
	s_waitcnt lgkmcnt(6)
	v_mfma_f32_32x32x16_bf16 v[16:31], v[194:197], v[80:83], v[16:31]
	v_fmac_f32_e32 v90, 0x3e38aa3b, v58
	v_fmac_f32_e32 v91, 0x3e38aa3b, v59
	v_fmac_f32_e32 v92, 0x3e38aa3b, v60
	v_fmac_f32_e32 v93, 0x3e38aa3b, v61
	v_fmac_f32_e32 v94, 0x3e38aa3b, v62
	v_fmac_f32_e32 v95, 0x3e38aa3b, v63
	s_waitcnt lgkmcnt(4)
	v_mfma_f32_32x32x16_bf16 v[0:15], v[198:201], v[80:83], v[0:15]
	v_cndmask_b32_e64 v88, v238, v88, s[88:89]
	v_cndmask_b32_e64 v89, v238, v89, s[92:93]
	v_cndmask_b32_e64 v90, v238, v90, s[96:97]
	v_cndmask_b32_e64 v91, v238, v91, s[2:3]
	v_cndmask_b32_e64 v92, v238, v92, s[6:7]
	v_cndmask_b32_e64 v93, v238, v93, s[10:11]
	v_cndmask_b32_e64 v94, v238, v94, s[14:15]
	v_cndmask_b32_e64 v95, v238, v95, s[18:19]
	v_exp_f32_e32 v88, v88
	v_exp_f32_e32 v89, v89
	v_exp_f32_e32 v90, v90
	v_exp_f32_e32 v91, v91
	v_exp_f32_e32 v92, v92
	v_exp_f32_e32 v93, v93
	v_exp_f32_e32 v94, v94
	v_exp_f32_e32 v95, v95
	v_pk_add_f32 v[234:235], v[234:235], v[88:89]
	v_pk_add_f32 v[234:235], v[234:235], v[90:91]
	v_pk_add_f32 v[234:235], v[234:235], v[92:93]
	v_pk_add_f32 v[234:235], v[234:235], v[94:95]
	v_cvt_pk_bf16_f32 v88, v88, v89
	v_cvt_pk_bf16_f32 v89, v90, v91
	v_cvt_pk_bf16_f32 v90, v92, v93
	v_cvt_pk_bf16_f32 v91, v94, v95
	s_nop 1
	s_waitcnt lgkmcnt(2)
	v_mfma_f32_32x32x16_bf16 v[16:31], v[202:205], v[88:91], v[16:31]
	s_waitcnt lgkmcnt(0)
	v_mfma_f32_32x32x16_bf16 v[0:15], v[206:209], v[88:91], v[0:15]
	v_add_f32_e32 v234, v234, v235
	v_add_f32_e32 v176, v176, v234
	v_cmp_lt_f32_e32 vcc, 0x43000000, v234
	s_cbranch_vccz .Lm0_nr_m1B
	s_nop 15
	v_mov_b32_e32 v235, v234
	s_nop 1
	v_permlane32_swap_b32_e32 v234, v235
	v_add_f32_e32 v178, v234, v235
	v_cmp_lt_f32_e32 vcc, 0x43800000, v178
	v_frexp_exp_i32_f32_e32 v179, v178
	s_nop 1
	v_cndmask_b32_e32 v179, 0, v179, vcc
	v_cvt_f32_i32_e32 v180, v179
	v_sub_u32_e32 v179, 0, v179
	v_ldexp_f32 v178, 1.0, v179
	v_add_f32_e32 v168, v168, v180
	v_mul_f32_e32 v176, v176, v178
	v_mul_f32_e32 v0, v0, v178
	v_mul_f32_e32 v1, v1, v178
	v_mul_f32_e32 v2, v2, v178
	v_mul_f32_e32 v3, v3, v178
	v_mul_f32_e32 v4, v4, v178
	v_mul_f32_e32 v5, v5, v178
	v_mul_f32_e32 v6, v6, v178
	v_mul_f32_e32 v7, v7, v178
	v_mul_f32_e32 v8, v8, v178
	v_mul_f32_e32 v9, v9, v178
	v_mul_f32_e32 v10, v10, v178
	v_mul_f32_e32 v11, v11, v178
	v_mul_f32_e32 v12, v12, v178
	v_mul_f32_e32 v13, v13, v178
	v_mul_f32_e32 v14, v14, v178
	v_mul_f32_e32 v15, v15, v178
	v_mul_f32_e32 v16, v16, v178
	v_mul_f32_e32 v17, v17, v178
	v_mul_f32_e32 v18, v18, v178
	v_mul_f32_e32 v19, v19, v178
	v_mul_f32_e32 v20, v20, v178
	v_mul_f32_e32 v21, v21, v178
	v_mul_f32_e32 v22, v22, v178
	v_mul_f32_e32 v23, v23, v178
	v_mul_f32_e32 v24, v24, v178
	v_mul_f32_e32 v25, v25, v178
	v_mul_f32_e32 v26, v26, v178
	v_mul_f32_e32 v27, v27, v178
	v_mul_f32_e32 v28, v28, v178
	v_mul_f32_e32 v29, v29, v178
	v_mul_f32_e32 v30, v30, v178
	v_mul_f32_e32 v31, v31, v178
	v_mul_f32_e32 v218, 0xc0b17218, v168
	v_mov_b32_e32 v219, v218
	v_mov_b32_e32 v220, v218
	v_mov_b32_e32 v221, v218
	v_mov_b32_e32 v222, v218
	v_mov_b32_e32 v223, v218
	v_mov_b32_e32 v224, v218
	v_mov_b32_e32 v225, v218
	v_mov_b32_e32 v226, v218
	v_mov_b32_e32 v227, v218
	v_mov_b32_e32 v228, v218
	v_mov_b32_e32 v229, v218
	v_mov_b32_e32 v230, v218
	v_mov_b32_e32 v231, v218
	v_mov_b32_e32 v232, v218
	v_mov_b32_e32 v233, v218

.Lm0_ctxB:
	v_add_u32_e32 v236, v173, v162
	ds_read_b128 v[128:131], v236 offset:13312
	ds_read_b128 v[144:147], v236 offset:19968
	ds_read_b128 v[132:135], v236 offset:13344
	ds_read_b128 v[148:151], v236 offset:20000
	ds_read_b128 v[136:139], v236 offset:13376
	ds_read_b128 v[152:155], v236 offset:20032
	ds_read_b128 v[140:143], v236 offset:13408
	ds_read_b128 v[156:159], v236 offset:20064
	v_add_u32_e32 v237, v175, v174
	s_waitcnt lgkmcnt(7)
	v_mfma_f32_32x32x16_bf16 v[32:47], v[128:131], v[96:99], v[218:233]
	s_waitcnt lgkmcnt(6)
	v_mfma_f32_32x32x16_bf16 v[48:63], v[144:147], v[96:99], v[218:233]
	s_waitcnt lgkmcnt(5)
	v_mfma_f32_32x32x16_bf16 v[32:47], v[132:135], v[100:103], v[32:47]
	s_waitcnt lgkmcnt(4)
	v_mfma_f32_32x32x16_bf16 v[48:63], v[148:151], v[100:103], v[48:63]
	s_waitcnt lgkmcnt(3)
	v_mfma_f32_32x32x16_bf16 v[32:47], v[136:139], v[104:107], v[32:47]
	s_waitcnt lgkmcnt(2)
	v_mfma_f32_32x32x16_bf16 v[48:63], v[152:155], v[104:107], v[48:63]
	s_waitcnt lgkmcnt(1)
	v_mfma_f32_32x32x16_bf16 v[32:47], v[140:143], v[108:111], v[32:47]
	s_waitcnt lgkmcnt(0)
	v_mfma_f32_32x32x16_bf16 v[48:63], v[156:159], v[108:111], v[48:63]
	ds_read_b64_tr_b16 v[186:187], v237 offset:38912
	ds_read_b64_tr_b16 v[188:189], v237 offset:40448
	ds_read_b64_tr_b16 v[190:191], v237 offset:38976
	ds_read_b64_tr_b16 v[192:193], v237 offset:40512
	ds_read_b64_tr_b16 v[194:195], v237 offset:41984
	ds_read_b64_tr_b16 v[196:197], v237 offset:43520
	ds_read_b64_tr_b16 v[198:199], v237 offset:42048
	ds_read_b64_tr_b16 v[200:201], v237 offset:43584
	ds_read_b64_tr_b16 v[202:203], v237 offset:45056
	ds_read_b64_tr_b16 v[204:205], v237 offset:46592
	ds_read_b64_tr_b16 v[206:207], v237 offset:45120
	ds_read_b64_tr_b16 v[208:209], v237 offset:46656
	ds_read_b64_tr_b16 v[210:211], v237 offset:48128
	ds_read_b64_tr_b16 v[212:213], v237 offset:49664
	ds_read_b64_tr_b16 v[214:215], v237 offset:48192
	ds_read_b64_tr_b16 v[216:217], v237 offset:49728
	v_mul_f32_e32 v32, 0x3e38aa3b, v32
	v_mul_f32_e32 v33, 0x3e38aa3b, v33
	v_mul_f32_e32 v34, 0x3e38aa3b, v34
	v_mul_f32_e32 v35, 0x3e38aa3b, v35
	v_mul_f32_e32 v36, 0x3e38aa3b, v36
	v_mul_f32_e32 v37, 0x3e38aa3b, v37
	v_mul_f32_e32 v38, 0x3e38aa3b, v38
	v_mul_f32_e32 v39, 0x3e38aa3b, v39
	v_exp_f32_e32 v32, v32
	v_exp_f32_e32 v33, v33
	v_exp_f32_e32 v34, v34
	v_exp_f32_e32 v35, v35
	v_exp_f32_e32 v36, v36
	v_exp_f32_e32 v37, v37
	v_exp_f32_e32 v38, v38
	v_exp_f32_e32 v39, v39
	v_pk_add_f32 v[234:235], v[32:33], v[34:35]
	v_pk_add_f32 v[234:235], v[234:235], v[36:37]
	v_pk_add_f32 v[234:235], v[234:235], v[38:39]
	v_cvt_pk_bf16_f32 v32, v32, v33
	v_cvt_pk_bf16_f32 v33, v34, v35
	v_cvt_pk_bf16_f32 v34, v36, v37
	v_cvt_pk_bf16_f32 v35, v38, v39
	v_mul_f32_e32 v40, 0x3e38aa3b, v40
	v_mul_f32_e32 v41, 0x3e38aa3b, v41
	s_waitcnt lgkmcnt(14)
	v_mfma_f32_32x32x16_bf16 v[16:31], v[186:189], v[32:35], v[16:31]
	v_mul_f32_e32 v42, 0x3e38aa3b, v42
	v_mul_f32_e32 v43, 0x3e38aa3b, v43
	v_mul_f32_e32 v44, 0x3e38aa3b, v44
	v_mul_f32_e32 v45, 0x3e38aa3b, v45
	v_mul_f32_e32 v46, 0x3e38aa3b, v46
	v_mul_f32_e32 v47, 0x3e38aa3b, v47
	s_waitcnt lgkmcnt(12)
	v_mfma_f32_32x32x16_bf16 v[0:15], v[190:193], v[32:35], v[0:15]
	v_exp_f32_e32 v40, v40
	v_exp_f32_e32 v41, v41
	v_exp_f32_e32 v42, v42
	v_exp_f32_e32 v43, v43
	v_exp_f32_e32 v44, v44
	v_exp_f32_e32 v45, v45
	v_exp_f32_e32 v46, v46
	v_exp_f32_e32 v47, v47
	v_pk_add_f32 v[234:235], v[234:235], v[40:41]
	v_pk_add_f32 v[234:235], v[234:235], v[42:43]
	v_pk_add_f32 v[234:235], v[234:235], v[44:45]
	v_pk_add_f32 v[234:235], v[234:235], v[46:47]
	v_cvt_pk_bf16_f32 v40, v40, v41
	v_cvt_pk_bf16_f32 v41, v42, v43
	v_cvt_pk_bf16_f32 v42, v44, v45
	v_cvt_pk_bf16_f32 v43, v46, v47
	v_mul_f32_e32 v48, 0x3e38aa3b, v48
	v_mul_f32_e32 v49, 0x3e38aa3b, v49
	s_waitcnt lgkmcnt(10)
	v_mfma_f32_32x32x16_bf16 v[16:31], v[194:197], v[40:43], v[16:31]
	v_mul_f32_e32 v50, 0x3e38aa3b, v50
	v_mul_f32_e32 v51, 0x3e38aa3b, v51
	v_mul_f32_e32 v52, 0x3e38aa3b, v52
	v_mul_f32_e32 v53, 0x3e38aa3b, v53
	v_mul_f32_e32 v54, 0x3e38aa3b, v54
	v_mul_f32_e32 v55, 0x3e38aa3b, v55
	s_waitcnt lgkmcnt(8)
	v_mfma_f32_32x32x16_bf16 v[0:15], v[198:201], v[40:43], v[0:15]
	v_exp_f32_e32 v48, v48
	v_exp_f32_e32 v49, v49
	v_exp_f32_e32 v50, v50
	v_exp_f32_e32 v51, v51
	v_exp_f32_e32 v52, v52
	v_exp_f32_e32 v53, v53
	v_exp_f32_e32 v54, v54
	v_exp_f32_e32 v55, v55
	v_pk_add_f32 v[234:235], v[234:235], v[48:49]
	v_pk_add_f32 v[234:235], v[234:235], v[50:51]
	v_pk_add_f32 v[234:235], v[234:235], v[52:53]
	v_pk_add_f32 v[234:235], v[234:235], v[54:55]
	v_cvt_pk_bf16_f32 v48, v48, v49
	v_cvt_pk_bf16_f32 v49, v50, v51
	v_cvt_pk_bf16_f32 v50, v52, v53
	v_cvt_pk_bf16_f32 v51, v54, v55
	v_mul_f32_e32 v56, 0x3e38aa3b, v56
	v_mul_f32_e32 v57, 0x3e38aa3b, v57
	s_waitcnt lgkmcnt(6)
	v_mfma_f32_32x32x16_bf16 v[16:31], v[202:205], v[48:51], v[16:31]
	v_mul_f32_e32 v58, 0x3e38aa3b, v58
	v_mul_f32_e32 v59, 0x3e38aa3b, v59
	v_mul_f32_e32 v60, 0x3e38aa3b, v60
	v_mul_f32_e32 v61, 0x3e38aa3b, v61
	v_mul_f32_e32 v62, 0x3e38aa3b, v62
	v_mul_f32_e32 v63, 0x3e38aa3b, v63
	s_waitcnt lgkmcnt(4)
	v_mfma_f32_32x32x16_bf16 v[0:15], v[206:209], v[48:51], v[0:15]
	v_exp_f32_e32 v56, v56
	v_exp_f32_e32 v57, v57
	v_exp_f32_e32 v58, v58
	v_exp_f32_e32 v59, v59
	v_exp_f32_e32 v60, v60
	v_exp_f32_e32 v61, v61
	v_exp_f32_e32 v62, v62
	v_exp_f32_e32 v63, v63
	v_pk_add_f32 v[234:235], v[234:235], v[56:57]
	v_pk_add_f32 v[234:235], v[234:235], v[58:59]
	v_pk_add_f32 v[234:235], v[234:235], v[60:61]
	v_pk_add_f32 v[234:235], v[234:235], v[62:63]
	v_cvt_pk_bf16_f32 v56, v56, v57
	v_cvt_pk_bf16_f32 v57, v58, v59
	v_cvt_pk_bf16_f32 v58, v60, v61
	v_cvt_pk_bf16_f32 v59, v62, v63
	s_nop 1
	s_waitcnt lgkmcnt(2)
	v_mfma_f32_32x32x16_bf16 v[16:31], v[210:213], v[56:59], v[16:31]
	s_waitcnt lgkmcnt(0)
	v_mfma_f32_32x32x16_bf16 v[0:15], v[214:217], v[56:59], v[0:15]
	v_add_f32_e32 v234, v234, v235
	v_add_f32_e32 v176, v176, v234
	v_cmp_lt_f32_e32 vcc, 0x43000000, v234
	s_cbranch_vccz .Lm0_nr_cB
	s_nop 15
	v_mov_b32_e32 v235, v234
	s_nop 1
	v_permlane32_swap_b32_e32 v234, v235
	v_add_f32_e32 v178, v234, v235
	v_cmp_lt_f32_e32 vcc, 0x43800000, v178
	v_frexp_exp_i32_f32_e32 v179, v178
	s_nop 1
	v_cndmask_b32_e32 v179, 0, v179, vcc
	v_cvt_f32_i32_e32 v180, v179
	v_sub_u32_e32 v179, 0, v179
	v_ldexp_f32 v178, 1.0, v179
	v_add_f32_e32 v168, v168, v180
	v_mul_f32_e32 v176, v176, v178
	v_mul_f32_e32 v0, v0, v178
	v_mul_f32_e32 v1, v1, v178
	v_mul_f32_e32 v2, v2, v178
	v_mul_f32_e32 v3, v3, v178
	v_mul_f32_e32 v4, v4, v178
	v_mul_f32_e32 v5, v5, v178
	v_mul_f32_e32 v6, v6, v178
	v_mul_f32_e32 v7, v7, v178
	v_mul_f32_e32 v8, v8, v178
	v_mul_f32_e32 v9, v9, v178
	v_mul_f32_e32 v10, v10, v178
	v_mul_f32_e32 v11, v11, v178
	v_mul_f32_e32 v12, v12, v178
	v_mul_f32_e32 v13, v13, v178
	v_mul_f32_e32 v14, v14, v178
	v_mul_f32_e32 v15, v15, v178
	v_mul_f32_e32 v16, v16, v178
	v_mul_f32_e32 v17, v17, v178
	v_mul_f32_e32 v18, v18, v178
	v_mul_f32_e32 v19, v19, v178
	v_mul_f32_e32 v20, v20, v178
	v_mul_f32_e32 v21, v21, v178
	v_mul_f32_e32 v22, v22, v178
	v_mul_f32_e32 v23, v23, v178
	v_mul_f32_e32 v24, v24, v178
	v_mul_f32_e32 v25, v25, v178
	v_mul_f32_e32 v26, v26, v178
	v_mul_f32_e32 v27, v27, v178
	v_mul_f32_e32 v28, v28, v178
	v_mul_f32_e32 v29, v29, v178
	v_mul_f32_e32 v30, v30, v178
	v_mul_f32_e32 v31, v31, v178
	v_mul_f32_e32 v218, 0xc0b17218, v168
	v_mov_b32_e32 v219, v218
	v_mov_b32_e32 v220, v218
	v_mov_b32_e32 v221, v218
	v_mov_b32_e32 v222, v218
	v_mov_b32_e32 v223, v218
	v_mov_b32_e32 v224, v218
	v_mov_b32_e32 v225, v218
	v_mov_b32_e32 v226, v218
	v_mov_b32_e32 v227, v218
	v_mov_b32_e32 v228, v218
	v_mov_b32_e32 v229, v218
	v_mov_b32_e32 v230, v218
	v_mov_b32_e32 v231, v218
	v_mov_b32_e32 v232, v218
	v_mov_b32_e32 v233, v218

.Lm2_fullA:
	v_add_u32_e32 v236, v174, v162
	ds_read_b128 v[128:131], v236
	ds_read_b128 v[144:147], v236 offset:6656
	ds_read_b128 v[132:135], v236 offset:32
	ds_read_b128 v[148:151], v236 offset:6688
	ds_read_b128 v[136:139], v236 offset:64
	ds_read_b128 v[152:155], v236 offset:6720
	ds_read_b128 v[140:143], v236 offset:96
	ds_read_b128 v[156:159], v236 offset:6752
	v_add_u32_e32 v237, v176, v175
	s_waitcnt lgkmcnt(7)
	v_mfma_f32_32x32x16_bf16 v[32:47], v[128:131], v[96:99], v[218:233]
	s_waitcnt lgkmcnt(6)
	v_mfma_f32_32x32x16_bf16 v[48:63], v[144:147], v[96:99], v[218:233]
	s_waitcnt lgkmcnt(5)
	v_mfma_f32_32x32x16_bf16 v[32:47], v[132:135], v[100:103], v[32:47]
	s_waitcnt lgkmcnt(4)
	v_mfma_f32_32x32x16_bf16 v[48:63], v[148:151], v[100:103], v[48:63]
	s_waitcnt lgkmcnt(3)
	v_mfma_f32_32x32x16_bf16 v[32:47], v[136:139], v[104:107], v[32:47]
	s_waitcnt lgkmcnt(2)
	v_mfma_f32_32x32x16_bf16 v[48:63], v[152:155], v[104:107], v[48:63]
	s_waitcnt lgkmcnt(1)
	v_mfma_f32_32x32x16_bf16 v[32:47], v[140:143], v[108:111], v[32:47]
	s_waitcnt lgkmcnt(0)
	v_mfma_f32_32x32x16_bf16 v[48:63], v[156:159], v[108:111], v[48:63]
	ds_read_b64_tr_b16 v[186:187], v237 offset:26624
	ds_read_b64_tr_b16 v[188:189], v237 offset:28160
	ds_read_b64_tr_b16 v[190:191], v237 offset:26688
	ds_read_b64_tr_b16 v[192:193], v237 offset:28224
	ds_read_b64_tr_b16 v[194:195], v237 offset:29696
	ds_read_b64_tr_b16 v[196:197], v237 offset:31232
	ds_read_b64_tr_b16 v[198:199], v237 offset:29760
	ds_read_b64_tr_b16 v[200:201], v237 offset:31296
	ds_read_b64_tr_b16 v[202:203], v237 offset:32768
	ds_read_b64_tr_b16 v[204:205], v237 offset:34304
	ds_read_b64_tr_b16 v[206:207], v237 offset:32832
	ds_read_b64_tr_b16 v[208:209], v237 offset:34368
	ds_read_b64_tr_b16 v[210:211], v237 offset:35840
	ds_read_b64_tr_b16 v[212:213], v237 offset:37376
	ds_read_b64_tr_b16 v[214:215], v237 offset:35904
	ds_read_b64_tr_b16 v[216:217], v237 offset:37440
	v_mul_f32_e32 v32, 0x3e38aa3b, v32
	v_mul_f32_e32 v33, 0x3e38aa3b, v33
	v_mul_f32_e32 v34, 0x3e38aa3b, v34
	v_mul_f32_e32 v35, 0x3e38aa3b, v35
	v_mul_f32_e32 v36, 0x3e38aa3b, v36
	v_mul_f32_e32 v37, 0x3e38aa3b, v37
	v_mul_f32_e32 v38, 0x3e38aa3b, v38
	v_mul_f32_e32 v39, 0x3e38aa3b, v39
	v_exp_f32_e32 v32, v32
	v_exp_f32_e32 v33, v33
	v_exp_f32_e32 v34, v34
	v_exp_f32_e32 v35, v35
	v_exp_f32_e32 v36, v36
	v_exp_f32_e32 v37, v37
	v_exp_f32_e32 v38, v38
	v_exp_f32_e32 v39, v39
	v_pk_add_f32 v[234:235], v[32:33], v[34:35]
	v_pk_add_f32 v[234:235], v[234:235], v[36:37]
	v_pk_add_f32 v[234:235], v[234:235], v[38:39]
	v_cvt_pk_bf16_f32 v32, v32, v33
	v_cvt_pk_bf16_f32 v33, v34, v35
	v_cvt_pk_bf16_f32 v34, v36, v37
	v_cvt_pk_bf16_f32 v35, v38, v39
	v_mul_f32_e32 v40, 0x3e38aa3b, v40
	v_mul_f32_e32 v41, 0x3e38aa3b, v41
	s_waitcnt lgkmcnt(14)
	v_mfma_f32_32x32x16_bf16 v[16:31], v[186:189], v[32:35], v[16:31]
	v_mul_f32_e32 v42, 0x3e38aa3b, v42
	v_mul_f32_e32 v43, 0x3e38aa3b, v43
	v_mul_f32_e32 v44, 0x3e38aa3b, v44
	v_mul_f32_e32 v45, 0x3e38aa3b, v45
	v_mul_f32_e32 v46, 0x3e38aa3b, v46
	v_mul_f32_e32 v47, 0x3e38aa3b, v47
	s_waitcnt lgkmcnt(12)
	v_mfma_f32_32x32x16_bf16 v[0:15], v[190:193], v[32:35], v[0:15]
	v_exp_f32_e32 v40, v40
	v_exp_f32_e32 v41, v41
	v_exp_f32_e32 v42, v42
	v_exp_f32_e32 v43, v43
	v_exp_f32_e32 v44, v44
	v_exp_f32_e32 v45, v45
	v_exp_f32_e32 v46, v46
	v_exp_f32_e32 v47, v47
	v_pk_add_f32 v[234:235], v[234:235], v[40:41]
	v_pk_add_f32 v[234:235], v[234:235], v[42:43]
	v_pk_add_f32 v[234:235], v[234:235], v[44:45]
	v_pk_add_f32 v[234:235], v[234:235], v[46:47]
	v_cvt_pk_bf16_f32 v40, v40, v41
	v_cvt_pk_bf16_f32 v41, v42, v43
	v_cvt_pk_bf16_f32 v42, v44, v45
	v_cvt_pk_bf16_f32 v43, v46, v47
	v_mul_f32_e32 v48, 0x3e38aa3b, v48
	v_mul_f32_e32 v49, 0x3e38aa3b, v49
	s_waitcnt lgkmcnt(10)
	v_mfma_f32_32x32x16_bf16 v[16:31], v[194:197], v[40:43], v[16:31]
	v_mul_f32_e32 v50, 0x3e38aa3b, v50
	v_mul_f32_e32 v51, 0x3e38aa3b, v51
	v_mul_f32_e32 v52, 0x3e38aa3b, v52
	v_mul_f32_e32 v53, 0x3e38aa3b, v53
	v_mul_f32_e32 v54, 0x3e38aa3b, v54
	v_mul_f32_e32 v55, 0x3e38aa3b, v55
	s_waitcnt lgkmcnt(8)
	v_mfma_f32_32x32x16_bf16 v[0:15], v[198:201], v[40:43], v[0:15]
	v_exp_f32_e32 v48, v48
	v_exp_f32_e32 v49, v49
	v_exp_f32_e32 v50, v50
	v_exp_f32_e32 v51, v51
	v_exp_f32_e32 v52, v52
	v_exp_f32_e32 v53, v53
	v_exp_f32_e32 v54, v54
	v_exp_f32_e32 v55, v55
	v_pk_add_f32 v[234:235], v[234:235], v[48:49]
	v_pk_add_f32 v[234:235], v[234:235], v[50:51]
	v_pk_add_f32 v[234:235], v[234:235], v[52:53]
	v_pk_add_f32 v[234:235], v[234:235], v[54:55]
	v_cvt_pk_bf16_f32 v48, v48, v49
	v_cvt_pk_bf16_f32 v49, v50, v51
	v_cvt_pk_bf16_f32 v50, v52, v53
	v_cvt_pk_bf16_f32 v51, v54, v55
	v_mul_f32_e32 v56, 0x3e38aa3b, v56
	v_mul_f32_e32 v57, 0x3e38aa3b, v57
	s_waitcnt lgkmcnt(6)
	v_mfma_f32_32x32x16_bf16 v[16:31], v[202:205], v[48:51], v[16:31]
	v_mul_f32_e32 v58, 0x3e38aa3b, v58
	v_mul_f32_e32 v59, 0x3e38aa3b, v59
	v_mul_f32_e32 v60, 0x3e38aa3b, v60
	v_mul_f32_e32 v61, 0x3e38aa3b, v61
	v_mul_f32_e32 v62, 0x3e38aa3b, v62
	v_mul_f32_e32 v63, 0x3e38aa3b, v63
	s_waitcnt lgkmcnt(4)
	v_mfma_f32_32x32x16_bf16 v[0:15], v[206:209], v[48:51], v[0:15]
	v_exp_f32_e32 v56, v56
	v_exp_f32_e32 v57, v57
	v_exp_f32_e32 v58, v58
	v_exp_f32_e32 v59, v59
	v_exp_f32_e32 v60, v60
	v_exp_f32_e32 v61, v61
	v_exp_f32_e32 v62, v62
	v_exp_f32_e32 v63, v63
	v_pk_add_f32 v[234:235], v[234:235], v[56:57]
	v_pk_add_f32 v[234:235], v[234:235], v[58:59]
	v_pk_add_f32 v[234:235], v[234:235], v[60:61]
	v_pk_add_f32 v[234:235], v[234:235], v[62:63]
	v_cvt_pk_bf16_f32 v56, v56, v57
	v_cvt_pk_bf16_f32 v57, v58, v59
	v_cvt_pk_bf16_f32 v58, v60, v61
	v_cvt_pk_bf16_f32 v59, v62, v63
	s_nop 1
	s_waitcnt lgkmcnt(2)
	v_mfma_f32_32x32x16_bf16 v[16:31], v[210:213], v[56:59], v[16:31]
	s_waitcnt lgkmcnt(0)
	v_mfma_f32_32x32x16_bf16 v[0:15], v[214:217], v[56:59], v[0:15]
	v_add_f32_e32 v234, v234, v235
	v_add_f32_e32 v163, v163, v234
	v_cmp_lt_f32_e32 vcc, 0x43000000, v234
	s_cbranch_vccz .Lm2_nr_fA
	s_nop 15
	v_mov_b32_e32 v235, v234
	s_nop 1
	v_permlane32_swap_b32_e32 v234, v235
	v_add_f32_e32 v178, v234, v235
	v_cmp_lt_f32_e32 vcc, 0x43800000, v178
	v_frexp_exp_i32_f32_e32 v179, v178
	s_nop 1
	v_cndmask_b32_e32 v179, 0, v179, vcc
	v_cvt_f32_i32_e32 v180, v179
	v_sub_u32_e32 v179, 0, v179
	v_ldexp_f32 v178, 1.0, v179
	v_add_f32_e32 v168, v168, v180
	v_mul_f32_e32 v163, v163, v178
	v_mul_f32_e32 v0, v0, v178
	v_mul_f32_e32 v1, v1, v178
	v_mul_f32_e32 v2, v2, v178
	v_mul_f32_e32 v3, v3, v178
	v_mul_f32_e32 v4, v4, v178
	v_mul_f32_e32 v5, v5, v178
	v_mul_f32_e32 v6, v6, v178
	v_mul_f32_e32 v7, v7, v178
	v_mul_f32_e32 v8, v8, v178
	v_mul_f32_e32 v9, v9, v178
	v_mul_f32_e32 v10, v10, v178
	v_mul_f32_e32 v11, v11, v178
	v_mul_f32_e32 v12, v12, v178
	v_mul_f32_e32 v13, v13, v178
	v_mul_f32_e32 v14, v14, v178
	v_mul_f32_e32 v15, v15, v178
	v_mul_f32_e32 v16, v16, v178
	v_mul_f32_e32 v17, v17, v178
	v_mul_f32_e32 v18, v18, v178
	v_mul_f32_e32 v19, v19, v178
	v_mul_f32_e32 v20, v20, v178
	v_mul_f32_e32 v21, v21, v178
	v_mul_f32_e32 v22, v22, v178
	v_mul_f32_e32 v23, v23, v178
	v_mul_f32_e32 v24, v24, v178
	v_mul_f32_e32 v25, v25, v178
	v_mul_f32_e32 v26, v26, v178
	v_mul_f32_e32 v27, v27, v178
	v_mul_f32_e32 v28, v28, v178
	v_mul_f32_e32 v29, v29, v178
	v_mul_f32_e32 v30, v30, v178
	v_mul_f32_e32 v31, v31, v178
	v_mul_f32_e32 v218, 0xc0b17218, v168
	v_mov_b32_e32 v219, v218
	v_mov_b32_e32 v220, v218
	v_mov_b32_e32 v221, v218
	v_mov_b32_e32 v222, v218
	v_mov_b32_e32 v223, v218
	v_mov_b32_e32 v224, v218
	v_mov_b32_e32 v225, v218
	v_mov_b32_e32 v226, v218
	v_mov_b32_e32 v227, v218
	v_mov_b32_e32 v228, v218
	v_mov_b32_e32 v229, v218
	v_mov_b32_e32 v230, v218
	v_mov_b32_e32 v231, v218
	v_mov_b32_e32 v232, v218
	v_mov_b32_e32 v233, v218

.Lm2_lowA:
	v_add_u32_e32 v236, v174, v162
	ds_read_b128 v[128:131], v236
	ds_read_b128 v[144:147], v236 offset:6656
	ds_read_b128 v[132:135], v236 offset:32
	ds_read_b128 v[148:151], v236 offset:6688
	ds_read_b128 v[136:139], v236 offset:64
	ds_read_b128 v[152:155], v236 offset:6720
	ds_read_b128 v[140:143], v236 offset:96
	ds_read_b128 v[156:159], v236 offset:6752
	v_add_u32_e32 v237, v176, v175
	s_add_i32 s27, s27, 0x80
	v_add_u32_e32 v178, s27, v177
	v_sub_u32_e32 v178, 0, v178
	s_waitcnt lgkmcnt(7)
	v_mfma_f32_32x32x16_bf16 v[32:47], v[128:131], v[96:99], v[218:233]
	s_waitcnt lgkmcnt(6)
	v_mfma_f32_32x32x16_bf16 v[48:63], v[144:147], v[96:99], v[218:233]
	s_waitcnt lgkmcnt(5)
	v_mfma_f32_32x32x16_bf16 v[32:47], v[132:135], v[100:103], v[32:47]
	s_waitcnt lgkmcnt(4)
	v_mfma_f32_32x32x16_bf16 v[48:63], v[148:151], v[100:103], v[48:63]
	s_waitcnt lgkmcnt(3)
	v_mfma_f32_32x32x16_bf16 v[32:47], v[136:139], v[104:107], v[32:47]
	s_waitcnt lgkmcnt(2)
	v_mfma_f32_32x32x16_bf16 v[48:63], v[152:155], v[104:107], v[48:63]
	s_waitcnt lgkmcnt(1)
	v_mfma_f32_32x32x16_bf16 v[32:47], v[140:143], v[108:111], v[32:47]
	s_waitcnt lgkmcnt(0)
	v_mfma_f32_32x32x16_bf16 v[48:63], v[156:159], v[108:111], v[48:63]
	ds_read_b64_tr_b16 v[186:187], v237 offset:26624
	ds_read_b64_tr_b16 v[188:189], v237 offset:28160
	ds_read_b64_tr_b16 v[190:191], v237 offset:26688
	ds_read_b64_tr_b16 v[192:193], v237 offset:28224
	ds_read_b64_tr_b16 v[194:195], v237 offset:29696
	ds_read_b64_tr_b16 v[196:197], v237 offset:31232
	ds_read_b64_tr_b16 v[198:199], v237 offset:29760
	ds_read_b64_tr_b16 v[200:201], v237 offset:31296
	ds_read_b64_tr_b16 v[202:203], v237 offset:32768
	ds_read_b64_tr_b16 v[204:205], v237 offset:34304
	ds_read_b64_tr_b16 v[206:207], v237 offset:32832
	ds_read_b64_tr_b16 v[208:209], v237 offset:34368
	ds_read_b64_tr_b16 v[210:211], v237 offset:35840
	ds_read_b64_tr_b16 v[212:213], v237 offset:37376
	ds_read_b64_tr_b16 v[214:215], v237 offset:35904
	ds_read_b64_tr_b16 v[216:217], v237 offset:37440
	v_cmp_ge_i32_e64 s[2:3], 0, v178
	v_cmp_ge_i32_e64 s[4:5], 1, v178
	v_cmp_ge_i32_e64 s[24:25], 2, v178
	v_cmp_ge_i32_e64 s[26:27], 3, v178
	v_cndmask_b32_e64 v32, v238, v32, s[2:3]
	v_cndmask_b32_e64 v33, v238, v33, s[4:5]
	v_cndmask_b32_e64 v34, v238, v34, s[24:25]
	v_cndmask_b32_e64 v35, v238, v35, s[26:27]
	v_cmp_ge_i32_e64 s[2:3], 8, v178
	v_cmp_ge_i32_e64 s[4:5], 9, v178
	v_cmp_ge_i32_e64 s[24:25], 10, v178
	v_cmp_ge_i32_e64 s[26:27], 11, v178
	v_cndmask_b32_e64 v36, v238, v36, s[2:3]
	v_cndmask_b32_e64 v37, v238, v37, s[4:5]
	v_cndmask_b32_e64 v38, v238, v38, s[24:25]
	v_cndmask_b32_e64 v39, v238, v39, s[26:27]
	v_mul_f32_e32 v32, 0x3e38aa3b, v32
	v_mul_f32_e32 v33, 0x3e38aa3b, v33
	v_mul_f32_e32 v34, 0x3e38aa3b, v34
	v_mul_f32_e32 v35, 0x3e38aa3b, v35
	v_mul_f32_e32 v36, 0x3e38aa3b, v36
	v_mul_f32_e32 v37, 0x3e38aa3b, v37
	v_mul_f32_e32 v38, 0x3e38aa3b, v38
	v_mul_f32_e32 v39, 0x3e38aa3b, v39
	v_exp_f32_e32 v32, v32
	v_exp_f32_e32 v33, v33
	v_exp_f32_e32 v34, v34
	v_exp_f32_e32 v35, v35
	v_exp_f32_e32 v36, v36
	v_exp_f32_e32 v37, v37
	v_exp_f32_e32 v38, v38
	v_exp_f32_e32 v39, v39
	v_pk_add_f32 v[234:235], v[32:33], v[34:35]
	v_pk_add_f32 v[234:235], v[234:235], v[36:37]
	v_pk_add_f32 v[234:235], v[234:235], v[38:39]
	v_cvt_pk_bf16_f32 v32, v32, v33
	v_cvt_pk_bf16_f32 v33, v34, v35
	v_cvt_pk_bf16_f32 v34, v36, v37
	v_cvt_pk_bf16_f32 v35, v38, v39
	v_cmp_ge_i32_e64 s[2:3], 16, v178
	v_cmp_ge_i32_e64 s[4:5], 17, v178
	s_waitcnt lgkmcnt(14)
	v_mfma_f32_32x32x16_bf16 v[16:31], v[186:189], v[32:35], v[16:31]
	v_cmp_ge_i32_e64 s[24:25], 18, v178
	v_cmp_ge_i32_e64 s[26:27], 19, v178
	v_cndmask_b32_e64 v40, v238, v40, s[2:3]
	v_cndmask_b32_e64 v41, v238, v41, s[4:5]
	v_cndmask_b32_e64 v42, v238, v42, s[24:25]
	v_cndmask_b32_e64 v43, v238, v43, s[26:27]
	s_waitcnt lgkmcnt(12)
	v_mfma_f32_32x32x16_bf16 v[0:15], v[190:193], v[32:35], v[0:15]
	v_cmp_ge_i32_e64 s[2:3], 24, v178
	v_cmp_ge_i32_e64 s[4:5], 25, v178
	v_cmp_ge_i32_e64 s[24:25], 26, v178
	v_cmp_ge_i32_e64 s[26:27], 27, v178
	v_cndmask_b32_e64 v44, v238, v44, s[2:3]
	v_cndmask_b32_e64 v45, v238, v45, s[4:5]
	v_cndmask_b32_e64 v46, v238, v46, s[24:25]
	v_cndmask_b32_e64 v47, v238, v47, s[26:27]
	v_mul_f32_e32 v40, 0x3e38aa3b, v40
	v_mul_f32_e32 v41, 0x3e38aa3b, v41
	v_mul_f32_e32 v42, 0x3e38aa3b, v42
	v_mul_f32_e32 v43, 0x3e38aa3b, v43
	v_mul_f32_e32 v44, 0x3e38aa3b, v44
	v_mul_f32_e32 v45, 0x3e38aa3b, v45
	v_mul_f32_e32 v46, 0x3e38aa3b, v46
	v_mul_f32_e32 v47, 0x3e38aa3b, v47
	v_exp_f32_e32 v40, v40
	v_exp_f32_e32 v41, v41
	v_exp_f32_e32 v42, v42
	v_exp_f32_e32 v43, v43
	v_exp_f32_e32 v44, v44
	v_exp_f32_e32 v45, v45
	v_exp_f32_e32 v46, v46
	v_exp_f32_e32 v47, v47
	v_pk_add_f32 v[234:235], v[234:235], v[40:41]
	v_pk_add_f32 v[234:235], v[234:235], v[42:43]
	v_pk_add_f32 v[234:235], v[234:235], v[44:45]
	v_pk_add_f32 v[234:235], v[234:235], v[46:47]
	v_cvt_pk_bf16_f32 v40, v40, v41
	v_cvt_pk_bf16_f32 v41, v42, v43
	v_cvt_pk_bf16_f32 v42, v44, v45
	v_cvt_pk_bf16_f32 v43, v46, v47
	v_cmp_ge_i32_e64 s[2:3], 32, v178
	v_cmp_ge_i32_e64 s[4:5], 33, v178
	s_waitcnt lgkmcnt(10)
	v_mfma_f32_32x32x16_bf16 v[16:31], v[194:197], v[40:43], v[16:31]
	v_cmp_ge_i32_e64 s[24:25], 34, v178
	v_cmp_ge_i32_e64 s[26:27], 35, v178
	v_cndmask_b32_e64 v48, v238, v48, s[2:3]
	v_cndmask_b32_e64 v49, v238, v49, s[4:5]
	v_cndmask_b32_e64 v50, v238, v50, s[24:25]
	v_cndmask_b32_e64 v51, v238, v51, s[26:27]
	s_waitcnt lgkmcnt(8)
	v_mfma_f32_32x32x16_bf16 v[0:15], v[198:201], v[40:43], v[0:15]
	v_cmp_ge_i32_e64 s[2:3], 40, v178
	v_cmp_ge_i32_e64 s[4:5], 41, v178
	v_cmp_ge_i32_e64 s[24:25], 42, v178
	v_cmp_ge_i32_e64 s[26:27], 43, v178
	v_cndmask_b32_e64 v52, v238, v52, s[2:3]
	v_cndmask_b32_e64 v53, v238, v53, s[4:5]
	v_cndmask_b32_e64 v54, v238, v54, s[24:25]
	v_cndmask_b32_e64 v55, v238, v55, s[26:27]
	v_mul_f32_e32 v48, 0x3e38aa3b, v48
	v_mul_f32_e32 v49, 0x3e38aa3b, v49
	v_mul_f32_e32 v50, 0x3e38aa3b, v50
	v_mul_f32_e32 v51, 0x3e38aa3b, v51
	v_mul_f32_e32 v52, 0x3e38aa3b, v52
	v_mul_f32_e32 v53, 0x3e38aa3b, v53
	v_mul_f32_e32 v54, 0x3e38aa3b, v54
	v_mul_f32_e32 v55, 0x3e38aa3b, v55
	v_exp_f32_e32 v48, v48
	v_exp_f32_e32 v49, v49
	v_exp_f32_e32 v50, v50
	v_exp_f32_e32 v51, v51
	v_exp_f32_e32 v52, v52
	v_exp_f32_e32 v53, v53
	v_exp_f32_e32 v54, v54
	v_exp_f32_e32 v55, v55
	v_pk_add_f32 v[234:235], v[234:235], v[48:49]
	v_pk_add_f32 v[234:235], v[234:235], v[50:51]
	v_pk_add_f32 v[234:235], v[234:235], v[52:53]
	v_pk_add_f32 v[234:235], v[234:235], v[54:55]
	v_cvt_pk_bf16_f32 v48, v48, v49
	v_cvt_pk_bf16_f32 v49, v50, v51
	v_cvt_pk_bf16_f32 v50, v52, v53
	v_cvt_pk_bf16_f32 v51, v54, v55
	v_cmp_ge_i32_e64 s[2:3], 48, v178
	v_cmp_ge_i32_e64 s[4:5], 49, v178
	s_waitcnt lgkmcnt(6)
	v_mfma_f32_32x32x16_bf16 v[16:31], v[202:205], v[48:51], v[16:31]
	v_cmp_ge_i32_e64 s[24:25], 50, v178
	v_cmp_ge_i32_e64 s[26:27], 51, v178
	v_cndmask_b32_e64 v56, v238, v56, s[2:3]
	v_cndmask_b32_e64 v57, v238, v57, s[4:5]
	v_cndmask_b32_e64 v58, v238, v58, s[24:25]
	v_cndmask_b32_e64 v59, v238, v59, s[26:27]
	s_waitcnt lgkmcnt(4)
	v_mfma_f32_32x32x16_bf16 v[0:15], v[206:209], v[48:51], v[0:15]
	v_cmp_ge_i32_e64 s[2:3], 56, v178
	v_cmp_ge_i32_e64 s[4:5], 57, v178
	v_cmp_ge_i32_e64 s[24:25], 58, v178
	v_cmp_ge_i32_e64 s[26:27], 59, v178
	v_cndmask_b32_e64 v60, v238, v60, s[2:3]
	v_cndmask_b32_e64 v61, v238, v61, s[4:5]
	v_cndmask_b32_e64 v62, v238, v62, s[24:25]
	v_cndmask_b32_e64 v63, v238, v63, s[26:27]
	v_mul_f32_e32 v56, 0x3e38aa3b, v56
	v_mul_f32_e32 v57, 0x3e38aa3b, v57
	v_mul_f32_e32 v58, 0x3e38aa3b, v58
	v_mul_f32_e32 v59, 0x3e38aa3b, v59
	v_mul_f32_e32 v60, 0x3e38aa3b, v60
	v_mul_f32_e32 v61, 0x3e38aa3b, v61
	v_mul_f32_e32 v62, 0x3e38aa3b, v62
	v_mul_f32_e32 v63, 0x3e38aa3b, v63
	v_exp_f32_e32 v56, v56
	v_exp_f32_e32 v57, v57
	v_exp_f32_e32 v58, v58
	v_exp_f32_e32 v59, v59
	v_exp_f32_e32 v60, v60
	v_exp_f32_e32 v61, v61
	v_exp_f32_e32 v62, v62
	v_exp_f32_e32 v63, v63
	v_pk_add_f32 v[234:235], v[234:235], v[56:57]
	v_pk_add_f32 v[234:235], v[234:235], v[58:59]
	v_pk_add_f32 v[234:235], v[234:235], v[60:61]
	v_pk_add_f32 v[234:235], v[234:235], v[62:63]
	v_cvt_pk_bf16_f32 v56, v56, v57
	v_cvt_pk_bf16_f32 v57, v58, v59
	v_cvt_pk_bf16_f32 v58, v60, v61
	v_cvt_pk_bf16_f32 v59, v62, v63
	s_nop 1
	s_waitcnt lgkmcnt(2)
	v_mfma_f32_32x32x16_bf16 v[16:31], v[210:213], v[56:59], v[16:31]
	s_waitcnt lgkmcnt(0)
	v_mfma_f32_32x32x16_bf16 v[0:15], v[214:217], v[56:59], v[0:15]
	v_add_f32_e32 v234, v234, v235
	v_add_f32_e32 v163, v163, v234
	v_cmp_lt_f32_e32 vcc, 0x43000000, v234
	s_cbranch_vccz .Lm2_nr_lA
	s_nop 15
	v_mov_b32_e32 v235, v234
	s_nop 1
	v_permlane32_swap_b32_e32 v234, v235
	v_add_f32_e32 v178, v234, v235
	v_cmp_lt_f32_e32 vcc, 0x43800000, v178
	v_frexp_exp_i32_f32_e32 v179, v178
	s_nop 1
	v_cndmask_b32_e32 v179, 0, v179, vcc
	v_cvt_f32_i32_e32 v180, v179
	v_sub_u32_e32 v179, 0, v179
	v_ldexp_f32 v178, 1.0, v179
	v_add_f32_e32 v168, v168, v180
	v_mul_f32_e32 v163, v163, v178
	v_mul_f32_e32 v0, v0, v178
	v_mul_f32_e32 v1, v1, v178
	v_mul_f32_e32 v2, v2, v178
	v_mul_f32_e32 v3, v3, v178
	v_mul_f32_e32 v4, v4, v178
	v_mul_f32_e32 v5, v5, v178
	v_mul_f32_e32 v6, v6, v178
	v_mul_f32_e32 v7, v7, v178
	v_mul_f32_e32 v8, v8, v178
	v_mul_f32_e32 v9, v9, v178
	v_mul_f32_e32 v10, v10, v178
	v_mul_f32_e32 v11, v11, v178
	v_mul_f32_e32 v12, v12, v178
	v_mul_f32_e32 v13, v13, v178
	v_mul_f32_e32 v14, v14, v178
	v_mul_f32_e32 v15, v15, v178
	v_mul_f32_e32 v16, v16, v178
	v_mul_f32_e32 v17, v17, v178
	v_mul_f32_e32 v18, v18, v178
	v_mul_f32_e32 v19, v19, v178
	v_mul_f32_e32 v20, v20, v178
	v_mul_f32_e32 v21, v21, v178
	v_mul_f32_e32 v22, v22, v178
	v_mul_f32_e32 v23, v23, v178
	v_mul_f32_e32 v24, v24, v178
	v_mul_f32_e32 v25, v25, v178
	v_mul_f32_e32 v26, v26, v178
	v_mul_f32_e32 v27, v27, v178
	v_mul_f32_e32 v28, v28, v178
	v_mul_f32_e32 v29, v29, v178
	v_mul_f32_e32 v30, v30, v178
	v_mul_f32_e32 v31, v31, v178
	v_mul_f32_e32 v218, 0xc0b17218, v168
	v_mov_b32_e32 v219, v218
	v_mov_b32_e32 v220, v218
	v_mov_b32_e32 v221, v218
	v_mov_b32_e32 v222, v218
	v_mov_b32_e32 v223, v218
	v_mov_b32_e32 v224, v218
	v_mov_b32_e32 v225, v218
	v_mov_b32_e32 v226, v218
	v_mov_b32_e32 v227, v218
	v_mov_b32_e32 v228, v218
	v_mov_b32_e32 v229, v218
	v_mov_b32_e32 v230, v218
	v_mov_b32_e32 v231, v218
	v_mov_b32_e32 v232, v218
	v_mov_b32_e32 v233, v218

.Lm2_highA:
	v_add_u32_e32 v236, v174, v162
	ds_read_b128 v[128:131], v236
	ds_read_b128 v[144:147], v236 offset:6656
	ds_read_b128 v[132:135], v236 offset:32
	ds_read_b128 v[148:151], v236 offset:6688
	ds_read_b128 v[136:139], v236 offset:64
	ds_read_b128 v[152:155], v236 offset:6720
	ds_read_b128 v[140:143], v236 offset:96
	ds_read_b128 v[156:159], v236 offset:6752
	v_add_u32_e32 v237, v176, v175
	s_sub_i32 s27, 0x80, s27
	v_sub_u32_e32 v178, s27, v177
	s_waitcnt lgkmcnt(7)
	v_mfma_f32_32x32x16_bf16 v[32:47], v[128:131], v[96:99], v[218:233]
	s_waitcnt lgkmcnt(6)
	v_mfma_f32_32x32x16_bf16 v[48:63], v[144:147], v[96:99], v[218:233]
	s_waitcnt lgkmcnt(5)
	v_mfma_f32_32x32x16_bf16 v[32:47], v[132:135], v[100:103], v[32:47]
	s_waitcnt lgkmcnt(4)
	v_mfma_f32_32x32x16_bf16 v[48:63], v[148:151], v[100:103], v[48:63]
	s_waitcnt lgkmcnt(3)
	v_mfma_f32_32x32x16_bf16 v[32:47], v[136:139], v[104:107], v[32:47]
	s_waitcnt lgkmcnt(2)
	v_mfma_f32_32x32x16_bf16 v[48:63], v[152:155], v[104:107], v[48:63]
	s_waitcnt lgkmcnt(1)
	v_mfma_f32_32x32x16_bf16 v[32:47], v[140:143], v[108:111], v[32:47]
	s_waitcnt lgkmcnt(0)
	v_mfma_f32_32x32x16_bf16 v[48:63], v[156:159], v[108:111], v[48:63]
	ds_read_b64_tr_b16 v[186:187], v237 offset:26624
	ds_read_b64_tr_b16 v[188:189], v237 offset:28160
	ds_read_b64_tr_b16 v[190:191], v237 offset:26688
	ds_read_b64_tr_b16 v[192:193], v237 offset:28224
	ds_read_b64_tr_b16 v[194:195], v237 offset:29696
	ds_read_b64_tr_b16 v[196:197], v237 offset:31232
	ds_read_b64_tr_b16 v[198:199], v237 offset:29760
	ds_read_b64_tr_b16 v[200:201], v237 offset:31296
	ds_read_b64_tr_b16 v[202:203], v237 offset:32768
	ds_read_b64_tr_b16 v[204:205], v237 offset:34304
	ds_read_b64_tr_b16 v[206:207], v237 offset:32832
	ds_read_b64_tr_b16 v[208:209], v237 offset:34368
	ds_read_b64_tr_b16 v[210:211], v237 offset:35840
	ds_read_b64_tr_b16 v[212:213], v237 offset:37376
	ds_read_b64_tr_b16 v[214:215], v237 offset:35904
	ds_read_b64_tr_b16 v[216:217], v237 offset:37440
	v_cmp_le_i32_e64 s[2:3], 0, v178
	v_cmp_le_i32_e64 s[4:5], 1, v178
	v_cmp_le_i32_e64 s[24:25], 2, v178
	v_cmp_le_i32_e64 s[26:27], 3, v178
	v_cndmask_b32_e64 v32, v238, v32, s[2:3]
	v_cndmask_b32_e64 v33, v238, v33, s[4:5]
	v_cndmask_b32_e64 v34, v238, v34, s[24:25]
	v_cndmask_b32_e64 v35, v238, v35, s[26:27]
	v_cmp_le_i32_e64 s[2:3], 8, v178
	v_cmp_le_i32_e64 s[4:5], 9, v178
	v_cmp_le_i32_e64 s[24:25], 10, v178
	v_cmp_le_i32_e64 s[26:27], 11, v178
	v_cndmask_b32_e64 v36, v238, v36, s[2:3]
	v_cndmask_b32_e64 v37, v238, v37, s[4:5]
	v_cndmask_b32_e64 v38, v238, v38, s[24:25]
	v_cndmask_b32_e64 v39, v238, v39, s[26:27]
	v_mul_f32_e32 v32, 0x3e38aa3b, v32
	v_mul_f32_e32 v33, 0x3e38aa3b, v33
	v_mul_f32_e32 v34, 0x3e38aa3b, v34
	v_mul_f32_e32 v35, 0x3e38aa3b, v35
	v_mul_f32_e32 v36, 0x3e38aa3b, v36
	v_mul_f32_e32 v37, 0x3e38aa3b, v37
	v_mul_f32_e32 v38, 0x3e38aa3b, v38
	v_mul_f32_e32 v39, 0x3e38aa3b, v39
	v_exp_f32_e32 v32, v32
	v_exp_f32_e32 v33, v33
	v_exp_f32_e32 v34, v34
	v_exp_f32_e32 v35, v35
	v_exp_f32_e32 v36, v36
	v_exp_f32_e32 v37, v37
	v_exp_f32_e32 v38, v38
	v_exp_f32_e32 v39, v39
	v_pk_add_f32 v[234:235], v[32:33], v[34:35]
	v_pk_add_f32 v[234:235], v[234:235], v[36:37]
	v_pk_add_f32 v[234:235], v[234:235], v[38:39]
	v_cvt_pk_bf16_f32 v32, v32, v33
	v_cvt_pk_bf16_f32 v33, v34, v35
	v_cvt_pk_bf16_f32 v34, v36, v37
	v_cvt_pk_bf16_f32 v35, v38, v39
	v_cmp_le_i32_e64 s[2:3], 16, v178
	v_cmp_le_i32_e64 s[4:5], 17, v178
	s_waitcnt lgkmcnt(14)
	v_mfma_f32_32x32x16_bf16 v[16:31], v[186:189], v[32:35], v[16:31]
	v_cmp_le_i32_e64 s[24:25], 18, v178
	v_cmp_le_i32_e64 s[26:27], 19, v178
	v_cndmask_b32_e64 v40, v238, v40, s[2:3]
	v_cndmask_b32_e64 v41, v238, v41, s[4:5]
	v_cndmask_b32_e64 v42, v238, v42, s[24:25]
	v_cndmask_b32_e64 v43, v238, v43, s[26:27]
	s_waitcnt lgkmcnt(12)
	v_mfma_f32_32x32x16_bf16 v[0:15], v[190:193], v[32:35], v[0:15]
	v_cmp_le_i32_e64 s[2:3], 24, v178
	v_cmp_le_i32_e64 s[4:5], 25, v178
	v_cmp_le_i32_e64 s[24:25], 26, v178
	v_cmp_le_i32_e64 s[26:27], 27, v178
	v_cndmask_b32_e64 v44, v238, v44, s[2:3]
	v_cndmask_b32_e64 v45, v238, v45, s[4:5]
	v_cndmask_b32_e64 v46, v238, v46, s[24:25]
	v_cndmask_b32_e64 v47, v238, v47, s[26:27]
	v_mul_f32_e32 v40, 0x3e38aa3b, v40
	v_mul_f32_e32 v41, 0x3e38aa3b, v41
	v_mul_f32_e32 v42, 0x3e38aa3b, v42
	v_mul_f32_e32 v43, 0x3e38aa3b, v43
	v_mul_f32_e32 v44, 0x3e38aa3b, v44
	v_mul_f32_e32 v45, 0x3e38aa3b, v45
	v_mul_f32_e32 v46, 0x3e38aa3b, v46
	v_mul_f32_e32 v47, 0x3e38aa3b, v47
	v_exp_f32_e32 v40, v40
	v_exp_f32_e32 v41, v41
	v_exp_f32_e32 v42, v42
	v_exp_f32_e32 v43, v43
	v_exp_f32_e32 v44, v44
	v_exp_f32_e32 v45, v45
	v_exp_f32_e32 v46, v46
	v_exp_f32_e32 v47, v47
	v_pk_add_f32 v[234:235], v[234:235], v[40:41]
	v_pk_add_f32 v[234:235], v[234:235], v[42:43]
	v_pk_add_f32 v[234:235], v[234:235], v[44:45]
	v_pk_add_f32 v[234:235], v[234:235], v[46:47]
	v_cvt_pk_bf16_f32 v40, v40, v41
	v_cvt_pk_bf16_f32 v41, v42, v43
	v_cvt_pk_bf16_f32 v42, v44, v45
	v_cvt_pk_bf16_f32 v43, v46, v47
	v_cmp_le_i32_e64 s[2:3], 32, v178
	v_cmp_le_i32_e64 s[4:5], 33, v178
	s_waitcnt lgkmcnt(10)
	v_mfma_f32_32x32x16_bf16 v[16:31], v[194:197], v[40:43], v[16:31]
	v_cmp_le_i32_e64 s[24:25], 34, v178
	v_cmp_le_i32_e64 s[26:27], 35, v178
	v_cndmask_b32_e64 v48, v238, v48, s[2:3]
	v_cndmask_b32_e64 v49, v238, v49, s[4:5]
	v_cndmask_b32_e64 v50, v238, v50, s[24:25]
	v_cndmask_b32_e64 v51, v238, v51, s[26:27]
	s_waitcnt lgkmcnt(8)
	v_mfma_f32_32x32x16_bf16 v[0:15], v[198:201], v[40:43], v[0:15]
	v_cmp_le_i32_e64 s[2:3], 40, v178
	v_cmp_le_i32_e64 s[4:5], 41, v178
	v_cmp_le_i32_e64 s[24:25], 42, v178
	v_cmp_le_i32_e64 s[26:27], 43, v178
	v_cndmask_b32_e64 v52, v238, v52, s[2:3]
	v_cndmask_b32_e64 v53, v238, v53, s[4:5]
	v_cndmask_b32_e64 v54, v238, v54, s[24:25]
	v_cndmask_b32_e64 v55, v238, v55, s[26:27]
	v_mul_f32_e32 v48, 0x3e38aa3b, v48
	v_mul_f32_e32 v49, 0x3e38aa3b, v49
	v_mul_f32_e32 v50, 0x3e38aa3b, v50
	v_mul_f32_e32 v51, 0x3e38aa3b, v51
	v_mul_f32_e32 v52, 0x3e38aa3b, v52
	v_mul_f32_e32 v53, 0x3e38aa3b, v53
	v_mul_f32_e32 v54, 0x3e38aa3b, v54
	v_mul_f32_e32 v55, 0x3e38aa3b, v55
	v_exp_f32_e32 v48, v48
	v_exp_f32_e32 v49, v49
	v_exp_f32_e32 v50, v50
	v_exp_f32_e32 v51, v51
	v_exp_f32_e32 v52, v52
	v_exp_f32_e32 v53, v53
	v_exp_f32_e32 v54, v54
	v_exp_f32_e32 v55, v55
	v_pk_add_f32 v[234:235], v[234:235], v[48:49]
	v_pk_add_f32 v[234:235], v[234:235], v[50:51]
	v_pk_add_f32 v[234:235], v[234:235], v[52:53]
	v_pk_add_f32 v[234:235], v[234:235], v[54:55]
	v_cvt_pk_bf16_f32 v48, v48, v49
	v_cvt_pk_bf16_f32 v49, v50, v51
	v_cvt_pk_bf16_f32 v50, v52, v53
	v_cvt_pk_bf16_f32 v51, v54, v55
	v_cmp_le_i32_e64 s[2:3], 48, v178
	v_cmp_le_i32_e64 s[4:5], 49, v178
	s_waitcnt lgkmcnt(6)
	v_mfma_f32_32x32x16_bf16 v[16:31], v[202:205], v[48:51], v[16:31]
	v_cmp_le_i32_e64 s[24:25], 50, v178
	v_cmp_le_i32_e64 s[26:27], 51, v178
	v_cndmask_b32_e64 v56, v238, v56, s[2:3]
	v_cndmask_b32_e64 v57, v238, v57, s[4:5]
	v_cndmask_b32_e64 v58, v238, v58, s[24:25]
	v_cndmask_b32_e64 v59, v238, v59, s[26:27]
	s_waitcnt lgkmcnt(4)
	v_mfma_f32_32x32x16_bf16 v[0:15], v[206:209], v[48:51], v[0:15]
	v_cmp_le_i32_e64 s[2:3], 56, v178
	v_cmp_le_i32_e64 s[4:5], 57, v178
	v_cmp_le_i32_e64 s[24:25], 58, v178
	v_cmp_le_i32_e64 s[26:27], 59, v178
	v_cndmask_b32_e64 v60, v238, v60, s[2:3]
	v_cndmask_b32_e64 v61, v238, v61, s[4:5]
	v_cndmask_b32_e64 v62, v238, v62, s[24:25]
	v_cndmask_b32_e64 v63, v238, v63, s[26:27]
	v_mul_f32_e32 v56, 0x3e38aa3b, v56
	v_mul_f32_e32 v57, 0x3e38aa3b, v57
	v_mul_f32_e32 v58, 0x3e38aa3b, v58
	v_mul_f32_e32 v59, 0x3e38aa3b, v59
	v_mul_f32_e32 v60, 0x3e38aa3b, v60
	v_mul_f32_e32 v61, 0x3e38aa3b, v61
	v_mul_f32_e32 v62, 0x3e38aa3b, v62
	v_mul_f32_e32 v63, 0x3e38aa3b, v63
	v_exp_f32_e32 v56, v56
	v_exp_f32_e32 v57, v57
	v_exp_f32_e32 v58, v58
	v_exp_f32_e32 v59, v59
	v_exp_f32_e32 v60, v60
	v_exp_f32_e32 v61, v61
	v_exp_f32_e32 v62, v62
	v_exp_f32_e32 v63, v63
	v_pk_add_f32 v[234:235], v[234:235], v[56:57]
	v_pk_add_f32 v[234:235], v[234:235], v[58:59]
	v_pk_add_f32 v[234:235], v[234:235], v[60:61]
	v_pk_add_f32 v[234:235], v[234:235], v[62:63]
	v_cvt_pk_bf16_f32 v56, v56, v57
	v_cvt_pk_bf16_f32 v57, v58, v59
	v_cvt_pk_bf16_f32 v58, v60, v61
	v_cvt_pk_bf16_f32 v59, v62, v63
	s_nop 1
	s_waitcnt lgkmcnt(2)
	v_mfma_f32_32x32x16_bf16 v[16:31], v[210:213], v[56:59], v[16:31]
	s_waitcnt lgkmcnt(0)
	v_mfma_f32_32x32x16_bf16 v[0:15], v[214:217], v[56:59], v[0:15]
	v_add_f32_e32 v234, v234, v235
	v_add_f32_e32 v163, v163, v234
	v_cmp_lt_f32_e32 vcc, 0x43000000, v234
	s_cbranch_vccz .Lm2_nr_hA
	s_nop 15
	v_mov_b32_e32 v235, v234
	s_nop 1
	v_permlane32_swap_b32_e32 v234, v235
	v_add_f32_e32 v178, v234, v235
	v_cmp_lt_f32_e32 vcc, 0x43800000, v178
	v_frexp_exp_i32_f32_e32 v179, v178
	s_nop 1
	v_cndmask_b32_e32 v179, 0, v179, vcc
	v_cvt_f32_i32_e32 v180, v179
	v_sub_u32_e32 v179, 0, v179
	v_ldexp_f32 v178, 1.0, v179
	v_add_f32_e32 v168, v168, v180
	v_mul_f32_e32 v163, v163, v178
	v_mul_f32_e32 v0, v0, v178
	v_mul_f32_e32 v1, v1, v178
	v_mul_f32_e32 v2, v2, v178
	v_mul_f32_e32 v3, v3, v178
	v_mul_f32_e32 v4, v4, v178
	v_mul_f32_e32 v5, v5, v178
	v_mul_f32_e32 v6, v6, v178
	v_mul_f32_e32 v7, v7, v178
	v_mul_f32_e32 v8, v8, v178
	v_mul_f32_e32 v9, v9, v178
	v_mul_f32_e32 v10, v10, v178
	v_mul_f32_e32 v11, v11, v178
	v_mul_f32_e32 v12, v12, v178
	v_mul_f32_e32 v13, v13, v178
	v_mul_f32_e32 v14, v14, v178
	v_mul_f32_e32 v15, v15, v178
	v_mul_f32_e32 v16, v16, v178
	v_mul_f32_e32 v17, v17, v178
	v_mul_f32_e32 v18, v18, v178
	v_mul_f32_e32 v19, v19, v178
	v_mul_f32_e32 v20, v20, v178
	v_mul_f32_e32 v21, v21, v178
	v_mul_f32_e32 v22, v22, v178
	v_mul_f32_e32 v23, v23, v178
	v_mul_f32_e32 v24, v24, v178
	v_mul_f32_e32 v25, v25, v178
	v_mul_f32_e32 v26, v26, v178
	v_mul_f32_e32 v27, v27, v178
	v_mul_f32_e32 v28, v28, v178
	v_mul_f32_e32 v29, v29, v178
	v_mul_f32_e32 v30, v30, v178
	v_mul_f32_e32 v31, v31, v178
	v_mul_f32_e32 v218, 0xc0b17218, v168
	v_mov_b32_e32 v219, v218
	v_mov_b32_e32 v220, v218
	v_mov_b32_e32 v221, v218
	v_mov_b32_e32 v222, v218
	v_mov_b32_e32 v223, v218
	v_mov_b32_e32 v224, v218
	v_mov_b32_e32 v225, v218
	v_mov_b32_e32 v226, v218
	v_mov_b32_e32 v227, v218
	v_mov_b32_e32 v228, v218
	v_mov_b32_e32 v229, v218
	v_mov_b32_e32 v230, v218
	v_mov_b32_e32 v231, v218
	v_mov_b32_e32 v232, v218
	v_mov_b32_e32 v233, v218

.Lm2_fullB:
	v_add_u32_e32 v236, v174, v162
	ds_read_b128 v[128:131], v236 offset:13312
	ds_read_b128 v[144:147], v236 offset:19968
	ds_read_b128 v[132:135], v236 offset:13344
	ds_read_b128 v[148:151], v236 offset:20000
	ds_read_b128 v[136:139], v236 offset:13376
	ds_read_b128 v[152:155], v236 offset:20032
	ds_read_b128 v[140:143], v236 offset:13408
	ds_read_b128 v[156:159], v236 offset:20064
	v_add_u32_e32 v237, v176, v175
	s_waitcnt lgkmcnt(7)
	v_mfma_f32_32x32x16_bf16 v[32:47], v[128:131], v[96:99], v[218:233]
	s_waitcnt lgkmcnt(6)
	v_mfma_f32_32x32x16_bf16 v[48:63], v[144:147], v[96:99], v[218:233]
	s_waitcnt lgkmcnt(5)
	v_mfma_f32_32x32x16_bf16 v[32:47], v[132:135], v[100:103], v[32:47]
	s_waitcnt lgkmcnt(4)
	v_mfma_f32_32x32x16_bf16 v[48:63], v[148:151], v[100:103], v[48:63]
	s_waitcnt lgkmcnt(3)
	v_mfma_f32_32x32x16_bf16 v[32:47], v[136:139], v[104:107], v[32:47]
	s_waitcnt lgkmcnt(2)
	v_mfma_f32_32x32x16_bf16 v[48:63], v[152:155], v[104:107], v[48:63]
	s_waitcnt lgkmcnt(1)
	v_mfma_f32_32x32x16_bf16 v[32:47], v[140:143], v[108:111], v[32:47]
	s_waitcnt lgkmcnt(0)
	v_mfma_f32_32x32x16_bf16 v[48:63], v[156:159], v[108:111], v[48:63]
	ds_read_b64_tr_b16 v[186:187], v237 offset:38912
	ds_read_b64_tr_b16 v[188:189], v237 offset:40448
	ds_read_b64_tr_b16 v[190:191], v237 offset:38976
	ds_read_b64_tr_b16 v[192:193], v237 offset:40512
	ds_read_b64_tr_b16 v[194:195], v237 offset:41984
	ds_read_b64_tr_b16 v[196:197], v237 offset:43520
	ds_read_b64_tr_b16 v[198:199], v237 offset:42048
	ds_read_b64_tr_b16 v[200:201], v237 offset:43584
	ds_read_b64_tr_b16 v[202:203], v237 offset:45056
	ds_read_b64_tr_b16 v[204:205], v237 offset:46592
	ds_read_b64_tr_b16 v[206:207], v237 offset:45120
	ds_read_b64_tr_b16 v[208:209], v237 offset:46656
	ds_read_b64_tr_b16 v[210:211], v237 offset:48128
	ds_read_b64_tr_b16 v[212:213], v237 offset:49664
	ds_read_b64_tr_b16 v[214:215], v237 offset:48192
	ds_read_b64_tr_b16 v[216:217], v237 offset:49728
	v_mul_f32_e32 v32, 0x3e38aa3b, v32
	v_mul_f32_e32 v33, 0x3e38aa3b, v33
	v_mul_f32_e32 v34, 0x3e38aa3b, v34
	v_mul_f32_e32 v35, 0x3e38aa3b, v35
	v_mul_f32_e32 v36, 0x3e38aa3b, v36
	v_mul_f32_e32 v37, 0x3e38aa3b, v37
	v_mul_f32_e32 v38, 0x3e38aa3b, v38
	v_mul_f32_e32 v39, 0x3e38aa3b, v39
	v_exp_f32_e32 v32, v32
	v_exp_f32_e32 v33, v33
	v_exp_f32_e32 v34, v34
	v_exp_f32_e32 v35, v35
	v_exp_f32_e32 v36, v36
	v_exp_f32_e32 v37, v37
	v_exp_f32_e32 v38, v38
	v_exp_f32_e32 v39, v39
	v_pk_add_f32 v[234:235], v[32:33], v[34:35]
	v_pk_add_f32 v[234:235], v[234:235], v[36:37]
	v_pk_add_f32 v[234:235], v[234:235], v[38:39]
	v_cvt_pk_bf16_f32 v32, v32, v33
	v_cvt_pk_bf16_f32 v33, v34, v35
	v_cvt_pk_bf16_f32 v34, v36, v37
	v_cvt_pk_bf16_f32 v35, v38, v39
	v_mul_f32_e32 v40, 0x3e38aa3b, v40
	v_mul_f32_e32 v41, 0x3e38aa3b, v41
	s_waitcnt lgkmcnt(14)
	v_mfma_f32_32x32x16_bf16 v[16:31], v[186:189], v[32:35], v[16:31]
	v_mul_f32_e32 v42, 0x3e38aa3b, v42
	v_mul_f32_e32 v43, 0x3e38aa3b, v43
	v_mul_f32_e32 v44, 0x3e38aa3b, v44
	v_mul_f32_e32 v45, 0x3e38aa3b, v45
	v_mul_f32_e32 v46, 0x3e38aa3b, v46
	v_mul_f32_e32 v47, 0x3e38aa3b, v47
	s_waitcnt lgkmcnt(12)
	v_mfma_f32_32x32x16_bf16 v[0:15], v[190:193], v[32:35], v[0:15]
	v_exp_f32_e32 v40, v40
	v_exp_f32_e32 v41, v41
	v_exp_f32_e32 v42, v42
	v_exp_f32_e32 v43, v43
	v_exp_f32_e32 v44, v44
	v_exp_f32_e32 v45, v45
	v_exp_f32_e32 v46, v46
	v_exp_f32_e32 v47, v47
	v_pk_add_f32 v[234:235], v[234:235], v[40:41]
	v_pk_add_f32 v[234:235], v[234:235], v[42:43]
	v_pk_add_f32 v[234:235], v[234:235], v[44:45]
	v_pk_add_f32 v[234:235], v[234:235], v[46:47]
	v_cvt_pk_bf16_f32 v40, v40, v41
	v_cvt_pk_bf16_f32 v41, v42, v43
	v_cvt_pk_bf16_f32 v42, v44, v45
	v_cvt_pk_bf16_f32 v43, v46, v47
	v_mul_f32_e32 v48, 0x3e38aa3b, v48
	v_mul_f32_e32 v49, 0x3e38aa3b, v49
	s_waitcnt lgkmcnt(10)
	v_mfma_f32_32x32x16_bf16 v[16:31], v[194:197], v[40:43], v[16:31]
	v_mul_f32_e32 v50, 0x3e38aa3b, v50
	v_mul_f32_e32 v51, 0x3e38aa3b, v51
	v_mul_f32_e32 v52, 0x3e38aa3b, v52
	v_mul_f32_e32 v53, 0x3e38aa3b, v53
	v_mul_f32_e32 v54, 0x3e38aa3b, v54
	v_mul_f32_e32 v55, 0x3e38aa3b, v55
	s_waitcnt lgkmcnt(8)
	v_mfma_f32_32x32x16_bf16 v[0:15], v[198:201], v[40:43], v[0:15]
	v_exp_f32_e32 v48, v48
	v_exp_f32_e32 v49, v49
	v_exp_f32_e32 v50, v50
	v_exp_f32_e32 v51, v51
	v_exp_f32_e32 v52, v52
	v_exp_f32_e32 v53, v53
	v_exp_f32_e32 v54, v54
	v_exp_f32_e32 v55, v55
	v_pk_add_f32 v[234:235], v[234:235], v[48:49]
	v_pk_add_f32 v[234:235], v[234:235], v[50:51]
	v_pk_add_f32 v[234:235], v[234:235], v[52:53]
	v_pk_add_f32 v[234:235], v[234:235], v[54:55]
	v_cvt_pk_bf16_f32 v48, v48, v49
	v_cvt_pk_bf16_f32 v49, v50, v51
	v_cvt_pk_bf16_f32 v50, v52, v53
	v_cvt_pk_bf16_f32 v51, v54, v55
	v_mul_f32_e32 v56, 0x3e38aa3b, v56
	v_mul_f32_e32 v57, 0x3e38aa3b, v57
	s_waitcnt lgkmcnt(6)
	v_mfma_f32_32x32x16_bf16 v[16:31], v[202:205], v[48:51], v[16:31]
	v_mul_f32_e32 v58, 0x3e38aa3b, v58
	v_mul_f32_e32 v59, 0x3e38aa3b, v59
	v_mul_f32_e32 v60, 0x3e38aa3b, v60
	v_mul_f32_e32 v61, 0x3e38aa3b, v61
	v_mul_f32_e32 v62, 0x3e38aa3b, v62
	v_mul_f32_e32 v63, 0x3e38aa3b, v63
	s_waitcnt lgkmcnt(4)
	v_mfma_f32_32x32x16_bf16 v[0:15], v[206:209], v[48:51], v[0:15]
	v_exp_f32_e32 v56, v56
	v_exp_f32_e32 v57, v57
	v_exp_f32_e32 v58, v58
	v_exp_f32_e32 v59, v59
	v_exp_f32_e32 v60, v60
	v_exp_f32_e32 v61, v61
	v_exp_f32_e32 v62, v62
	v_exp_f32_e32 v63, v63
	v_pk_add_f32 v[234:235], v[234:235], v[56:57]
	v_pk_add_f32 v[234:235], v[234:235], v[58:59]
	v_pk_add_f32 v[234:235], v[234:235], v[60:61]
	v_pk_add_f32 v[234:235], v[234:235], v[62:63]
	v_cvt_pk_bf16_f32 v56, v56, v57
	v_cvt_pk_bf16_f32 v57, v58, v59
	v_cvt_pk_bf16_f32 v58, v60, v61
	v_cvt_pk_bf16_f32 v59, v62, v63
	s_nop 1
	s_waitcnt lgkmcnt(2)
	v_mfma_f32_32x32x16_bf16 v[16:31], v[210:213], v[56:59], v[16:31]
	s_waitcnt lgkmcnt(0)
	v_mfma_f32_32x32x16_bf16 v[0:15], v[214:217], v[56:59], v[0:15]
	v_add_f32_e32 v234, v234, v235
	v_add_f32_e32 v163, v163, v234
	v_cmp_lt_f32_e32 vcc, 0x43000000, v234
	s_cbranch_vccz .Lm2_nr_fB
	s_nop 15
	v_mov_b32_e32 v235, v234
	s_nop 1
	v_permlane32_swap_b32_e32 v234, v235
	v_add_f32_e32 v178, v234, v235
	v_cmp_lt_f32_e32 vcc, 0x43800000, v178
	v_frexp_exp_i32_f32_e32 v179, v178
	s_nop 1
	v_cndmask_b32_e32 v179, 0, v179, vcc
	v_cvt_f32_i32_e32 v180, v179
	v_sub_u32_e32 v179, 0, v179
	v_ldexp_f32 v178, 1.0, v179
	v_add_f32_e32 v168, v168, v180
	v_mul_f32_e32 v163, v163, v178
	v_mul_f32_e32 v0, v0, v178
	v_mul_f32_e32 v1, v1, v178
	v_mul_f32_e32 v2, v2, v178
	v_mul_f32_e32 v3, v3, v178
	v_mul_f32_e32 v4, v4, v178
	v_mul_f32_e32 v5, v5, v178
	v_mul_f32_e32 v6, v6, v178
	v_mul_f32_e32 v7, v7, v178
	v_mul_f32_e32 v8, v8, v178
	v_mul_f32_e32 v9, v9, v178
	v_mul_f32_e32 v10, v10, v178
	v_mul_f32_e32 v11, v11, v178
	v_mul_f32_e32 v12, v12, v178
	v_mul_f32_e32 v13, v13, v178
	v_mul_f32_e32 v14, v14, v178
	v_mul_f32_e32 v15, v15, v178
	v_mul_f32_e32 v16, v16, v178
	v_mul_f32_e32 v17, v17, v178
	v_mul_f32_e32 v18, v18, v178
	v_mul_f32_e32 v19, v19, v178
	v_mul_f32_e32 v20, v20, v178
	v_mul_f32_e32 v21, v21, v178
	v_mul_f32_e32 v22, v22, v178
	v_mul_f32_e32 v23, v23, v178
	v_mul_f32_e32 v24, v24, v178
	v_mul_f32_e32 v25, v25, v178
	v_mul_f32_e32 v26, v26, v178
	v_mul_f32_e32 v27, v27, v178
	v_mul_f32_e32 v28, v28, v178
	v_mul_f32_e32 v29, v29, v178
	v_mul_f32_e32 v30, v30, v178
	v_mul_f32_e32 v31, v31, v178
	v_mul_f32_e32 v218, 0xc0b17218, v168
	v_mov_b32_e32 v219, v218
	v_mov_b32_e32 v220, v218
	v_mov_b32_e32 v221, v218
	v_mov_b32_e32 v222, v218
	v_mov_b32_e32 v223, v218
	v_mov_b32_e32 v224, v218
	v_mov_b32_e32 v225, v218
	v_mov_b32_e32 v226, v218
	v_mov_b32_e32 v227, v218
	v_mov_b32_e32 v228, v218
	v_mov_b32_e32 v229, v218
	v_mov_b32_e32 v230, v218
	v_mov_b32_e32 v231, v218
	v_mov_b32_e32 v232, v218
	v_mov_b32_e32 v233, v218

.Lm2_lowB:
	v_add_u32_e32 v236, v174, v162
	ds_read_b128 v[128:131], v236 offset:13312
	ds_read_b128 v[144:147], v236 offset:19968
	ds_read_b128 v[132:135], v236 offset:13344
	ds_read_b128 v[148:151], v236 offset:20000
	ds_read_b128 v[136:139], v236 offset:13376
	ds_read_b128 v[152:155], v236 offset:20032
	ds_read_b128 v[140:143], v236 offset:13408
	ds_read_b128 v[156:159], v236 offset:20064
	v_add_u32_e32 v237, v176, v175
	s_add_i32 s27, s27, 0x80
	v_add_u32_e32 v178, s27, v177
	v_sub_u32_e32 v178, 0, v178
	s_waitcnt lgkmcnt(7)
	v_mfma_f32_32x32x16_bf16 v[32:47], v[128:131], v[96:99], v[218:233]
	s_waitcnt lgkmcnt(6)
	v_mfma_f32_32x32x16_bf16 v[48:63], v[144:147], v[96:99], v[218:233]
	s_waitcnt lgkmcnt(5)
	v_mfma_f32_32x32x16_bf16 v[32:47], v[132:135], v[100:103], v[32:47]
	s_waitcnt lgkmcnt(4)
	v_mfma_f32_32x32x16_bf16 v[48:63], v[148:151], v[100:103], v[48:63]
	s_waitcnt lgkmcnt(3)
	v_mfma_f32_32x32x16_bf16 v[32:47], v[136:139], v[104:107], v[32:47]
	s_waitcnt lgkmcnt(2)
	v_mfma_f32_32x32x16_bf16 v[48:63], v[152:155], v[104:107], v[48:63]
	s_waitcnt lgkmcnt(1)
	v_mfma_f32_32x32x16_bf16 v[32:47], v[140:143], v[108:111], v[32:47]
	s_waitcnt lgkmcnt(0)
	v_mfma_f32_32x32x16_bf16 v[48:63], v[156:159], v[108:111], v[48:63]
	ds_read_b64_tr_b16 v[186:187], v237 offset:38912
	ds_read_b64_tr_b16 v[188:189], v237 offset:40448
	ds_read_b64_tr_b16 v[190:191], v237 offset:38976
	ds_read_b64_tr_b16 v[192:193], v237 offset:40512
	ds_read_b64_tr_b16 v[194:195], v237 offset:41984
	ds_read_b64_tr_b16 v[196:197], v237 offset:43520
	ds_read_b64_tr_b16 v[198:199], v237 offset:42048
	ds_read_b64_tr_b16 v[200:201], v237 offset:43584
	ds_read_b64_tr_b16 v[202:203], v237 offset:45056
	ds_read_b64_tr_b16 v[204:205], v237 offset:46592
	ds_read_b64_tr_b16 v[206:207], v237 offset:45120
	ds_read_b64_tr_b16 v[208:209], v237 offset:46656
	ds_read_b64_tr_b16 v[210:211], v237 offset:48128
	ds_read_b64_tr_b16 v[212:213], v237 offset:49664
	ds_read_b64_tr_b16 v[214:215], v237 offset:48192
	ds_read_b64_tr_b16 v[216:217], v237 offset:49728
	v_cmp_ge_i32_e64 s[2:3], 0, v178
	v_cmp_ge_i32_e64 s[4:5], 1, v178
	v_cmp_ge_i32_e64 s[24:25], 2, v178
	v_cmp_ge_i32_e64 s[26:27], 3, v178
	v_cndmask_b32_e64 v32, v238, v32, s[2:3]
	v_cndmask_b32_e64 v33, v238, v33, s[4:5]
	v_cndmask_b32_e64 v34, v238, v34, s[24:25]
	v_cndmask_b32_e64 v35, v238, v35, s[26:27]
	v_cmp_ge_i32_e64 s[2:3], 8, v178
	v_cmp_ge_i32_e64 s[4:5], 9, v178
	v_cmp_ge_i32_e64 s[24:25], 10, v178
	v_cmp_ge_i32_e64 s[26:27], 11, v178
	v_cndmask_b32_e64 v36, v238, v36, s[2:3]
	v_cndmask_b32_e64 v37, v238, v37, s[4:5]
	v_cndmask_b32_e64 v38, v238, v38, s[24:25]
	v_cndmask_b32_e64 v39, v238, v39, s[26:27]
	v_mul_f32_e32 v32, 0x3e38aa3b, v32
	v_mul_f32_e32 v33, 0x3e38aa3b, v33
	v_mul_f32_e32 v34, 0x3e38aa3b, v34
	v_mul_f32_e32 v35, 0x3e38aa3b, v35
	v_mul_f32_e32 v36, 0x3e38aa3b, v36
	v_mul_f32_e32 v37, 0x3e38aa3b, v37
	v_mul_f32_e32 v38, 0x3e38aa3b, v38
	v_mul_f32_e32 v39, 0x3e38aa3b, v39
	v_exp_f32_e32 v32, v32
	v_exp_f32_e32 v33, v33
	v_exp_f32_e32 v34, v34
	v_exp_f32_e32 v35, v35
	v_exp_f32_e32 v36, v36
	v_exp_f32_e32 v37, v37
	v_exp_f32_e32 v38, v38
	v_exp_f32_e32 v39, v39
	v_pk_add_f32 v[234:235], v[32:33], v[34:35]
	v_pk_add_f32 v[234:235], v[234:235], v[36:37]
	v_pk_add_f32 v[234:235], v[234:235], v[38:39]
	v_cvt_pk_bf16_f32 v32, v32, v33
	v_cvt_pk_bf16_f32 v33, v34, v35
	v_cvt_pk_bf16_f32 v34, v36, v37
	v_cvt_pk_bf16_f32 v35, v38, v39
	v_cmp_ge_i32_e64 s[2:3], 16, v178
	v_cmp_ge_i32_e64 s[4:5], 17, v178
	s_waitcnt lgkmcnt(14)
	v_mfma_f32_32x32x16_bf16 v[16:31], v[186:189], v[32:35], v[16:31]
	v_cmp_ge_i32_e64 s[24:25], 18, v178
	v_cmp_ge_i32_e64 s[26:27], 19, v178
	v_cndmask_b32_e64 v40, v238, v40, s[2:3]
	v_cndmask_b32_e64 v41, v238, v41, s[4:5]
	v_cndmask_b32_e64 v42, v238, v42, s[24:25]
	v_cndmask_b32_e64 v43, v238, v43, s[26:27]
	s_waitcnt lgkmcnt(12)
	v_mfma_f32_32x32x16_bf16 v[0:15], v[190:193], v[32:35], v[0:15]
	v_cmp_ge_i32_e64 s[2:3], 24, v178
	v_cmp_ge_i32_e64 s[4:5], 25, v178
	v_cmp_ge_i32_e64 s[24:25], 26, v178
	v_cmp_ge_i32_e64 s[26:27], 27, v178
	v_cndmask_b32_e64 v44, v238, v44, s[2:3]
	v_cndmask_b32_e64 v45, v238, v45, s[4:5]
	v_cndmask_b32_e64 v46, v238, v46, s[24:25]
	v_cndmask_b32_e64 v47, v238, v47, s[26:27]
	v_mul_f32_e32 v40, 0x3e38aa3b, v40
	v_mul_f32_e32 v41, 0x3e38aa3b, v41
	v_mul_f32_e32 v42, 0x3e38aa3b, v42
	v_mul_f32_e32 v43, 0x3e38aa3b, v43
	v_mul_f32_e32 v44, 0x3e38aa3b, v44
	v_mul_f32_e32 v45, 0x3e38aa3b, v45
	v_mul_f32_e32 v46, 0x3e38aa3b, v46
	v_mul_f32_e32 v47, 0x3e38aa3b, v47
	v_exp_f32_e32 v40, v40
	v_exp_f32_e32 v41, v41
	v_exp_f32_e32 v42, v42
	v_exp_f32_e32 v43, v43
	v_exp_f32_e32 v44, v44
	v_exp_f32_e32 v45, v45
	v_exp_f32_e32 v46, v46
	v_exp_f32_e32 v47, v47
	v_pk_add_f32 v[234:235], v[234:235], v[40:41]
	v_pk_add_f32 v[234:235], v[234:235], v[42:43]
	v_pk_add_f32 v[234:235], v[234:235], v[44:45]
	v_pk_add_f32 v[234:235], v[234:235], v[46:47]
	v_cvt_pk_bf16_f32 v40, v40, v41
	v_cvt_pk_bf16_f32 v41, v42, v43
	v_cvt_pk_bf16_f32 v42, v44, v45
	v_cvt_pk_bf16_f32 v43, v46, v47
	v_cmp_ge_i32_e64 s[2:3], 32, v178
	v_cmp_ge_i32_e64 s[4:5], 33, v178
	s_waitcnt lgkmcnt(10)
	v_mfma_f32_32x32x16_bf16 v[16:31], v[194:197], v[40:43], v[16:31]
	v_cmp_ge_i32_e64 s[24:25], 34, v178
	v_cmp_ge_i32_e64 s[26:27], 35, v178
	v_cndmask_b32_e64 v48, v238, v48, s[2:3]
	v_cndmask_b32_e64 v49, v238, v49, s[4:5]
	v_cndmask_b32_e64 v50, v238, v50, s[24:25]
	v_cndmask_b32_e64 v51, v238, v51, s[26:27]
	s_waitcnt lgkmcnt(8)
	v_mfma_f32_32x32x16_bf16 v[0:15], v[198:201], v[40:43], v[0:15]
	v_cmp_ge_i32_e64 s[2:3], 40, v178
	v_cmp_ge_i32_e64 s[4:5], 41, v178
	v_cmp_ge_i32_e64 s[24:25], 42, v178
	v_cmp_ge_i32_e64 s[26:27], 43, v178
	v_cndmask_b32_e64 v52, v238, v52, s[2:3]
	v_cndmask_b32_e64 v53, v238, v53, s[4:5]
	v_cndmask_b32_e64 v54, v238, v54, s[24:25]
	v_cndmask_b32_e64 v55, v238, v55, s[26:27]
	v_mul_f32_e32 v48, 0x3e38aa3b, v48
	v_mul_f32_e32 v49, 0x3e38aa3b, v49
	v_mul_f32_e32 v50, 0x3e38aa3b, v50
	v_mul_f32_e32 v51, 0x3e38aa3b, v51
	v_mul_f32_e32 v52, 0x3e38aa3b, v52
	v_mul_f32_e32 v53, 0x3e38aa3b, v53
	v_mul_f32_e32 v54, 0x3e38aa3b, v54
	v_mul_f32_e32 v55, 0x3e38aa3b, v55
	v_exp_f32_e32 v48, v48
	v_exp_f32_e32 v49, v49
	v_exp_f32_e32 v50, v50
	v_exp_f32_e32 v51, v51
	v_exp_f32_e32 v52, v52
	v_exp_f32_e32 v53, v53
	v_exp_f32_e32 v54, v54
	v_exp_f32_e32 v55, v55
	v_pk_add_f32 v[234:235], v[234:235], v[48:49]
	v_pk_add_f32 v[234:235], v[234:235], v[50:51]
	v_pk_add_f32 v[234:235], v[234:235], v[52:53]
	v_pk_add_f32 v[234:235], v[234:235], v[54:55]
	v_cvt_pk_bf16_f32 v48, v48, v49
	v_cvt_pk_bf16_f32 v49, v50, v51
	v_cvt_pk_bf16_f32 v50, v52, v53
	v_cvt_pk_bf16_f32 v51, v54, v55
	v_cmp_ge_i32_e64 s[2:3], 48, v178
	v_cmp_ge_i32_e64 s[4:5], 49, v178
	s_waitcnt lgkmcnt(6)
	v_mfma_f32_32x32x16_bf16 v[16:31], v[202:205], v[48:51], v[16:31]
	v_cmp_ge_i32_e64 s[24:25], 50, v178
	v_cmp_ge_i32_e64 s[26:27], 51, v178
	v_cndmask_b32_e64 v56, v238, v56, s[2:3]
	v_cndmask_b32_e64 v57, v238, v57, s[4:5]
	v_cndmask_b32_e64 v58, v238, v58, s[24:25]
	v_cndmask_b32_e64 v59, v238, v59, s[26:27]
	s_waitcnt lgkmcnt(4)
	v_mfma_f32_32x32x16_bf16 v[0:15], v[206:209], v[48:51], v[0:15]
	v_cmp_ge_i32_e64 s[2:3], 56, v178
	v_cmp_ge_i32_e64 s[4:5], 57, v178
	v_cmp_ge_i32_e64 s[24:25], 58, v178
	v_cmp_ge_i32_e64 s[26:27], 59, v178
	v_cndmask_b32_e64 v60, v238, v60, s[2:3]
	v_cndmask_b32_e64 v61, v238, v61, s[4:5]
	v_cndmask_b32_e64 v62, v238, v62, s[24:25]
	v_cndmask_b32_e64 v63, v238, v63, s[26:27]
	v_mul_f32_e32 v56, 0x3e38aa3b, v56
	v_mul_f32_e32 v57, 0x3e38aa3b, v57
	v_mul_f32_e32 v58, 0x3e38aa3b, v58
	v_mul_f32_e32 v59, 0x3e38aa3b, v59
	v_mul_f32_e32 v60, 0x3e38aa3b, v60
	v_mul_f32_e32 v61, 0x3e38aa3b, v61
	v_mul_f32_e32 v62, 0x3e38aa3b, v62
	v_mul_f32_e32 v63, 0x3e38aa3b, v63
	v_exp_f32_e32 v56, v56
	v_exp_f32_e32 v57, v57
	v_exp_f32_e32 v58, v58
	v_exp_f32_e32 v59, v59
	v_exp_f32_e32 v60, v60
	v_exp_f32_e32 v61, v61
	v_exp_f32_e32 v62, v62
	v_exp_f32_e32 v63, v63
	v_pk_add_f32 v[234:235], v[234:235], v[56:57]
	v_pk_add_f32 v[234:235], v[234:235], v[58:59]
	v_pk_add_f32 v[234:235], v[234:235], v[60:61]
	v_pk_add_f32 v[234:235], v[234:235], v[62:63]
	v_cvt_pk_bf16_f32 v56, v56, v57
	v_cvt_pk_bf16_f32 v57, v58, v59
	v_cvt_pk_bf16_f32 v58, v60, v61
	v_cvt_pk_bf16_f32 v59, v62, v63
	s_nop 1
	s_waitcnt lgkmcnt(2)
	v_mfma_f32_32x32x16_bf16 v[16:31], v[210:213], v[56:59], v[16:31]
	s_waitcnt lgkmcnt(0)
	v_mfma_f32_32x32x16_bf16 v[0:15], v[214:217], v[56:59], v[0:15]
	v_add_f32_e32 v234, v234, v235
	v_add_f32_e32 v163, v163, v234
	v_cmp_lt_f32_e32 vcc, 0x43000000, v234
	s_cbranch_vccz .Lm2_nr_lB
	s_nop 15
	v_mov_b32_e32 v235, v234
	s_nop 1
	v_permlane32_swap_b32_e32 v234, v235
	v_add_f32_e32 v178, v234, v235
	v_cmp_lt_f32_e32 vcc, 0x43800000, v178
	v_frexp_exp_i32_f32_e32 v179, v178
	s_nop 1
	v_cndmask_b32_e32 v179, 0, v179, vcc
	v_cvt_f32_i32_e32 v180, v179
	v_sub_u32_e32 v179, 0, v179
	v_ldexp_f32 v178, 1.0, v179
	v_add_f32_e32 v168, v168, v180
	v_mul_f32_e32 v163, v163, v178
	v_mul_f32_e32 v0, v0, v178
	v_mul_f32_e32 v1, v1, v178
	v_mul_f32_e32 v2, v2, v178
	v_mul_f32_e32 v3, v3, v178
	v_mul_f32_e32 v4, v4, v178
	v_mul_f32_e32 v5, v5, v178
	v_mul_f32_e32 v6, v6, v178
	v_mul_f32_e32 v7, v7, v178
	v_mul_f32_e32 v8, v8, v178
	v_mul_f32_e32 v9, v9, v178
	v_mul_f32_e32 v10, v10, v178
	v_mul_f32_e32 v11, v11, v178
	v_mul_f32_e32 v12, v12, v178
	v_mul_f32_e32 v13, v13, v178
	v_mul_f32_e32 v14, v14, v178
	v_mul_f32_e32 v15, v15, v178
	v_mul_f32_e32 v16, v16, v178
	v_mul_f32_e32 v17, v17, v178
	v_mul_f32_e32 v18, v18, v178
	v_mul_f32_e32 v19, v19, v178
	v_mul_f32_e32 v20, v20, v178
	v_mul_f32_e32 v21, v21, v178
	v_mul_f32_e32 v22, v22, v178
	v_mul_f32_e32 v23, v23, v178
	v_mul_f32_e32 v24, v24, v178
	v_mul_f32_e32 v25, v25, v178
	v_mul_f32_e32 v26, v26, v178
	v_mul_f32_e32 v27, v27, v178
	v_mul_f32_e32 v28, v28, v178
	v_mul_f32_e32 v29, v29, v178
	v_mul_f32_e32 v30, v30, v178
	v_mul_f32_e32 v31, v31, v178
	v_mul_f32_e32 v218, 0xc0b17218, v168
	v_mov_b32_e32 v219, v218
	v_mov_b32_e32 v220, v218
	v_mov_b32_e32 v221, v218
	v_mov_b32_e32 v222, v218
	v_mov_b32_e32 v223, v218
	v_mov_b32_e32 v224, v218
	v_mov_b32_e32 v225, v218
	v_mov_b32_e32 v226, v218
	v_mov_b32_e32 v227, v218
	v_mov_b32_e32 v228, v218
	v_mov_b32_e32 v229, v218
	v_mov_b32_e32 v230, v218
	v_mov_b32_e32 v231, v218
	v_mov_b32_e32 v232, v218
	v_mov_b32_e32 v233, v218

.Lm2_highB:
	v_add_u32_e32 v236, v174, v162
	ds_read_b128 v[128:131], v236 offset:13312
	ds_read_b128 v[144:147], v236 offset:19968
	ds_read_b128 v[132:135], v236 offset:13344
	ds_read_b128 v[148:151], v236 offset:20000
	ds_read_b128 v[136:139], v236 offset:13376
	ds_read_b128 v[152:155], v236 offset:20032
	ds_read_b128 v[140:143], v236 offset:13408
	ds_read_b128 v[156:159], v236 offset:20064
	v_add_u32_e32 v237, v176, v175
	s_sub_i32 s27, 0x80, s27
	v_sub_u32_e32 v178, s27, v177
	s_waitcnt lgkmcnt(7)
	v_mfma_f32_32x32x16_bf16 v[32:47], v[128:131], v[96:99], v[218:233]
	s_waitcnt lgkmcnt(6)
	v_mfma_f32_32x32x16_bf16 v[48:63], v[144:147], v[96:99], v[218:233]
	s_waitcnt lgkmcnt(5)
	v_mfma_f32_32x32x16_bf16 v[32:47], v[132:135], v[100:103], v[32:47]
	s_waitcnt lgkmcnt(4)
	v_mfma_f32_32x32x16_bf16 v[48:63], v[148:151], v[100:103], v[48:63]
	s_waitcnt lgkmcnt(3)
	v_mfma_f32_32x32x16_bf16 v[32:47], v[136:139], v[104:107], v[32:47]
	s_waitcnt lgkmcnt(2)
	v_mfma_f32_32x32x16_bf16 v[48:63], v[152:155], v[104:107], v[48:63]
	s_waitcnt lgkmcnt(1)
	v_mfma_f32_32x32x16_bf16 v[32:47], v[140:143], v[108:111], v[32:47]
	s_waitcnt lgkmcnt(0)
	v_mfma_f32_32x32x16_bf16 v[48:63], v[156:159], v[108:111], v[48:63]
	ds_read_b64_tr_b16 v[186:187], v237 offset:38912
	ds_read_b64_tr_b16 v[188:189], v237 offset:40448
	ds_read_b64_tr_b16 v[190:191], v237 offset:38976
	ds_read_b64_tr_b16 v[192:193], v237 offset:40512
	ds_read_b64_tr_b16 v[194:195], v237 offset:41984
	ds_read_b64_tr_b16 v[196:197], v237 offset:43520
	ds_read_b64_tr_b16 v[198:199], v237 offset:42048
	ds_read_b64_tr_b16 v[200:201], v237 offset:43584
	ds_read_b64_tr_b16 v[202:203], v237 offset:45056
	ds_read_b64_tr_b16 v[204:205], v237 offset:46592
	ds_read_b64_tr_b16 v[206:207], v237 offset:45120
	ds_read_b64_tr_b16 v[208:209], v237 offset:46656
	ds_read_b64_tr_b16 v[210:211], v237 offset:48128
	ds_read_b64_tr_b16 v[212:213], v237 offset:49664
	ds_read_b64_tr_b16 v[214:215], v237 offset:48192
	ds_read_b64_tr_b16 v[216:217], v237 offset:49728
	v_cmp_le_i32_e64 s[2:3], 0, v178
	v_cmp_le_i32_e64 s[4:5], 1, v178
	v_cmp_le_i32_e64 s[24:25], 2, v178
	v_cmp_le_i32_e64 s[26:27], 3, v178
	v_cndmask_b32_e64 v32, v238, v32, s[2:3]
	v_cndmask_b32_e64 v33, v238, v33, s[4:5]
	v_cndmask_b32_e64 v34, v238, v34, s[24:25]
	v_cndmask_b32_e64 v35, v238, v35, s[26:27]
	v_cmp_le_i32_e64 s[2:3], 8, v178
	v_cmp_le_i32_e64 s[4:5], 9, v178
	v_cmp_le_i32_e64 s[24:25], 10, v178
	v_cmp_le_i32_e64 s[26:27], 11, v178
	v_cndmask_b32_e64 v36, v238, v36, s[2:3]
	v_cndmask_b32_e64 v37, v238, v37, s[4:5]
	v_cndmask_b32_e64 v38, v238, v38, s[24:25]
	v_cndmask_b32_e64 v39, v238, v39, s[26:27]
	v_mul_f32_e32 v32, 0x3e38aa3b, v32
	v_mul_f32_e32 v33, 0x3e38aa3b, v33
	v_mul_f32_e32 v34, 0x3e38aa3b, v34
	v_mul_f32_e32 v35, 0x3e38aa3b, v35
	v_mul_f32_e32 v36, 0x3e38aa3b, v36
	v_mul_f32_e32 v37, 0x3e38aa3b, v37
	v_mul_f32_e32 v38, 0x3e38aa3b, v38
	v_mul_f32_e32 v39, 0x3e38aa3b, v39
	v_exp_f32_e32 v32, v32
	v_exp_f32_e32 v33, v33
	v_exp_f32_e32 v34, v34
	v_exp_f32_e32 v35, v35
	v_exp_f32_e32 v36, v36
	v_exp_f32_e32 v37, v37
	v_exp_f32_e32 v38, v38
	v_exp_f32_e32 v39, v39
	v_pk_add_f32 v[234:235], v[32:33], v[34:35]
	v_pk_add_f32 v[234:235], v[234:235], v[36:37]
	v_pk_add_f32 v[234:235], v[234:235], v[38:39]
	v_cvt_pk_bf16_f32 v32, v32, v33
	v_cvt_pk_bf16_f32 v33, v34, v35
	v_cvt_pk_bf16_f32 v34, v36, v37
	v_cvt_pk_bf16_f32 v35, v38, v39
	v_cmp_le_i32_e64 s[2:3], 16, v178
	v_cmp_le_i32_e64 s[4:5], 17, v178
	s_waitcnt lgkmcnt(14)
	v_mfma_f32_32x32x16_bf16 v[16:31], v[186:189], v[32:35], v[16:31]
	v_cmp_le_i32_e64 s[24:25], 18, v178
	v_cmp_le_i32_e64 s[26:27], 19, v178
	v_cndmask_b32_e64 v40, v238, v40, s[2:3]
	v_cndmask_b32_e64 v41, v238, v41, s[4:5]
	v_cndmask_b32_e64 v42, v238, v42, s[24:25]
	v_cndmask_b32_e64 v43, v238, v43, s[26:27]
	s_waitcnt lgkmcnt(12)
	v_mfma_f32_32x32x16_bf16 v[0:15], v[190:193], v[32:35], v[0:15]
	v_cmp_le_i32_e64 s[2:3], 24, v178
	v_cmp_le_i32_e64 s[4:5], 25, v178
	v_cmp_le_i32_e64 s[24:25], 26, v178
	v_cmp_le_i32_e64 s[26:27], 27, v178
	v_cndmask_b32_e64 v44, v238, v44, s[2:3]
	v_cndmask_b32_e64 v45, v238, v45, s[4:5]
	v_cndmask_b32_e64 v46, v238, v46, s[24:25]
	v_cndmask_b32_e64 v47, v238, v47, s[26:27]
	v_mul_f32_e32 v40, 0x3e38aa3b, v40
	v_mul_f32_e32 v41, 0x3e38aa3b, v41
	v_mul_f32_e32 v42, 0x3e38aa3b, v42
	v_mul_f32_e32 v43, 0x3e38aa3b, v43
	v_mul_f32_e32 v44, 0x3e38aa3b, v44
	v_mul_f32_e32 v45, 0x3e38aa3b, v45
	v_mul_f32_e32 v46, 0x3e38aa3b, v46
	v_mul_f32_e32 v47, 0x3e38aa3b, v47
	v_exp_f32_e32 v40, v40
	v_exp_f32_e32 v41, v41
	v_exp_f32_e32 v42, v42
	v_exp_f32_e32 v43, v43
	v_exp_f32_e32 v44, v44
	v_exp_f32_e32 v45, v45
	v_exp_f32_e32 v46, v46
	v_exp_f32_e32 v47, v47
	v_pk_add_f32 v[234:235], v[234:235], v[40:41]
	v_pk_add_f32 v[234:235], v[234:235], v[42:43]
	v_pk_add_f32 v[234:235], v[234:235], v[44:45]
	v_pk_add_f32 v[234:235], v[234:235], v[46:47]
	v_cvt_pk_bf16_f32 v40, v40, v41
	v_cvt_pk_bf16_f32 v41, v42, v43
	v_cvt_pk_bf16_f32 v42, v44, v45
	v_cvt_pk_bf16_f32 v43, v46, v47
	v_cmp_le_i32_e64 s[2:3], 32, v178
	v_cmp_le_i32_e64 s[4:5], 33, v178
	s_waitcnt lgkmcnt(10)
	v_mfma_f32_32x32x16_bf16 v[16:31], v[194:197], v[40:43], v[16:31]
	v_cmp_le_i32_e64 s[24:25], 34, v178
	v_cmp_le_i32_e64 s[26:27], 35, v178
	v_cndmask_b32_e64 v48, v238, v48, s[2:3]
	v_cndmask_b32_e64 v49, v238, v49, s[4:5]
	v_cndmask_b32_e64 v50, v238, v50, s[24:25]
	v_cndmask_b32_e64 v51, v238, v51, s[26:27]
	s_waitcnt lgkmcnt(8)
	v_mfma_f32_32x32x16_bf16 v[0:15], v[198:201], v[40:43], v[0:15]
	v_cmp_le_i32_e64 s[2:3], 40, v178
	v_cmp_le_i32_e64 s[4:5], 41, v178
	v_cmp_le_i32_e64 s[24:25], 42, v178
	v_cmp_le_i32_e64 s[26:27], 43, v178
	v_cndmask_b32_e64 v52, v238, v52, s[2:3]
	v_cndmask_b32_e64 v53, v238, v53, s[4:5]
	v_cndmask_b32_e64 v54, v238, v54, s[24:25]
	v_cndmask_b32_e64 v55, v238, v55, s[26:27]
	v_mul_f32_e32 v48, 0x3e38aa3b, v48
	v_mul_f32_e32 v49, 0x3e38aa3b, v49
	v_mul_f32_e32 v50, 0x3e38aa3b, v50
	v_mul_f32_e32 v51, 0x3e38aa3b, v51
	v_mul_f32_e32 v52, 0x3e38aa3b, v52
	v_mul_f32_e32 v53, 0x3e38aa3b, v53
	v_mul_f32_e32 v54, 0x3e38aa3b, v54
	v_mul_f32_e32 v55, 0x3e38aa3b, v55
	v_exp_f32_e32 v48, v48
	v_exp_f32_e32 v49, v49
	v_exp_f32_e32 v50, v50
	v_exp_f32_e32 v51, v51
	v_exp_f32_e32 v52, v52
	v_exp_f32_e32 v53, v53
	v_exp_f32_e32 v54, v54
	v_exp_f32_e32 v55, v55
	v_pk_add_f32 v[234:235], v[234:235], v[48:49]
	v_pk_add_f32 v[234:235], v[234:235], v[50:51]
	v_pk_add_f32 v[234:235], v[234:235], v[52:53]
	v_pk_add_f32 v[234:235], v[234:235], v[54:55]
	v_cvt_pk_bf16_f32 v48, v48, v49
	v_cvt_pk_bf16_f32 v49, v50, v51
	v_cvt_pk_bf16_f32 v50, v52, v53
	v_cvt_pk_bf16_f32 v51, v54, v55
	v_cmp_le_i32_e64 s[2:3], 48, v178
	v_cmp_le_i32_e64 s[4:5], 49, v178
	s_waitcnt lgkmcnt(6)
	v_mfma_f32_32x32x16_bf16 v[16:31], v[202:205], v[48:51], v[16:31]
	v_cmp_le_i32_e64 s[24:25], 50, v178
	v_cmp_le_i32_e64 s[26:27], 51, v178
	v_cndmask_b32_e64 v56, v238, v56, s[2:3]
	v_cndmask_b32_e64 v57, v238, v57, s[4:5]
	v_cndmask_b32_e64 v58, v238, v58, s[24:25]
	v_cndmask_b32_e64 v59, v238, v59, s[26:27]
	s_waitcnt lgkmcnt(4)
	v_mfma_f32_32x32x16_bf16 v[0:15], v[206:209], v[48:51], v[0:15]
	v_cmp_le_i32_e64 s[2:3], 56, v178
	v_cmp_le_i32_e64 s[4:5], 57, v178
	v_cmp_le_i32_e64 s[24:25], 58, v178
	v_cmp_le_i32_e64 s[26:27], 59, v178
	v_cndmask_b32_e64 v60, v238, v60, s[2:3]
	v_cndmask_b32_e64 v61, v238, v61, s[4:5]
	v_cndmask_b32_e64 v62, v238, v62, s[24:25]
	v_cndmask_b32_e64 v63, v238, v63, s[26:27]
	v_mul_f32_e32 v56, 0x3e38aa3b, v56
	v_mul_f32_e32 v57, 0x3e38aa3b, v57
	v_mul_f32_e32 v58, 0x3e38aa3b, v58
	v_mul_f32_e32 v59, 0x3e38aa3b, v59
	v_mul_f32_e32 v60, 0x3e38aa3b, v60
	v_mul_f32_e32 v61, 0x3e38aa3b, v61
	v_mul_f32_e32 v62, 0x3e38aa3b, v62
	v_mul_f32_e32 v63, 0x3e38aa3b, v63
	v_exp_f32_e32 v56, v56
	v_exp_f32_e32 v57, v57
	v_exp_f32_e32 v58, v58
	v_exp_f32_e32 v59, v59
	v_exp_f32_e32 v60, v60
	v_exp_f32_e32 v61, v61
	v_exp_f32_e32 v62, v62
	v_exp_f32_e32 v63, v63
	v_pk_add_f32 v[234:235], v[234:235], v[56:57]
	v_pk_add_f32 v[234:235], v[234:235], v[58:59]
	v_pk_add_f32 v[234:235], v[234:235], v[60:61]
	v_pk_add_f32 v[234:235], v[234:235], v[62:63]
	v_cvt_pk_bf16_f32 v56, v56, v57
	v_cvt_pk_bf16_f32 v57, v58, v59
	v_cvt_pk_bf16_f32 v58, v60, v61
	v_cvt_pk_bf16_f32 v59, v62, v63
	s_nop 1
	s_waitcnt lgkmcnt(2)
	v_mfma_f32_32x32x16_bf16 v[16:31], v[210:213], v[56:59], v[16:31]
	s_waitcnt lgkmcnt(0)
	v_mfma_f32_32x32x16_bf16 v[0:15], v[214:217], v[56:59], v[0:15]
	v_add_f32_e32 v234, v234, v235
	v_add_f32_e32 v163, v163, v234
	v_cmp_lt_f32_e32 vcc, 0x43000000, v234
	s_cbranch_vccz .Lm2_nr_hB
	s_nop 15
	v_mov_b32_e32 v235, v234
	s_nop 1
	v_permlane32_swap_b32_e32 v234, v235
	v_add_f32_e32 v178, v234, v235
	v_cmp_lt_f32_e32 vcc, 0x43800000, v178
	v_frexp_exp_i32_f32_e32 v179, v178
	s_nop 1
	v_cndmask_b32_e32 v179, 0, v179, vcc
	v_cvt_f32_i32_e32 v180, v179
	v_sub_u32_e32 v179, 0, v179
	v_ldexp_f32 v178, 1.0, v179
	v_add_f32_e32 v168, v168, v180
	v_mul_f32_e32 v163, v163, v178
	v_mul_f32_e32 v0, v0, v178
	v_mul_f32_e32 v1, v1, v178
	v_mul_f32_e32 v2, v2, v178
	v_mul_f32_e32 v3, v3, v178
	v_mul_f32_e32 v4, v4, v178
	v_mul_f32_e32 v5, v5, v178
	v_mul_f32_e32 v6, v6, v178
	v_mul_f32_e32 v7, v7, v178
	v_mul_f32_e32 v8, v8, v178
	v_mul_f32_e32 v9, v9, v178
	v_mul_f32_e32 v10, v10, v178
	v_mul_f32_e32 v11, v11, v178
	v_mul_f32_e32 v12, v12, v178
	v_mul_f32_e32 v13, v13, v178
	v_mul_f32_e32 v14, v14, v178
	v_mul_f32_e32 v15, v15, v178
	v_mul_f32_e32 v16, v16, v178
	v_mul_f32_e32 v17, v17, v178
	v_mul_f32_e32 v18, v18, v178
	v_mul_f32_e32 v19, v19, v178
	v_mul_f32_e32 v20, v20, v178
	v_mul_f32_e32 v21, v21, v178
	v_mul_f32_e32 v22, v22, v178
	v_mul_f32_e32 v23, v23, v178
	v_mul_f32_e32 v24, v24, v178
	v_mul_f32_e32 v25, v25, v178
	v_mul_f32_e32 v26, v26, v178
	v_mul_f32_e32 v27, v27, v178
	v_mul_f32_e32 v28, v28, v178
	v_mul_f32_e32 v29, v29, v178
	v_mul_f32_e32 v30, v30, v178
	v_mul_f32_e32 v31, v31, v178
	v_mul_f32_e32 v218, 0xc0b17218, v168
	v_mov_b32_e32 v219, v218
	v_mov_b32_e32 v220, v218
	v_mov_b32_e32 v221, v218
	v_mov_b32_e32 v222, v218
	v_mov_b32_e32 v223, v218
	v_mov_b32_e32 v224, v218
	v_mov_b32_e32 v225, v218
	v_mov_b32_e32 v226, v218
	v_mov_b32_e32 v227, v218
	v_mov_b32_e32 v228, v218
	v_mov_b32_e32 v229, v218
	v_mov_b32_e32 v230, v218
	v_mov_b32_e32 v231, v218
	v_mov_b32_e32 v232, v218
	v_mov_b32_e32 v233, v218
